# step4 + software-pipelined residual loads (renamed into free registers, counted vmcnt) in the first-residual and LN-residual GEMM epilogues + hoisted RMS-stat loads in the q-up epilogue
# speedup vs baseline: 1.0196x; 1.0087x over previous
.LBB0_678:
	v_lshl_add_u32 v146, s77, 8, v188
	v_lshl_or_b32 v156, s78, 8, v192
	v_ashrrev_i32_e32 v147, 31, v146
	v_ashrrev_i32_e32 v157, 31, v156
	v_lshlrev_b64 v[162:163], 11, v[146:147]
	v_lshl_add_u64 v[148:149], v[162:163], 0, v[156:157]
	v_lshl_add_u64 v[168:169], v[148:149], 2, s[48:49]
	global_load_dwordx4 v[234:237], v[168:169], off
	global_load_dwordx4 v[238:241], v[168:169], off offset:16
	v_or_b32_e32 v144, 16, v146
	v_ashrrev_i32_e32 v145, 31, v144
	v_lshl_add_u64 v[154:155], v[148:149], 1, s[16:17]
	v_lshlrev_b64 v[160:161], 11, v[144:145]
	v_lshl_add_u64 v[158:159], v[160:161], 0, v[156:157]
	v_lshl_add_u64 v[164:165], v[158:159], 2, s[48:49]
	v_lshl_add_u64 v[158:159], v[158:159], 1, s[16:17]
	global_load_dwordx4 v[242:245], v[164:165], off
	global_load_dwordx4 v[246:249], v[164:165], off offset:16
	s_waitcnt vmcnt(2)
	v_pk_fma_f32 v[148:149], v[236:237], s[28:29], v[122:123] op_sel_hi:[1,0,1]
	v_pk_fma_f32 v[150:151], v[234:235], s[28:29], v[120:121] op_sel_hi:[1,0,1]
	v_pk_fma_f32 v[126:127], v[240:241], s[28:29], v[126:127] op_sel_hi:[1,0,1]
	v_pk_fma_f32 v[152:153], v[238:239], s[28:29], v[124:125] op_sel_hi:[1,0,1]
	v_cvt_pk_bf16_f32 v120, v150, v151
	v_cvt_pk_bf16_f32 v121, v148, v149
	v_cvt_pk_bf16_f32 v122, v152, v153
	v_cvt_pk_bf16_f32 v123, v126, v127
	global_store_dwordx4 v[154:155], v[120:123], off
	s_nop 0
	s_nop 0
	v_or_b32_e32 v120, 32, v146
	v_ashrrev_i32_e32 v121, 31, v120
	v_lshlrev_b64 v[166:167], 11, v[120:121]
	v_lshl_add_u64 v[154:155], v[166:167], 0, v[156:157]
	v_lshl_add_u64 v[170:171], v[154:155], 2, s[48:49]
	v_lshl_add_u64 v[154:155], v[154:155], 1, s[16:17]
	global_load_dwordx4 v[234:237], v[170:171], off
	global_load_dwordx4 v[238:241], v[170:171], off offset:16
	s_waitcnt vmcnt(3)
	v_pk_fma_f32 v[122:123], v[244:245], s[28:29], v[118:119] op_sel_hi:[1,0,1]
	v_pk_fma_f32 v[124:125], v[242:243], s[28:29], v[116:117] op_sel_hi:[1,0,1]
	v_pk_fma_f32 v[116:117], v[248:249], s[28:29], v[114:115] op_sel_hi:[1,0,1]
	v_pk_fma_f32 v[118:119], v[246:247], s[28:29], v[112:113] op_sel_hi:[1,0,1]
	v_cvt_pk_bf16_f32 v112, v124, v125
	v_cvt_pk_bf16_f32 v113, v122, v123
	v_cvt_pk_bf16_f32 v114, v118, v119
	v_cvt_pk_bf16_f32 v115, v116, v117
	global_store_dwordx4 v[158:159], v[112:115], off
	s_nop 0
	s_nop 0
	v_or_b32_e32 v112, 48, v146
	v_ashrrev_i32_e32 v113, 31, v112
	v_lshlrev_b64 v[172:173], 11, v[112:113]
	v_lshl_add_u64 v[186:187], v[172:173], 0, v[156:157]
	v_lshl_add_u64 v[174:175], v[186:187], 2, s[48:49]
	v_lshl_add_u64 v[186:187], v[186:187], 1, s[16:17]
	global_load_dwordx4 v[242:245], v[174:175], off
	global_load_dwordx4 v[246:249], v[174:175], off offset:16
	s_waitcnt vmcnt(3)
	v_pk_fma_f32 v[110:111], v[236:237], s[28:29], v[110:111] op_sel_hi:[1,0,1]
	v_pk_fma_f32 v[114:115], v[234:235], s[28:29], v[108:109] op_sel_hi:[1,0,1]
	v_pk_fma_f32 v[106:107], v[240:241], s[28:29], v[106:107] op_sel_hi:[1,0,1]
	v_pk_fma_f32 v[108:109], v[238:239], s[28:29], v[104:105] op_sel_hi:[1,0,1]
	v_cvt_pk_bf16_f32 v176, v114, v115
	v_cvt_pk_bf16_f32 v177, v110, v111
	v_cvt_pk_bf16_f32 v178, v108, v109
	v_cvt_pk_bf16_f32 v179, v106, v107
	global_store_dwordx4 v[154:155], v[176:179], off
	s_nop 0
	s_nop 0
	v_add_u32_e32 v104, 0x80, v146
	v_ashrrev_i32_e32 v105, 31, v104
	v_lshlrev_b64 v[158:159], 11, v[104:105]
	v_lshl_add_u64 v[154:155], v[158:159], 0, v[156:157]
	v_lshl_add_u64 v[176:177], v[154:155], 2, s[48:49]
	v_lshl_add_u64 v[154:155], v[154:155], 1, s[16:17]
	global_load_dwordx4 v[234:237], v[176:177], off
	global_load_dwordx4 v[238:241], v[176:177], off offset:16
	s_waitcnt vmcnt(3)
	v_pk_fma_f32 v[102:103], v[244:245], s[28:29], v[102:103] op_sel_hi:[1,0,1]
	v_pk_fma_f32 v[100:101], v[242:243], s[28:29], v[100:101] op_sel_hi:[1,0,1]
	v_pk_fma_f32 v[98:99], v[248:249], s[28:29], v[98:99] op_sel_hi:[1,0,1]
	v_pk_fma_f32 v[96:97], v[246:247], s[28:29], v[96:97] op_sel_hi:[1,0,1]
	v_cvt_pk_bf16_f32 v178, v100, v101
	v_cvt_pk_bf16_f32 v179, v102, v103
	v_cvt_pk_bf16_f32 v180, v96, v97
	v_cvt_pk_bf16_f32 v181, v98, v99
	global_store_dwordx4 v[186:187], v[178:181], off
	s_nop 0
	s_nop 0
	v_add_u32_e32 v178, 0x90, v146
	v_ashrrev_i32_e32 v179, 31, v178
	v_lshlrev_b64 v[178:179], 11, v[178:179]
	v_lshl_add_u64 v[186:187], v[178:179], 0, v[156:157]
	v_lshl_add_u64 v[180:181], v[186:187], 2, s[48:49]
	global_load_dwordx4 v[242:245], v[180:181], off
	global_load_dwordx4 v[246:249], v[180:181], off offset:16
	s_waitcnt vmcnt(3)
	v_pk_fma_f32 v[94:95], v[236:237], s[28:29], v[94:95] op_sel_hi:[1,0,1]
	v_pk_fma_f32 v[92:93], v[234:235], s[28:29], v[92:93] op_sel_hi:[1,0,1]
	v_pk_fma_f32 v[90:91], v[240:241], s[28:29], v[90:91] op_sel_hi:[1,0,1]
	v_pk_fma_f32 v[88:89], v[238:239], s[28:29], v[88:89] op_sel_hi:[1,0,1]
	v_cvt_pk_bf16_f32 v182, v92, v93
	v_cvt_pk_bf16_f32 v183, v94, v95
	v_cvt_pk_bf16_f32 v184, v88, v89
	v_cvt_pk_bf16_f32 v185, v90, v91
	global_store_dwordx4 v[154:155], v[182:185], off
	s_nop 0
	s_nop 0
	v_add_u32_e32 v154, 0xa0, v146
	v_ashrrev_i32_e32 v155, 31, v154
	v_lshlrev_b64 v[182:183], 11, v[154:155]
	v_lshl_add_u64 v[154:155], v[186:187], 1, s[16:17]
	v_lshl_add_u64 v[204:205], v[182:183], 0, v[156:157]
	v_lshl_add_u64 v[184:185], v[204:205], 2, s[48:49]
	v_lshl_add_u64 v[204:205], v[204:205], 1, s[16:17]
	global_load_dwordx4 v[234:237], v[184:185], off
	global_load_dwordx4 v[238:241], v[184:185], off offset:16
	s_waitcnt vmcnt(3)
	v_pk_fma_f32 v[86:87], v[244:245], s[28:29], v[86:87] op_sel_hi:[1,0,1]
	v_pk_fma_f32 v[84:85], v[242:243], s[28:29], v[84:85] op_sel_hi:[1,0,1]
	v_pk_fma_f32 v[82:83], v[248:249], s[28:29], v[82:83] op_sel_hi:[1,0,1]
	v_pk_fma_f32 v[80:81], v[246:247], s[28:29], v[80:81] op_sel_hi:[1,0,1]
	v_cvt_pk_bf16_f32 v196, v84, v85
	v_cvt_pk_bf16_f32 v197, v86, v87
	v_cvt_pk_bf16_f32 v198, v80, v81
	v_cvt_pk_bf16_f32 v199, v82, v83
	global_store_dwordx4 v[154:155], v[196:199], off
	s_nop 0
	s_nop 0
	v_add_u32_e32 v154, 0xb0, v146
	v_ashrrev_i32_e32 v155, 31, v154
	v_lshlrev_b64 v[154:155], 11, v[154:155]
	v_lshl_add_u64 v[206:207], v[154:155], 0, v[156:157]
	v_lshl_add_u64 v[186:187], v[206:207], 2, s[48:49]
	v_or_b32_e32 v156, 0x80, v156
	v_ashrrev_i32_e32 v157, 31, v156
	v_lshl_add_u64 v[162:163], v[162:163], 0, v[156:157]
	v_lshl_add_u64 v[162:163], v[162:163], 1, s[16:17]
	v_lshl_add_u64 v[160:161], v[160:161], 0, v[156:157]
	v_lshl_add_u64 v[158:159], v[158:159], 0, v[156:157]
	global_load_dwordx4 v[242:245], v[186:187], off
	global_load_dwordx4 v[246:249], v[186:187], off offset:16
	s_waitcnt vmcnt(3)
	v_pk_fma_f32 v[78:79], v[236:237], s[28:29], v[78:79] op_sel_hi:[1,0,1]
	v_pk_fma_f32 v[76:77], v[234:235], s[28:29], v[76:77] op_sel_hi:[1,0,1]
	v_pk_fma_f32 v[74:75], v[240:241], s[28:29], v[74:75] op_sel_hi:[1,0,1]
	v_pk_fma_f32 v[72:73], v[238:239], s[28:29], v[72:73] op_sel_hi:[1,0,1]
	v_cvt_pk_bf16_f32 v196, v76, v77
	v_cvt_pk_bf16_f32 v197, v78, v79
	v_cvt_pk_bf16_f32 v198, v72, v73
	v_cvt_pk_bf16_f32 v199, v74, v75
	global_store_dwordx4 v[204:205], v[196:199], off
	s_nop 0
	s_nop 0
	v_lshl_add_u64 v[204:205], v[206:207], 1, s[16:17]
	global_load_dwordx4 v[234:237], v[168:169], off offset:512
	global_load_dwordx4 v[238:241], v[168:169], off offset:528
	s_waitcnt vmcnt(3)
	v_pk_fma_f32 v[70:71], v[244:245], s[28:29], v[70:71] op_sel_hi:[1,0,1]
	v_pk_fma_f32 v[68:69], v[242:243], s[28:29], v[68:69] op_sel_hi:[1,0,1]
	v_pk_fma_f32 v[66:67], v[248:249], s[28:29], v[66:67] op_sel_hi:[1,0,1]
	v_pk_fma_f32 v[64:65], v[246:247], s[28:29], v[64:65] op_sel_hi:[1,0,1]
	v_cvt_pk_bf16_f32 v196, v68, v69
	v_cvt_pk_bf16_f32 v197, v70, v71
	v_cvt_pk_bf16_f32 v198, v64, v65
	v_cvt_pk_bf16_f32 v199, v66, v67
	global_store_dwordx4 v[204:205], v[196:199], off
	s_nop 0
	s_nop 0
	v_lshl_add_u64 v[168:169], v[160:161], 1, s[16:17]
	global_load_dwordx4 v[242:245], v[164:165], off offset:512
	global_load_dwordx4 v[246:249], v[164:165], off offset:528
	s_waitcnt vmcnt(3)
	v_pk_fma_f32 v[62:63], v[236:237], s[28:29], v[62:63] op_sel_hi:[1,0,1]
	v_pk_fma_f32 v[60:61], v[234:235], s[28:29], v[60:61] op_sel_hi:[1,0,1]
	v_pk_fma_f32 v[58:59], v[240:241], s[28:29], v[58:59] op_sel_hi:[1,0,1]
	v_pk_fma_f32 v[56:57], v[238:239], s[28:29], v[56:57] op_sel_hi:[1,0,1]
	v_cvt_pk_bf16_f32 v196, v60, v61
	v_cvt_pk_bf16_f32 v197, v62, v63
	v_cvt_pk_bf16_f32 v198, v56, v57
	v_cvt_pk_bf16_f32 v199, v58, v59
	global_store_dwordx4 v[162:163], v[196:199], off
	s_nop 0
	s_nop 0
	s_nop 0
	global_load_dwordx4 v[234:237], v[170:171], off offset:512
	global_load_dwordx4 v[238:241], v[170:171], off offset:528
	s_waitcnt vmcnt(3)
	v_pk_fma_f32 v[54:55], v[244:245], s[28:29], v[54:55] op_sel_hi:[1,0,1]
	v_pk_fma_f32 v[52:53], v[242:243], s[28:29], v[52:53] op_sel_hi:[1,0,1]
	v_pk_fma_f32 v[50:51], v[248:249], s[28:29], v[50:51] op_sel_hi:[1,0,1]
	v_pk_fma_f32 v[48:49], v[246:247], s[28:29], v[48:49] op_sel_hi:[1,0,1]
	v_cvt_pk_bf16_f32 v160, v52, v53
	v_cvt_pk_bf16_f32 v161, v54, v55
	v_cvt_pk_bf16_f32 v162, v48, v49
	v_cvt_pk_bf16_f32 v163, v50, v51
	global_store_dwordx4 v[168:169], v[160:163], off
	s_nop 0
	s_nop 0
	s_nop 0
	v_lshl_add_u64 v[164:165], v[166:167], 0, v[156:157]
	v_lshl_add_u64 v[164:165], v[164:165], 1, s[16:17]
	global_load_dwordx4 v[242:245], v[174:175], off offset:512
	global_load_dwordx4 v[246:249], v[174:175], off offset:528
	s_waitcnt vmcnt(3)
	v_pk_fma_f32 v[46:47], v[236:237], s[28:29], v[46:47] op_sel_hi:[1,0,1]
	v_pk_fma_f32 v[44:45], v[234:235], s[28:29], v[44:45] op_sel_hi:[1,0,1]
	v_pk_fma_f32 v[42:43], v[240:241], s[28:29], v[42:43] op_sel_hi:[1,0,1]
	v_pk_fma_f32 v[40:41], v[238:239], s[28:29], v[40:41] op_sel_hi:[1,0,1]
	v_cvt_pk_bf16_f32 v160, v44, v45
	v_cvt_pk_bf16_f32 v161, v46, v47
	v_cvt_pk_bf16_f32 v162, v40, v41
	v_cvt_pk_bf16_f32 v163, v42, v43
	global_store_dwordx4 v[164:165], v[160:163], off
	s_nop 0
	s_nop 0
	v_lshl_add_u64 v[168:169], v[172:173], 0, v[156:157]
	v_lshl_add_u64 v[168:169], v[168:169], 1, s[16:17]
	global_load_dwordx4 v[234:237], v[176:177], off offset:512
	global_load_dwordx4 v[238:241], v[176:177], off offset:528
	s_waitcnt vmcnt(3)
	v_pk_fma_f32 v[38:39], v[244:245], s[28:29], v[38:39] op_sel_hi:[1,0,1]
	v_pk_fma_f32 v[36:37], v[242:243], s[28:29], v[36:37] op_sel_hi:[1,0,1]
	v_pk_fma_f32 v[34:35], v[248:249], s[28:29], v[34:35] op_sel_hi:[1,0,1]
	v_pk_fma_f32 v[32:33], v[246:247], s[28:29], v[32:33] op_sel_hi:[1,0,1]
	v_cvt_pk_bf16_f32 v160, v36, v37
	v_cvt_pk_bf16_f32 v161, v38, v39
	v_cvt_pk_bf16_f32 v162, v32, v33
	v_cvt_pk_bf16_f32 v163, v34, v35
	global_store_dwordx4 v[168:169], v[160:163], off
	s_nop 0
	s_nop 0
	v_lshl_add_u64 v[168:169], v[158:159], 1, s[16:17]
	global_load_dwordx4 v[242:245], v[180:181], off offset:512
	global_load_dwordx4 v[246:249], v[180:181], off offset:528
	s_waitcnt vmcnt(3)
	v_pk_fma_f32 v[30:31], v[236:237], s[28:29], v[30:31] op_sel_hi:[1,0,1]
	v_pk_fma_f32 v[28:29], v[234:235], s[28:29], v[28:29] op_sel_hi:[1,0,1]
	v_pk_fma_f32 v[26:27], v[240:241], s[28:29], v[26:27] op_sel_hi:[1,0,1]
	v_pk_fma_f32 v[24:25], v[238:239], s[28:29], v[24:25] op_sel_hi:[1,0,1]
	v_cvt_pk_bf16_f32 v158, v28, v29
	v_cvt_pk_bf16_f32 v159, v30, v31
	v_cvt_pk_bf16_f32 v160, v24, v25
	v_cvt_pk_bf16_f32 v161, v26, v27
	global_store_dwordx4 v[168:169], v[158:161], off
	s_nop 0
	s_nop 0
	v_lshl_add_u64 v[166:167], v[178:179], 0, v[156:157]
	v_lshl_add_u64 v[166:167], v[166:167], 1, s[16:17]
	v_add_f32_e32 v168, v152, v153
	v_add_f32_e32 v169, v126, v127
	v_mul_f32_e32 v153, v153, v153
	v_mul_f32_e32 v127, v127, v127
	v_fmac_f32_e32 v153, v152, v152
	v_fmac_f32_e32 v127, v126, v126
	v_add_f32_e32 v127, v153, v127
	global_load_dwordx4 v[234:237], v[184:185], off offset:512
	global_load_dwordx4 v[238:241], v[184:185], off offset:528
	s_waitcnt vmcnt(3)
	v_pk_fma_f32 v[22:23], v[244:245], s[28:29], v[22:23] op_sel_hi:[1,0,1]
	v_pk_fma_f32 v[20:21], v[242:243], s[28:29], v[20:21] op_sel_hi:[1,0,1]
	v_pk_fma_f32 v[18:19], v[248:249], s[28:29], v[18:19] op_sel_hi:[1,0,1]
	v_pk_fma_f32 v[16:17], v[246:247], s[28:29], v[16:17] op_sel_hi:[1,0,1]
	v_cvt_pk_bf16_f32 v158, v20, v21
	v_cvt_pk_bf16_f32 v159, v22, v23
	v_cvt_pk_bf16_f32 v160, v16, v17
	v_cvt_pk_bf16_f32 v161, v18, v19
	global_store_dwordx4 v[166:167], v[158:161], off
	s_nop 0
	s_nop 0
	v_lshl_add_u64 v[166:167], v[182:183], 0, v[156:157]
	v_lshl_add_u64 v[166:167], v[166:167], 1, s[16:17]
	s_waitcnt vmcnt(1)
	v_pk_fma_f32 v[14:15], v[236:237], s[28:29], v[14:15] op_sel_hi:[1,0,1]
	v_pk_fma_f32 v[12:13], v[234:235], s[28:29], v[12:13] op_sel_hi:[1,0,1]
	v_pk_fma_f32 v[10:11], v[240:241], s[28:29], v[10:11] op_sel_hi:[1,0,1]
	v_pk_fma_f32 v[8:9], v[238:239], s[28:29], v[8:9] op_sel_hi:[1,0,1]
	v_cvt_pk_bf16_f32 v158, v12, v13
	v_cvt_pk_bf16_f32 v159, v14, v15
	v_cvt_pk_bf16_f32 v160, v8, v9
	v_cvt_pk_bf16_f32 v161, v10, v11
	global_store_dwordx4 v[166:167], v[158:161], off
	global_load_dwordx4 v[158:161], v[186:187], off offset:512
	global_load_dwordx4 v[162:165], v[186:187], off offset:528
	v_add_f32_e32 v166, v150, v151
	v_add_f32_e32 v167, v148, v149
	v_mul_f32_e32 v151, v151, v151
	v_mul_f32_e32 v149, v149, v149
	v_fmac_f32_e32 v151, v150, v150
	v_fmac_f32_e32 v149, v148, v148
	v_add_f32_e32 v148, v151, v149
	v_add_f32_e32 v166, v166, v167
	v_add_f32_e32 v167, v168, v169
	v_add_f32_e32 v127, v148, v127
	v_add_f32_e32 v148, v60, v61
	v_add_f32_e32 v149, v62, v63
	v_add_f32_e32 v150, v56, v57
	v_add_f32_e32 v151, v58, v59
	v_mul_f32_e32 v61, v61, v61
	v_mul_f32_e32 v63, v63, v63
	v_mul_f32_e32 v57, v57, v57
	v_mul_f32_e32 v59, v59, v59
	v_add_f32_e32 v126, v166, v167
	v_add_f32_e32 v148, v148, v149
	v_add_f32_e32 v149, v150, v151
	v_fmac_f32_e32 v61, v60, v60
	v_fmac_f32_e32 v63, v62, v62
	v_fmac_f32_e32 v57, v56, v56
	v_fmac_f32_e32 v59, v58, v58
	v_add_f32_e32 v126, 0, v126
	v_add_f32_e32 v56, v148, v149
	v_add_f32_e32 v58, v61, v63
	v_add_f32_e32 v57, v57, v59
	v_add_f32_e32 v59, v126, v56
	v_add_f32_e32 v56, v58, v57
	v_add_f32_e32 v60, v127, v56
	ds_bpermute_b32 v58, v190, v59
	ds_bpermute_b32 v61, v190, v60
	v_lshl_add_u64 v[56:57], v[154:155], 0, v[156:157]
	v_lshl_add_u64 v[126:127], v[56:57], 1, s[16:17]
	s_waitcnt lgkmcnt(0)
	v_add_f32_e32 v56, v59, v58
	v_add_f32_e32 v58, v60, v61
	ds_bpermute_b32 v57, v191, v56
	ds_bpermute_b32 v59, v191, v58
	s_waitcnt vmcnt(1)
	v_pk_fma_f32 v[6:7], v[160:161], s[28:29], v[6:7] op_sel_hi:[1,0,1]
	v_pk_fma_f32 v[4:5], v[158:159], s[28:29], v[4:5] op_sel_hi:[1,0,1]
	s_waitcnt vmcnt(0)
	v_pk_fma_f32 v[2:3], v[164:165], s[28:29], v[2:3] op_sel_hi:[1,0,1]
	v_pk_fma_f32 v[0:1], v[162:163], s[28:29], v[0:1] op_sel_hi:[1,0,1]
	v_cvt_pk_bf16_f32 v60, v4, v5
	v_cvt_pk_bf16_f32 v61, v6, v7
	v_cvt_pk_bf16_f32 v62, v0, v1
	v_cvt_pk_bf16_f32 v63, v2, v3
	global_store_dwordx4 v[126:127], v[60:63], off
	s_and_saveexec_b64 s[34:35], s[6:7]
	s_cbranch_execz .LBB0_680
	s_waitcnt lgkmcnt(0)
	v_add_f32_e32 v58, v58, v59
	v_add_f32_e32 v59, v56, v57
	v_lshl_add_u64 v[56:57], v[146:147], 3, s[20:21]
	global_atomic_add_f32 v[56:57], v59, off
	global_atomic_add_f32 v[56:57], v58, off offset:4

.LBB0_858:
	v_lshl_add_u32 v128, s84, 8, v224
	v_ashrrev_i32_e32 v129, 31, v128
	v_lshlrev_b64 v[164:165], 3, v[128:129]
	v_lshl_add_u64 v[130:131], s[20:21], 0, v[164:165]
	global_load_dwordx2 v[186:187], v[130:131], off
	v_lshl_or_b32 v130, s81, 8, v228
	v_ashrrev_i32_e32 v131, 31, v130
	v_lshlrev_b64 v[132:133], 12, v[128:129]
	v_lshl_add_u64 v[132:133], s[16:17], 0, v[132:133]
	v_lshlrev_b64 v[178:179], 1, v[130:131]
	v_lshl_add_u64 v[176:177], v[132:133], 0, v[178:179]
	global_load_dwordx4 v[192:195], v[176:177], off
	v_or_b32_e32 v196, 16, v128
	v_or_b32_e32 v218, 32, v128
	v_or_b32_e32 v198, 48, v128
	v_add_u32_e32 v204, 0x80, v128
	v_add_u32_e32 v208, 0x90, v128
	v_add_u32_e32 v184, 0xa0, v128
	v_add_u32_e32 v180, 0xb0, v128
	v_lshlrev_b64 v[128:129], 2, v[130:131]
	v_lshl_add_u64 v[188:189], s[64:65], 0, v[128:129]
	v_lshl_add_u64 v[190:191], s[66:67], 0, v[128:129]
	global_load_dwordx4 v[128:131], v[188:189], off offset:16
	global_load_dwordx4 v[136:139], v[188:189], off
	global_load_dwordx4 v[132:135], v[190:191], off offset:16
	global_load_dwordx4 v[140:143], v[190:191], off
	v_ashrrev_i32_e32 v197, 31, v196
	v_ashrrev_i32_e32 v219, 31, v218
	v_ashrrev_i32_e32 v199, 31, v198
	v_ashrrev_i32_e32 v205, 31, v204
	v_ashrrev_i32_e32 v209, 31, v208
	v_ashrrev_i32_e32 v185, 31, v184
	v_ashrrev_i32_e32 v181, 31, v180
	v_lshlrev_b64 v[174:175], 3, v[196:197]
	v_lshlrev_b64 v[172:173], 3, v[218:219]
	v_lshlrev_b64 v[170:171], 3, v[198:199]
	v_lshlrev_b64 v[168:169], 3, v[204:205]
	v_lshlrev_b64 v[166:167], 3, v[208:209]
	v_lshlrev_b64 v[162:163], 3, v[184:185]
	v_lshlrev_b64 v[160:161], 3, v[180:181]
	v_lshl_add_u64 v[182:183], s[20:21], 0, v[174:175]
	v_lshl_add_u64 v[200:201], s[20:21], 0, v[172:173]
	v_lshl_add_u64 v[202:203], s[20:21], 0, v[170:171]
	v_lshl_add_u64 v[210:211], s[20:21], 0, v[168:169]
	v_lshl_add_u64 v[212:213], s[20:21], 0, v[166:167]
	v_lshl_add_u64 v[214:215], s[20:21], 0, v[162:163]
	v_lshl_add_u64 v[216:217], s[20:21], 0, v[160:161]
	global_load_dwordx2 v[234:235], v[182:183], off
	s_nop 0
	global_load_dwordx2 v[200:201], v[200:201], off
	s_nop 0
	global_load_dwordx2 v[206:207], v[202:203], off
	s_nop 0
	global_load_dwordx2 v[210:211], v[210:211], off
	s_nop 0
	global_load_dwordx2 v[212:213], v[212:213], off
	s_nop 0
	global_load_dwordx2 v[182:183], v[214:215], off
	global_load_dwordx2 v[202:203], v[216:217], off
	v_lshlrev_b64 v[198:199], 12, v[198:199]
	v_lshl_add_u64 v[198:199], s[16:17], 0, v[198:199]
	v_lshl_add_u64 v[198:199], v[198:199], 0, v[178:179]
	v_lshlrev_b64 v[204:205], 12, v[204:205]
	v_lshl_add_u64 v[204:205], s[16:17], 0, v[204:205]
	v_lshl_add_u64 v[204:205], v[204:205], 0, v[178:179]
	v_lshlrev_b64 v[208:209], 12, v[208:209]
	v_lshl_add_u64 v[208:209], s[16:17], 0, v[208:209]
	v_lshl_add_u64 v[208:209], v[208:209], 0, v[178:179]
	v_lshlrev_b64 v[184:185], 12, v[184:185]
	v_lshl_add_u64 v[184:185], s[16:17], 0, v[184:185]
	v_lshlrev_b64 v[180:181], 12, v[180:181]
	v_lshl_add_u64 v[180:181], s[16:17], 0, v[180:181]
	s_waitcnt vmcnt(0)
	v_pk_mul_f32 v[186:187], v[186:187], s[34:35] op_sel:[1,0] op_sel_hi:[0,0]
	v_fma_f32 v186, -v187, v187, v186
	v_max_f32_e32 v186, 0, v186
	v_add_f32_e32 v186, 0x3727c5ac, v186
	v_cmp_gt_f32_e32 vcc, s78, v186
	v_lshlrev_b32_e32 v214, 16, v192
	v_and_b32_e32 v192, 0xffff0000, v192
	v_lshlrev_b32_e32 v215, 16, v193
	v_and_b32_e32 v216, 0xffff0000, v193
	v_sub_f32_e32 v193, v192, v187
	v_sub_f32_e32 v192, v214, v187
	v_mul_f32_e32 v214, 0x4f800000, v186
	v_cndmask_b32_e32 v186, v186, v214, vcc
	v_lshlrev_b32_e32 v236, 16, v195
	v_and_b32_e32 v237, 0xffff0000, v195
	v_sub_f32_e32 v195, v216, v187
	v_sqrt_f32_e32 v216, v186
	v_and_b32_e32 v233, 0xffff0000, v194
	v_lshlrev_b32_e32 v217, 16, v194
	v_sub_f32_e32 v194, v215, v187
	v_sub_f32_e32 v215, v233, v187
	v_add_u32_e32 v233, -1, v216
	v_sub_f32_e32 v214, v217, v187
	v_sub_f32_e32 v217, v237, v187
	v_add_u32_e32 v237, 1, v216
	v_fma_f32 v238, -v233, v216, v186
	v_fma_f32 v239, -v237, v216, v186
	v_cmp_ge_f32_e64 s[0:1], 0, v238
	v_pk_mul_f32 v[200:201], v[200:201], s[34:35] op_sel:[1,0] op_sel_hi:[0,0]
	s_nop 0
	v_cndmask_b32_e64 v216, v216, v233, s[0:1]
	v_cmp_lt_f32_e64 s[0:1], 0, v239
	v_fma_f32 v200, -v201, v201, v200
	v_max_f32_e32 v200, 0, v200
	v_cndmask_b32_e64 v216, v216, v237, s[0:1]
	v_mul_f32_e32 v233, 0x37800000, v216
	v_cndmask_b32_e32 v216, v216, v233, vcc
	v_cmp_class_f32_e32 vcc, v186, v232
	v_add_f32_e32 v200, 0x3727c5ac, v200
	v_pk_mul_f32 v[206:207], v[206:207], s[34:35] op_sel:[1,0] op_sel_hi:[0,0]
	v_cndmask_b32_e32 v186, v216, v186, vcc
	v_div_scale_f32 v233, s[0:1], v186, v186, 1.0
	v_rcp_f32_e32 v237, v233
	v_sub_f32_e32 v216, v236, v187
	v_div_scale_f32 v236, vcc, 1.0, v186, 1.0
	v_fma_f32 v238, -v233, v237, 1.0
	v_fmac_f32_e32 v237, v238, v237
	v_mul_f32_e32 v238, v236, v237
	v_fma_f32 v239, -v233, v238, v236
	v_fmac_f32_e32 v238, v239, v237
	v_fma_f32 v233, -v233, v238, v236
	v_div_fmas_f32 v233, v233, v237, v238
	v_div_fixup_f32 v186, v233, v186, 1.0
	v_pk_mul_f32 v[194:195], v[186:187], v[194:195] op_sel_hi:[0,1]
	v_pk_mul_f32 v[192:193], v[186:187], v[192:193] op_sel_hi:[0,1]
	v_pk_mul_f32 v[216:217], v[186:187], v[216:217] op_sel_hi:[0,1]
	v_pk_mul_f32 v[214:215], v[186:187], v[214:215] op_sel_hi:[0,1]
	v_pk_fma_f32 v[192:193], v[136:137], v[192:193], v[140:141]
	v_pk_fma_f32 v[194:195], v[138:139], v[194:195], v[142:143]
	v_pk_fma_f32 v[214:215], v[128:129], v[214:215], v[132:133]
	v_pk_fma_f32 v[216:217], v[130:131], v[216:217], v[134:135]
	v_pk_fma_f32 v[126:127], v[194:195], s[36:37], v[126:127] op_sel_hi:[1,0,1]
	v_pk_fma_f32 v[124:125], v[192:193], s[36:37], v[124:125] op_sel_hi:[1,0,1]
	v_pk_fma_f32 v[122:123], v[216:217], s[36:37], v[122:123] op_sel_hi:[1,0,1]
	v_pk_fma_f32 v[120:121], v[214:215], s[36:37], v[120:121] op_sel_hi:[1,0,1]
	v_cvt_pk_bf16_f32 v192, v124, v125
	v_cvt_pk_bf16_f32 v193, v126, v127
	v_cvt_pk_bf16_f32 v194, v120, v121
	v_cvt_pk_bf16_f32 v195, v122, v123
	global_store_dwordx4 v[176:177], v[192:195], off
	v_fma_f32 v206, -v207, v207, v206
	v_max_f32_e32 v206, 0, v206
	v_lshlrev_b64 v[192:193], 12, v[196:197]
	v_lshl_add_u64 v[192:193], s[16:17], 0, v[192:193]
	v_lshl_add_u64 v[192:193], v[192:193], 0, v[178:179]
	global_load_dwordx4 v[240:243], v[192:193], off
	v_pk_mul_f32 v[196:197], v[234:235], s[34:35] op_sel:[1,0] op_sel_hi:[0,0]
	v_fma_f32 v194, -v197, v197, v196
	v_max_f32_e32 v194, 0, v194
	v_add_f32_e32 v194, 0x3727c5ac, v194
	v_mul_f32_e32 v195, 0x4f800000, v194
	v_cmp_gt_f32_e32 vcc, s78, v194
	v_add_f32_e32 v206, 0x3727c5ac, v206
	v_pk_mul_f32 v[210:211], v[210:211], s[34:35] op_sel:[1,0] op_sel_hi:[0,0]
	v_cndmask_b32_e32 v196, v194, v195, vcc
	v_sqrt_f32_e32 v233, v196
	v_lshlrev_b64 v[194:195], 12, v[218:219]
	v_lshl_add_u64 v[194:195], s[16:17], 0, v[194:195]
	v_lshl_add_u64 v[194:195], v[194:195], 0, v[178:179]
	v_add_u32_e32 v218, -1, v233
	v_add_u32_e32 v219, 1, v233
	v_fma_f32 v234, -v218, v233, v196
	v_fma_f32 v235, -v219, v233, v196
	v_cmp_ge_f32_e64 s[0:1], 0, v234
	v_fma_f32 v210, -v211, v211, v210
	v_max_f32_e32 v210, 0, v210
	v_cndmask_b32_e64 v218, v233, v218, s[0:1]
	v_cmp_lt_f32_e64 s[0:1], 0, v235
	v_add_f32_e32 v210, 0x3727c5ac, v210
	v_pk_mul_f32 v[202:203], v[202:203], s[34:35] op_sel:[1,0] op_sel_hi:[0,0]
	v_cndmask_b32_e64 v218, v218, v219, s[0:1]
	v_mul_f32_e32 v219, 0x37800000, v218
	v_cndmask_b32_e32 v218, v218, v219, vcc
	v_cmp_class_f32_e32 vcc, v196, v232
	global_load_dwordx4 v[244:247], v[194:195], off
	s_waitcnt vmcnt(1)
	v_lshlrev_b32_e32 v236, 16, v243
	v_cndmask_b32_e32 v196, v218, v196, vcc
	v_div_scale_f32 v218, s[0:1], v196, v196, 1.0
	v_rcp_f32_e32 v219, v218
	v_div_scale_f32 v233, vcc, 1.0, v196, 1.0
	v_and_b32_e32 v237, 0xffff0000, v243
	v_fma_f32 v234, -v218, v219, 1.0
	v_fmac_f32_e32 v219, v234, v219
	v_mul_f32_e32 v234, v233, v219
	v_fma_f32 v235, -v218, v234, v233
	v_fmac_f32_e32 v234, v235, v219
	v_fma_f32 v218, -v218, v234, v233
	v_div_fmas_f32 v218, v218, v219, v234
	v_div_fixup_f32 v196, v218, v196, 1.0
	v_lshlrev_b32_e32 v218, 16, v240
	v_and_b32_e32 v214, 0xffff0000, v240
	v_lshlrev_b32_e32 v219, 16, v241
	v_and_b32_e32 v233, 0xffff0000, v241
	v_lshlrev_b32_e32 v234, 16, v242
	v_and_b32_e32 v235, 0xffff0000, v242
	v_sub_f32_e32 v215, v214, v197
	v_sub_f32_e32 v214, v218, v197
	v_sub_f32_e32 v217, v233, v197
	v_sub_f32_e32 v216, v219, v197
	v_sub_f32_e32 v219, v235, v197
	v_sub_f32_e32 v218, v234, v197
	v_sub_f32_e32 v235, v237, v197
	v_sub_f32_e32 v234, v236, v197
	v_pk_mul_f32 v[216:217], v[196:197], v[216:217] op_sel_hi:[0,1]
	v_pk_mul_f32 v[214:215], v[196:197], v[214:215] op_sel_hi:[0,1]
	v_pk_mul_f32 v[234:235], v[196:197], v[234:235] op_sel_hi:[0,1]
	v_pk_mul_f32 v[218:219], v[196:197], v[218:219] op_sel_hi:[0,1]
	v_pk_fma_f32 v[214:215], v[136:137], v[214:215], v[140:141]
	v_pk_fma_f32 v[216:217], v[138:139], v[216:217], v[142:143]
	v_pk_fma_f32 v[218:219], v[128:129], v[218:219], v[132:133]
	v_pk_fma_f32 v[234:235], v[130:131], v[234:235], v[134:135]
	v_pk_fma_f32 v[118:119], v[216:217], s[36:37], v[118:119] op_sel_hi:[1,0,1]
	v_pk_fma_f32 v[116:117], v[214:215], s[36:37], v[116:117] op_sel_hi:[1,0,1]
	v_pk_fma_f32 v[114:115], v[234:235], s[36:37], v[114:115] op_sel_hi:[1,0,1]
	v_pk_fma_f32 v[112:113], v[218:219], s[36:37], v[112:113] op_sel_hi:[1,0,1]
	v_cvt_pk_bf16_f32 v214, v116, v117
	v_cvt_pk_bf16_f32 v215, v118, v119
	v_cvt_pk_bf16_f32 v216, v112, v113
	v_cvt_pk_bf16_f32 v217, v114, v115
	global_store_dwordx4 v[192:193], v[214:217], off
	s_nop 0
	v_mul_f32_e32 v218, 0x4f800000, v200
	v_cmp_gt_f32_e32 vcc, s78, v200
	global_load_dwordx4 v[240:243], v[198:199], off
	s_waitcnt vmcnt(2)
	v_lshlrev_b32_e32 v236, 16, v247
	v_cndmask_b32_e32 v200, v200, v218, vcc
	v_sqrt_f32_e32 v218, v200
	v_and_b32_e32 v237, 0xffff0000, v247
	v_add_u32_e32 v219, -1, v218
	v_add_u32_e32 v233, 1, v218
	v_fma_f32 v234, -v219, v218, v200
	v_fma_f32 v235, -v233, v218, v200
	v_cmp_ge_f32_e64 s[0:1], 0, v234
	s_nop 1
	v_cndmask_b32_e64 v218, v218, v219, s[0:1]
	v_cmp_lt_f32_e64 s[0:1], 0, v235
	s_nop 1
	v_cndmask_b32_e64 v218, v218, v233, s[0:1]
	v_mul_f32_e32 v219, 0x37800000, v218
	v_cndmask_b32_e32 v218, v218, v219, vcc
	v_cmp_class_f32_e32 vcc, v200, v232
	s_nop 1
	v_cndmask_b32_e32 v200, v218, v200, vcc
	v_div_scale_f32 v218, s[0:1], v200, v200, 1.0
	v_rcp_f32_e32 v219, v218
	v_div_scale_f32 v233, vcc, 1.0, v200, 1.0
	v_fma_f32 v234, -v218, v219, 1.0
	v_fmac_f32_e32 v219, v234, v219
	v_mul_f32_e32 v234, v233, v219
	v_fma_f32 v235, -v218, v234, v233
	v_fmac_f32_e32 v234, v235, v219
	v_fma_f32 v218, -v218, v234, v233
	v_div_fmas_f32 v218, v218, v219, v234
	v_div_fixup_f32 v200, v218, v200, 1.0
	v_lshlrev_b32_e32 v218, 16, v244
	v_and_b32_e32 v214, 0xffff0000, v244
	v_lshlrev_b32_e32 v219, 16, v245
	v_and_b32_e32 v233, 0xffff0000, v245
	v_lshlrev_b32_e32 v234, 16, v246
	v_and_b32_e32 v235, 0xffff0000, v246
	v_sub_f32_e32 v215, v214, v201
	v_sub_f32_e32 v214, v218, v201
	v_sub_f32_e32 v217, v233, v201
	v_sub_f32_e32 v216, v219, v201
	v_sub_f32_e32 v219, v235, v201
	v_sub_f32_e32 v218, v234, v201
	v_sub_f32_e32 v235, v237, v201
	v_sub_f32_e32 v234, v236, v201
	v_pk_mul_f32 v[216:217], v[200:201], v[216:217] op_sel_hi:[0,1]
	v_pk_mul_f32 v[214:215], v[200:201], v[214:215] op_sel_hi:[0,1]
	v_pk_mul_f32 v[234:235], v[200:201], v[234:235] op_sel_hi:[0,1]
	v_pk_mul_f32 v[218:219], v[200:201], v[218:219] op_sel_hi:[0,1]
	v_pk_fma_f32 v[214:215], v[136:137], v[214:215], v[140:141]
	v_pk_fma_f32 v[216:217], v[138:139], v[216:217], v[142:143]
	v_pk_fma_f32 v[218:219], v[128:129], v[218:219], v[132:133]
	v_pk_fma_f32 v[234:235], v[130:131], v[234:235], v[134:135]
	v_pk_fma_f32 v[110:111], v[216:217], s[36:37], v[110:111] op_sel_hi:[1,0,1]
	v_pk_fma_f32 v[108:109], v[214:215], s[36:37], v[108:109] op_sel_hi:[1,0,1]
	v_pk_fma_f32 v[106:107], v[234:235], s[36:37], v[106:107] op_sel_hi:[1,0,1]
	v_pk_fma_f32 v[104:105], v[218:219], s[36:37], v[104:105] op_sel_hi:[1,0,1]
	v_cvt_pk_bf16_f32 v214, v108, v109
	v_cvt_pk_bf16_f32 v215, v110, v111
	v_cvt_pk_bf16_f32 v216, v104, v105
	v_cvt_pk_bf16_f32 v217, v106, v107
	global_store_dwordx4 v[194:195], v[214:217], off
	s_nop 0
	v_mul_f32_e32 v218, 0x4f800000, v206
	v_cmp_gt_f32_e32 vcc, s78, v206
	global_load_dwordx4 v[244:247], v[204:205], off
	s_waitcnt vmcnt(2)
	v_lshlrev_b32_e32 v236, 16, v243
	v_cndmask_b32_e32 v206, v206, v218, vcc
	v_sqrt_f32_e32 v218, v206
	v_and_b32_e32 v237, 0xffff0000, v243
	v_add_u32_e32 v219, -1, v218
	v_add_u32_e32 v233, 1, v218
	v_fma_f32 v234, -v219, v218, v206
	v_fma_f32 v235, -v233, v218, v206
	v_cmp_ge_f32_e64 s[0:1], 0, v234
	s_nop 1
	v_cndmask_b32_e64 v218, v218, v219, s[0:1]
	v_cmp_lt_f32_e64 s[0:1], 0, v235
	s_nop 1
	v_cndmask_b32_e64 v218, v218, v233, s[0:1]
	v_mul_f32_e32 v219, 0x37800000, v218
	v_cndmask_b32_e32 v218, v218, v219, vcc
	v_cmp_class_f32_e32 vcc, v206, v232
	s_nop 1
	v_cndmask_b32_e32 v206, v218, v206, vcc
	v_div_scale_f32 v218, s[0:1], v206, v206, 1.0
	v_rcp_f32_e32 v219, v218
	v_div_scale_f32 v233, vcc, 1.0, v206, 1.0
	v_fma_f32 v234, -v218, v219, 1.0
	v_fmac_f32_e32 v219, v234, v219
	v_mul_f32_e32 v234, v233, v219
	v_fma_f32 v235, -v218, v234, v233
	v_fmac_f32_e32 v234, v235, v219
	v_fma_f32 v218, -v218, v234, v233
	v_div_fmas_f32 v218, v218, v219, v234
	v_div_fixup_f32 v206, v218, v206, 1.0
	v_lshlrev_b32_e32 v218, 16, v240
	v_and_b32_e32 v214, 0xffff0000, v240
	v_lshlrev_b32_e32 v219, 16, v241
	v_and_b32_e32 v233, 0xffff0000, v241
	v_lshlrev_b32_e32 v234, 16, v242
	v_and_b32_e32 v235, 0xffff0000, v242
	v_sub_f32_e32 v215, v214, v207
	v_sub_f32_e32 v214, v218, v207
	v_sub_f32_e32 v217, v233, v207
	v_sub_f32_e32 v216, v219, v207
	v_sub_f32_e32 v219, v235, v207
	v_sub_f32_e32 v218, v234, v207
	v_sub_f32_e32 v235, v237, v207
	v_sub_f32_e32 v234, v236, v207
	v_pk_mul_f32 v[216:217], v[206:207], v[216:217] op_sel_hi:[0,1]
	v_pk_mul_f32 v[214:215], v[206:207], v[214:215] op_sel_hi:[0,1]
	v_pk_mul_f32 v[234:235], v[206:207], v[234:235] op_sel_hi:[0,1]
	v_pk_mul_f32 v[218:219], v[206:207], v[218:219] op_sel_hi:[0,1]
	v_pk_fma_f32 v[214:215], v[136:137], v[214:215], v[140:141]
	v_pk_fma_f32 v[216:217], v[138:139], v[216:217], v[142:143]
	v_pk_fma_f32 v[218:219], v[128:129], v[218:219], v[132:133]
	v_pk_fma_f32 v[234:235], v[130:131], v[234:235], v[134:135]
	v_pk_fma_f32 v[102:103], v[216:217], s[36:37], v[102:103] op_sel_hi:[1,0,1]
	v_pk_fma_f32 v[100:101], v[214:215], s[36:37], v[100:101] op_sel_hi:[1,0,1]
	v_pk_fma_f32 v[98:99], v[234:235], s[36:37], v[98:99] op_sel_hi:[1,0,1]
	v_pk_fma_f32 v[96:97], v[218:219], s[36:37], v[96:97] op_sel_hi:[1,0,1]
	v_cvt_pk_bf16_f32 v214, v100, v101
	v_cvt_pk_bf16_f32 v215, v102, v103
	v_cvt_pk_bf16_f32 v216, v96, v97
	v_cvt_pk_bf16_f32 v217, v98, v99
	global_store_dwordx4 v[198:199], v[214:217], off
	s_nop 0
	v_mul_f32_e32 v218, 0x4f800000, v210
	v_cmp_gt_f32_e32 vcc, s78, v210
	global_load_dwordx4 v[240:243], v[208:209], off
	s_waitcnt vmcnt(2)
	v_lshlrev_b32_e32 v236, 16, v247
	v_cndmask_b32_e32 v210, v210, v218, vcc
	v_sqrt_f32_e32 v218, v210
	v_and_b32_e32 v237, 0xffff0000, v247
	v_add_u32_e32 v219, -1, v218
	v_add_u32_e32 v233, 1, v218
	v_fma_f32 v234, -v219, v218, v210
	v_fma_f32 v235, -v233, v218, v210
	v_cmp_ge_f32_e64 s[0:1], 0, v234
	s_nop 1
	v_cndmask_b32_e64 v218, v218, v219, s[0:1]
	v_cmp_lt_f32_e64 s[0:1], 0, v235
	s_nop 1
	v_cndmask_b32_e64 v218, v218, v233, s[0:1]
	v_mul_f32_e32 v219, 0x37800000, v218
	v_cndmask_b32_e32 v218, v218, v219, vcc
	v_cmp_class_f32_e32 vcc, v210, v232
	s_nop 1
	v_cndmask_b32_e32 v210, v218, v210, vcc
	v_div_scale_f32 v218, s[0:1], v210, v210, 1.0
	v_rcp_f32_e32 v219, v218
	v_div_scale_f32 v233, vcc, 1.0, v210, 1.0
	v_fma_f32 v234, -v218, v219, 1.0
	v_fmac_f32_e32 v219, v234, v219
	v_mul_f32_e32 v234, v233, v219
	v_fma_f32 v235, -v218, v234, v233
	v_fmac_f32_e32 v234, v235, v219
	v_fma_f32 v218, -v218, v234, v233
	v_div_fmas_f32 v218, v218, v219, v234
	v_div_fixup_f32 v210, v218, v210, 1.0
	v_lshlrev_b32_e32 v218, 16, v244
	v_and_b32_e32 v214, 0xffff0000, v244
	v_lshlrev_b32_e32 v219, 16, v245
	v_and_b32_e32 v233, 0xffff0000, v245
	v_lshlrev_b32_e32 v234, 16, v246
	v_and_b32_e32 v235, 0xffff0000, v246
	v_sub_f32_e32 v215, v214, v211
	v_sub_f32_e32 v214, v218, v211
	v_sub_f32_e32 v217, v233, v211
	v_sub_f32_e32 v216, v219, v211
	v_sub_f32_e32 v219, v235, v211
	v_sub_f32_e32 v218, v234, v211
	v_sub_f32_e32 v235, v237, v211
	v_sub_f32_e32 v234, v236, v211
	v_pk_mul_f32 v[216:217], v[210:211], v[216:217] op_sel_hi:[0,1]
	v_pk_mul_f32 v[214:215], v[210:211], v[214:215] op_sel_hi:[0,1]
	v_pk_mul_f32 v[234:235], v[210:211], v[234:235] op_sel_hi:[0,1]
	v_pk_mul_f32 v[218:219], v[210:211], v[218:219] op_sel_hi:[0,1]
	v_pk_fma_f32 v[214:215], v[136:137], v[214:215], v[140:141]
	v_pk_fma_f32 v[216:217], v[138:139], v[216:217], v[142:143]
	v_pk_fma_f32 v[218:219], v[128:129], v[218:219], v[132:133]
	v_pk_fma_f32 v[234:235], v[130:131], v[234:235], v[134:135]
	v_pk_fma_f32 v[94:95], v[216:217], s[36:37], v[94:95] op_sel_hi:[1,0,1]
	v_pk_fma_f32 v[92:93], v[214:215], s[36:37], v[92:93] op_sel_hi:[1,0,1]
	v_pk_fma_f32 v[90:91], v[234:235], s[36:37], v[90:91] op_sel_hi:[1,0,1]
	v_pk_fma_f32 v[88:89], v[218:219], s[36:37], v[88:89] op_sel_hi:[1,0,1]
	v_cvt_pk_bf16_f32 v214, v92, v93
	v_cvt_pk_bf16_f32 v215, v94, v95
	v_cvt_pk_bf16_f32 v216, v88, v89
	v_cvt_pk_bf16_f32 v217, v90, v91
	global_store_dwordx4 v[204:205], v[214:217], off
	s_nop 0
	s_waitcnt vmcnt(1)
	v_and_b32_e32 v219, 0xffff0000, v242
	v_pk_mul_f32 v[216:217], v[212:213], s[34:35] op_sel:[1,0] op_sel_hi:[0,0]
	v_fma_f32 v212, -v217, v217, v216
	v_max_f32_e32 v212, 0, v212
	v_add_f32_e32 v212, 0x3727c5ac, v212
	v_mul_f32_e32 v213, 0x4f800000, v212
	v_cmp_gt_f32_e32 vcc, s78, v212
	v_lshlrev_b32_e32 v233, 16, v243
	v_sub_f32_e32 v219, v219, v217
	v_cndmask_b32_e32 v212, v212, v213, vcc
	v_sqrt_f32_e32 v213, v212
	s_nop 0
	v_add_u32_e32 v214, -1, v213
	v_add_u32_e32 v215, 1, v213
	v_fma_f32 v216, -v214, v213, v212
	v_fma_f32 v218, -v215, v213, v212
	v_cmp_ge_f32_e64 s[0:1], 0, v216
	s_nop 1
	v_cndmask_b32_e64 v213, v213, v214, s[0:1]
	v_cmp_lt_f32_e64 s[0:1], 0, v218
	s_nop 1
	v_cndmask_b32_e64 v213, v213, v215, s[0:1]
	v_mul_f32_e32 v214, 0x37800000, v213
	v_cndmask_b32_e32 v213, v213, v214, vcc
	v_cmp_class_f32_e32 vcc, v212, v232
	v_lshl_add_u64 v[214:215], v[184:185], 0, v[178:179]
	global_load_dwordx4 v[244:247], v[214:215], off
	s_nop 0
	v_cndmask_b32_e32 v212, v213, v212, vcc
	v_div_scale_f32 v213, s[0:1], v212, v212, 1.0
	v_rcp_f32_e32 v216, v213
	v_div_scale_f32 v184, vcc, 1.0, v212, 1.0
	v_fma_f32 v185, -v213, v216, 1.0
	v_fmac_f32_e32 v216, v185, v216
	v_mul_f32_e32 v185, v184, v216
	v_fma_f32 v218, -v213, v185, v184
	v_fmac_f32_e32 v185, v218, v216
	v_fma_f32 v184, -v213, v185, v184
	v_div_fmas_f32 v184, v184, v216, v185
	v_div_fixup_f32 v216, v184, v212, 1.0
	v_lshlrev_b32_e32 v184, 16, v240
	v_and_b32_e32 v185, 0xffff0000, v240
	v_lshlrev_b32_e32 v212, 16, v241
	v_and_b32_e32 v213, 0xffff0000, v241
	v_lshlrev_b32_e32 v218, 16, v242
	v_and_b32_e32 v234, 0xffff0000, v243
	v_sub_f32_e32 v185, v185, v217
	v_sub_f32_e32 v184, v184, v217
	v_sub_f32_e32 v213, v213, v217
	v_sub_f32_e32 v212, v212, v217
	v_sub_f32_e32 v218, v218, v217
	v_sub_f32_e32 v235, v234, v217
	v_sub_f32_e32 v234, v233, v217
	v_pk_mul_f32 v[212:213], v[216:217], v[212:213] op_sel_hi:[0,1]
	v_pk_mul_f32 v[184:185], v[216:217], v[184:185] op_sel_hi:[0,1]
	v_pk_mul_f32 v[234:235], v[216:217], v[234:235] op_sel_hi:[0,1]
	v_pk_mul_f32 v[218:219], v[216:217], v[218:219] op_sel_hi:[0,1]
	v_pk_fma_f32 v[184:185], v[136:137], v[184:185], v[140:141]
	v_pk_fma_f32 v[212:213], v[138:139], v[212:213], v[142:143]
	v_pk_fma_f32 v[218:219], v[128:129], v[218:219], v[132:133]
	v_pk_fma_f32 v[234:235], v[130:131], v[234:235], v[134:135]
	v_pk_fma_f32 v[86:87], v[212:213], s[36:37], v[86:87] op_sel_hi:[1,0,1]
	v_pk_fma_f32 v[84:85], v[184:185], s[36:37], v[84:85] op_sel_hi:[1,0,1]
	v_pk_fma_f32 v[82:83], v[234:235], s[36:37], v[82:83] op_sel_hi:[1,0,1]
	v_pk_fma_f32 v[80:81], v[218:219], s[36:37], v[80:81] op_sel_hi:[1,0,1]
	v_cvt_pk_bf16_f32 v234, v84, v85
	v_cvt_pk_bf16_f32 v235, v86, v87
	v_cvt_pk_bf16_f32 v236, v80, v81
	v_cvt_pk_bf16_f32 v237, v82, v83
	global_store_dwordx4 v[208:209], v[234:237], off
	s_nop 0
	v_pk_mul_f32 v[218:219], v[182:183], s[34:35] op_sel:[1,0] op_sel_hi:[0,0]
	v_fma_f32 v182, -v219, v219, v218
	v_max_f32_e32 v182, 0, v182
	v_add_f32_e32 v182, 0x3727c5ac, v182
	v_mul_f32_e32 v183, 0x4f800000, v182
	v_cmp_gt_f32_e32 vcc, s78, v182
	s_nop 1
	v_cndmask_b32_e32 v182, v182, v183, vcc
	v_sqrt_f32_e32 v183, v182
	s_nop 0
	v_add_u32_e32 v184, -1, v183
	v_add_u32_e32 v185, 1, v183
	v_fma_f32 v212, -v184, v183, v182
	v_fma_f32 v213, -v185, v183, v182
	v_cmp_ge_f32_e64 s[0:1], 0, v212
	s_nop 1
	v_cndmask_b32_e64 v183, v183, v184, s[0:1]
	v_cmp_lt_f32_e64 s[0:1], 0, v213
	v_lshl_add_u64 v[212:213], v[180:181], 0, v[178:179]
	global_load_dwordx4 v[240:243], v[212:213], off
	s_waitcnt vmcnt(2)
	v_and_b32_e32 v181, 0xffff0000, v245
	v_cndmask_b32_e64 v183, v183, v185, s[0:1]
	v_mul_f32_e32 v184, 0x37800000, v183
	v_cndmask_b32_e32 v183, v183, v184, vcc
	v_cmp_class_f32_e32 vcc, v182, v232
	v_and_b32_e32 v185, 0xffff0000, v247
	v_sub_f32_e32 v181, v181, v219
	v_cndmask_b32_e32 v182, v183, v182, vcc
	v_div_scale_f32 v183, s[0:1], v182, v182, 1.0
	v_rcp_f32_e32 v184, v183
	v_div_scale_f32 v178, vcc, 1.0, v182, 1.0
	v_sub_f32_e32 v185, v185, v219
	v_fma_f32 v179, -v183, v184, 1.0
	v_fmac_f32_e32 v184, v179, v184
	v_mul_f32_e32 v179, v178, v184
	v_fma_f32 v180, -v183, v179, v178
	v_fmac_f32_e32 v179, v180, v184
	v_fma_f32 v178, -v183, v179, v178
	v_div_fmas_f32 v178, v178, v184, v179
	v_div_fixup_f32 v218, v178, v182, 1.0
	v_lshlrev_b32_e32 v178, 16, v244
	v_and_b32_e32 v179, 0xffff0000, v244
	v_lshlrev_b32_e32 v180, 16, v245
	v_lshlrev_b32_e32 v182, 16, v246
	v_and_b32_e32 v183, 0xffff0000, v246
	v_lshlrev_b32_e32 v184, 16, v247
	v_sub_f32_e32 v179, v179, v219
	v_sub_f32_e32 v178, v178, v219
	v_sub_f32_e32 v180, v180, v219
	v_sub_f32_e32 v183, v183, v219
	v_sub_f32_e32 v182, v182, v219
	v_sub_f32_e32 v184, v184, v219
	v_pk_mul_f32 v[180:181], v[218:219], v[180:181] op_sel_hi:[0,1]
	v_pk_mul_f32 v[178:179], v[218:219], v[178:179] op_sel_hi:[0,1]
	v_pk_mul_f32 v[184:185], v[218:219], v[184:185] op_sel_hi:[0,1]
	v_pk_mul_f32 v[182:183], v[218:219], v[182:183] op_sel_hi:[0,1]
	v_pk_fma_f32 v[178:179], v[136:137], v[178:179], v[140:141]
	v_pk_fma_f32 v[180:181], v[138:139], v[180:181], v[142:143]
	v_pk_fma_f32 v[234:235], v[128:129], v[182:183], v[132:133]
	v_pk_fma_f32 v[236:237], v[130:131], v[184:185], v[134:135]
	v_pk_fma_f32 v[182:183], v[180:181], s[36:37], v[78:79] op_sel_hi:[1,0,1]
	v_pk_fma_f32 v[184:185], v[178:179], s[36:37], v[76:77] op_sel_hi:[1,0,1]
	v_pk_fma_f32 v[178:179], v[236:237], s[36:37], v[74:75] op_sel_hi:[1,0,1]
	v_pk_fma_f32 v[180:181], v[234:235], s[36:37], v[72:73] op_sel_hi:[1,0,1]
	v_cvt_pk_bf16_f32 v72, v184, v185
	v_cvt_pk_bf16_f32 v73, v182, v183
	v_cvt_pk_bf16_f32 v74, v180, v181
	v_cvt_pk_bf16_f32 v75, v178, v179
	global_store_dwordx4 v[214:215], v[72:75], off
	s_nop 0
	v_fma_f32 v76, -v203, v203, v202
	v_max_f32_e32 v76, 0, v76
	v_add_f32_e32 v76, 0x3727c5ac, v76
	v_mul_f32_e32 v77, 0x4f800000, v76
	v_cmp_gt_f32_e32 vcc, s78, v76
	s_waitcnt vmcnt(1)
	v_lshlrev_b32_e32 v234, 16, v243
	v_cndmask_b32_e32 v76, v76, v77, vcc
	v_sqrt_f32_e32 v77, v76
	v_and_b32_e32 v235, 0xffff0000, v243
	v_add_u32_e32 v78, -1, v77
	v_add_u32_e32 v79, 1, v77
	v_fma_f32 v202, -v78, v77, v76
	v_fma_f32 v233, -v79, v77, v76
	v_cmp_ge_f32_e64 s[0:1], 0, v202
	s_nop 1
	v_cndmask_b32_e64 v77, v77, v78, s[0:1]
	v_cmp_lt_f32_e64 s[0:1], 0, v233
	s_nop 1
	v_cndmask_b32_e64 v77, v77, v79, s[0:1]
	v_mul_f32_e32 v78, 0x37800000, v77
	v_cndmask_b32_e32 v77, v77, v78, vcc
	v_cmp_class_f32_e32 vcc, v76, v232
	s_nop 1
	v_cndmask_b32_e32 v76, v77, v76, vcc
	v_div_scale_f32 v77, s[0:1], v76, v76, 1.0
	v_rcp_f32_e32 v78, v77
	v_div_scale_f32 v79, vcc, 1.0, v76, 1.0
	v_fma_f32 v202, -v77, v78, 1.0
	v_fmac_f32_e32 v78, v202, v78
	v_mul_f32_e32 v202, v79, v78
	v_fma_f32 v233, -v77, v202, v79
	v_fmac_f32_e32 v202, v233, v78
	v_fma_f32 v77, -v77, v202, v79
	v_div_fmas_f32 v77, v77, v78, v202
	v_div_fixup_f32 v202, v77, v76, 1.0
	v_lshlrev_b32_e32 v76, 16, v240
	v_and_b32_e32 v72, 0xffff0000, v240
	v_lshlrev_b32_e32 v77, 16, v241
	v_and_b32_e32 v78, 0xffff0000, v241
	v_lshlrev_b32_e32 v79, 16, v242
	v_and_b32_e32 v233, 0xffff0000, v242
	v_sub_f32_e32 v73, v72, v203
	v_sub_f32_e32 v72, v76, v203
	v_sub_f32_e32 v75, v78, v203
	v_sub_f32_e32 v74, v77, v203
	v_sub_f32_e32 v77, v233, v203
	v_sub_f32_e32 v76, v79, v203
	v_sub_f32_e32 v79, v235, v203
	v_sub_f32_e32 v78, v234, v203
	v_pk_mul_f32 v[74:75], v[202:203], v[74:75] op_sel_hi:[0,1]
	v_pk_mul_f32 v[72:73], v[202:203], v[72:73] op_sel_hi:[0,1]
	v_pk_mul_f32 v[78:79], v[202:203], v[78:79] op_sel_hi:[0,1]
	v_pk_mul_f32 v[76:77], v[202:203], v[76:77] op_sel_hi:[0,1]
	v_pk_fma_f32 v[72:73], v[136:137], v[72:73], v[140:141]
	v_pk_fma_f32 v[74:75], v[138:139], v[74:75], v[142:143]
	v_pk_fma_f32 v[76:77], v[128:129], v[76:77], v[132:133]
	v_pk_fma_f32 v[78:79], v[130:131], v[78:79], v[134:135]
	v_pk_fma_f32 v[130:131], v[74:75], s[36:37], v[70:71] op_sel_hi:[1,0,1]
	v_pk_fma_f32 v[134:135], v[72:73], s[36:37], v[68:69] op_sel_hi:[1,0,1]
	v_pk_fma_f32 v[128:129], v[78:79], s[36:37], v[66:67] op_sel_hi:[1,0,1]
	v_pk_fma_f32 v[132:133], v[76:77], s[36:37], v[64:65] op_sel_hi:[1,0,1]
	v_cvt_pk_bf16_f32 v64, v134, v135
	v_cvt_pk_bf16_f32 v65, v130, v131
	v_cvt_pk_bf16_f32 v66, v132, v133
	v_cvt_pk_bf16_f32 v67, v128, v129
	global_store_dwordx4 v[212:213], v[64:67], off
	global_load_dwordx4 v[136:139], v[176:177], off offset:256
	global_load_dwordx4 v[68:71], v[190:191], off offset:512
	global_load_dwordx4 v[72:75], v[188:189], off offset:512
	global_load_dwordx4 v[64:67], v[188:189], off offset:528
	global_load_dwordx4 v[76:79], v[190:191], off offset:528
	s_waitcnt vmcnt(0)
	v_lshlrev_b32_e32 v140, 16, v136
	v_and_b32_e32 v136, 0xffff0000, v136
	v_lshlrev_b32_e32 v141, 16, v137
	v_and_b32_e32 v142, 0xffff0000, v137
	v_lshlrev_b32_e32 v143, 16, v138
	v_and_b32_e32 v188, 0xffff0000, v138
	v_lshlrev_b32_e32 v189, 16, v139
	v_and_b32_e32 v190, 0xffff0000, v139
	v_sub_f32_e32 v137, v136, v187
	v_sub_f32_e32 v136, v140, v187
	v_sub_f32_e32 v139, v142, v187
	v_sub_f32_e32 v138, v141, v187
	v_sub_f32_e32 v141, v188, v187
	v_sub_f32_e32 v140, v143, v187
	v_sub_f32_e32 v143, v190, v187
	v_sub_f32_e32 v142, v189, v187
	v_pk_mul_f32 v[138:139], v[186:187], v[138:139] op_sel_hi:[0,1]
	v_pk_mul_f32 v[136:137], v[186:187], v[136:137] op_sel_hi:[0,1]
	v_pk_mul_f32 v[142:143], v[186:187], v[142:143] op_sel_hi:[0,1]
	v_pk_mul_f32 v[140:141], v[186:187], v[140:141] op_sel_hi:[0,1]
	v_pk_fma_f32 v[136:137], v[72:73], v[136:137], v[68:69]
	v_pk_fma_f32 v[138:139], v[74:75], v[138:139], v[70:71]
	v_pk_fma_f32 v[140:141], v[64:65], v[140:141], v[76:77]
	v_pk_fma_f32 v[142:143], v[66:67], v[142:143], v[78:79]
	v_pk_fma_f32 v[62:63], v[138:139], s[36:37], v[62:63] op_sel_hi:[1,0,1]
	v_pk_fma_f32 v[60:61], v[136:137], s[36:37], v[60:61] op_sel_hi:[1,0,1]
	v_pk_fma_f32 v[58:59], v[142:143], s[36:37], v[58:59] op_sel_hi:[1,0,1]
	v_pk_fma_f32 v[56:57], v[140:141], s[36:37], v[56:57] op_sel_hi:[1,0,1]
	v_cvt_pk_bf16_f32 v136, v60, v61
	v_cvt_pk_bf16_f32 v137, v62, v63
	v_cvt_pk_bf16_f32 v138, v56, v57
	v_cvt_pk_bf16_f32 v139, v58, v59
	global_store_dwordx4 v[176:177], v[136:139], off offset:256
	global_load_dwordx4 v[240:243], v[192:193], off offset:256
	global_load_dwordx4 v[244:247], v[194:195], off offset:256
	s_waitcnt vmcnt(1)
	v_lshlrev_b32_e32 v140, 16, v240
	v_and_b32_e32 v136, 0xffff0000, v240
	v_lshlrev_b32_e32 v141, 16, v241
	v_and_b32_e32 v142, 0xffff0000, v241
	v_lshlrev_b32_e32 v143, 16, v242
	v_and_b32_e32 v176, 0xffff0000, v242
	v_lshlrev_b32_e32 v177, 16, v243
	v_and_b32_e32 v186, 0xffff0000, v243
	v_sub_f32_e32 v137, v136, v197
	v_sub_f32_e32 v136, v140, v197
	v_sub_f32_e32 v139, v142, v197
	v_sub_f32_e32 v138, v141, v197
	v_sub_f32_e32 v141, v176, v197
	v_sub_f32_e32 v140, v143, v197
	v_sub_f32_e32 v143, v186, v197
	v_sub_f32_e32 v142, v177, v197
	v_pk_mul_f32 v[138:139], v[196:197], v[138:139] op_sel_hi:[0,1]
	v_pk_mul_f32 v[136:137], v[196:197], v[136:137] op_sel_hi:[0,1]
	v_pk_mul_f32 v[142:143], v[196:197], v[142:143] op_sel_hi:[0,1]
	v_pk_mul_f32 v[140:141], v[196:197], v[140:141] op_sel_hi:[0,1]
	v_pk_fma_f32 v[136:137], v[72:73], v[136:137], v[68:69]
	v_pk_fma_f32 v[138:139], v[74:75], v[138:139], v[70:71]
	v_pk_fma_f32 v[140:141], v[64:65], v[140:141], v[76:77]
	v_pk_fma_f32 v[142:143], v[66:67], v[142:143], v[78:79]
	v_pk_fma_f32 v[54:55], v[138:139], s[36:37], v[54:55] op_sel_hi:[1,0,1]
	v_pk_fma_f32 v[52:53], v[136:137], s[36:37], v[52:53] op_sel_hi:[1,0,1]
	v_pk_fma_f32 v[50:51], v[142:143], s[36:37], v[50:51] op_sel_hi:[1,0,1]
	v_pk_fma_f32 v[48:49], v[140:141], s[36:37], v[48:49] op_sel_hi:[1,0,1]
	v_cvt_pk_bf16_f32 v136, v52, v53
	v_cvt_pk_bf16_f32 v137, v54, v55
	v_cvt_pk_bf16_f32 v138, v48, v49
	v_cvt_pk_bf16_f32 v139, v50, v51
	global_store_dwordx4 v[192:193], v[136:139], off offset:256
	s_nop 0
	global_load_dwordx4 v[240:243], v[198:199], off offset:256
	s_waitcnt vmcnt(2)
	v_lshlrev_b32_e32 v140, 16, v244
	v_and_b32_e32 v136, 0xffff0000, v244
	v_lshlrev_b32_e32 v141, 16, v245
	v_and_b32_e32 v142, 0xffff0000, v245
	v_lshlrev_b32_e32 v143, 16, v246
	v_and_b32_e32 v176, 0xffff0000, v246
	v_lshlrev_b32_e32 v177, 16, v247
	v_and_b32_e32 v186, 0xffff0000, v247
	v_sub_f32_e32 v137, v136, v201
	v_sub_f32_e32 v136, v140, v201
	v_sub_f32_e32 v139, v142, v201
	v_sub_f32_e32 v138, v141, v201
	v_sub_f32_e32 v141, v176, v201
	v_sub_f32_e32 v140, v143, v201
	v_sub_f32_e32 v143, v186, v201
	v_sub_f32_e32 v142, v177, v201
	v_pk_mul_f32 v[138:139], v[200:201], v[138:139] op_sel_hi:[0,1]
	v_pk_mul_f32 v[136:137], v[200:201], v[136:137] op_sel_hi:[0,1]
	v_pk_mul_f32 v[142:143], v[200:201], v[142:143] op_sel_hi:[0,1]
	v_pk_mul_f32 v[140:141], v[200:201], v[140:141] op_sel_hi:[0,1]
	v_pk_fma_f32 v[136:137], v[72:73], v[136:137], v[68:69]
	v_pk_fma_f32 v[138:139], v[74:75], v[138:139], v[70:71]
	v_pk_fma_f32 v[140:141], v[64:65], v[140:141], v[76:77]
	v_pk_fma_f32 v[142:143], v[66:67], v[142:143], v[78:79]
	v_pk_fma_f32 v[46:47], v[138:139], s[36:37], v[46:47] op_sel_hi:[1,0,1]
	v_pk_fma_f32 v[44:45], v[136:137], s[36:37], v[44:45] op_sel_hi:[1,0,1]
	v_pk_fma_f32 v[42:43], v[142:143], s[36:37], v[42:43] op_sel_hi:[1,0,1]
	v_pk_fma_f32 v[40:41], v[140:141], s[36:37], v[40:41] op_sel_hi:[1,0,1]
	v_cvt_pk_bf16_f32 v136, v44, v45
	v_cvt_pk_bf16_f32 v137, v46, v47
	v_cvt_pk_bf16_f32 v138, v40, v41
	v_cvt_pk_bf16_f32 v139, v42, v43
	global_store_dwordx4 v[194:195], v[136:139], off offset:256
	s_nop 0
	global_load_dwordx4 v[244:247], v[204:205], off offset:256
	s_waitcnt vmcnt(2)
	v_lshlrev_b32_e32 v140, 16, v240
	v_and_b32_e32 v136, 0xffff0000, v240
	v_lshlrev_b32_e32 v141, 16, v241
	v_and_b32_e32 v142, 0xffff0000, v241
	v_lshlrev_b32_e32 v143, 16, v242
	v_and_b32_e32 v176, 0xffff0000, v242
	v_lshlrev_b32_e32 v177, 16, v243
	v_and_b32_e32 v186, 0xffff0000, v243
	v_sub_f32_e32 v137, v136, v207
	v_sub_f32_e32 v136, v140, v207
	v_sub_f32_e32 v139, v142, v207
	v_sub_f32_e32 v138, v141, v207
	v_sub_f32_e32 v141, v176, v207
	v_sub_f32_e32 v140, v143, v207
	v_sub_f32_e32 v143, v186, v207
	v_sub_f32_e32 v142, v177, v207
	v_pk_mul_f32 v[138:139], v[206:207], v[138:139] op_sel_hi:[0,1]
	v_pk_mul_f32 v[136:137], v[206:207], v[136:137] op_sel_hi:[0,1]
	v_pk_mul_f32 v[142:143], v[206:207], v[142:143] op_sel_hi:[0,1]
	v_pk_mul_f32 v[140:141], v[206:207], v[140:141] op_sel_hi:[0,1]
	v_pk_fma_f32 v[136:137], v[72:73], v[136:137], v[68:69]
	v_pk_fma_f32 v[138:139], v[74:75], v[138:139], v[70:71]
	v_pk_fma_f32 v[140:141], v[64:65], v[140:141], v[76:77]
	v_pk_fma_f32 v[142:143], v[66:67], v[142:143], v[78:79]
	v_pk_fma_f32 v[38:39], v[138:139], s[36:37], v[38:39] op_sel_hi:[1,0,1]
	v_pk_fma_f32 v[36:37], v[136:137], s[36:37], v[36:37] op_sel_hi:[1,0,1]
	v_pk_fma_f32 v[34:35], v[142:143], s[36:37], v[34:35] op_sel_hi:[1,0,1]
	v_pk_fma_f32 v[32:33], v[140:141], s[36:37], v[32:33] op_sel_hi:[1,0,1]
	v_cvt_pk_bf16_f32 v136, v36, v37
	v_cvt_pk_bf16_f32 v137, v38, v39
	v_cvt_pk_bf16_f32 v138, v32, v33
	v_cvt_pk_bf16_f32 v139, v34, v35
	global_store_dwordx4 v[198:199], v[136:139], off offset:256
	s_nop 0
	global_load_dwordx4 v[240:243], v[208:209], off offset:256
	s_waitcnt vmcnt(2)
	v_lshlrev_b32_e32 v140, 16, v244
	v_and_b32_e32 v136, 0xffff0000, v244
	v_lshlrev_b32_e32 v141, 16, v245
	v_and_b32_e32 v142, 0xffff0000, v245
	v_lshlrev_b32_e32 v143, 16, v246
	v_and_b32_e32 v176, 0xffff0000, v246
	v_lshlrev_b32_e32 v177, 16, v247
	v_and_b32_e32 v186, 0xffff0000, v247
	v_sub_f32_e32 v137, v136, v211
	v_sub_f32_e32 v136, v140, v211
	v_sub_f32_e32 v139, v142, v211
	v_sub_f32_e32 v138, v141, v211
	v_sub_f32_e32 v141, v176, v211
	v_sub_f32_e32 v140, v143, v211
	v_sub_f32_e32 v143, v186, v211
	v_sub_f32_e32 v142, v177, v211
	v_pk_mul_f32 v[138:139], v[210:211], v[138:139] op_sel_hi:[0,1]
	v_pk_mul_f32 v[136:137], v[210:211], v[136:137] op_sel_hi:[0,1]
	v_pk_mul_f32 v[142:143], v[210:211], v[142:143] op_sel_hi:[0,1]
	v_pk_mul_f32 v[140:141], v[210:211], v[140:141] op_sel_hi:[0,1]
	v_pk_fma_f32 v[136:137], v[72:73], v[136:137], v[68:69]
	v_pk_fma_f32 v[138:139], v[74:75], v[138:139], v[70:71]
	v_pk_fma_f32 v[140:141], v[64:65], v[140:141], v[76:77]
	v_pk_fma_f32 v[142:143], v[66:67], v[142:143], v[78:79]
	v_pk_fma_f32 v[30:31], v[138:139], s[36:37], v[30:31] op_sel_hi:[1,0,1]
	v_pk_fma_f32 v[28:29], v[136:137], s[36:37], v[28:29] op_sel_hi:[1,0,1]
	v_pk_fma_f32 v[26:27], v[142:143], s[36:37], v[26:27] op_sel_hi:[1,0,1]
	v_pk_fma_f32 v[24:25], v[140:141], s[36:37], v[24:25] op_sel_hi:[1,0,1]
	v_cvt_pk_bf16_f32 v136, v28, v29
	v_cvt_pk_bf16_f32 v137, v30, v31
	v_cvt_pk_bf16_f32 v138, v24, v25
	v_cvt_pk_bf16_f32 v139, v26, v27
	global_store_dwordx4 v[204:205], v[136:139], off offset:256
	s_nop 0
	global_load_dwordx4 v[244:247], v[214:215], off offset:256
	s_waitcnt vmcnt(2)
	v_lshlrev_b32_e32 v140, 16, v240
	v_and_b32_e32 v136, 0xffff0000, v240
	v_lshlrev_b32_e32 v141, 16, v241
	v_and_b32_e32 v142, 0xffff0000, v241
	v_lshlrev_b32_e32 v143, 16, v242
	v_and_b32_e32 v176, 0xffff0000, v242
	v_lshlrev_b32_e32 v177, 16, v243
	v_and_b32_e32 v186, 0xffff0000, v243
	v_sub_f32_e32 v137, v136, v217
	v_sub_f32_e32 v136, v140, v217
	v_sub_f32_e32 v139, v142, v217
	v_sub_f32_e32 v138, v141, v217
	v_sub_f32_e32 v141, v176, v217
	v_sub_f32_e32 v140, v143, v217
	v_sub_f32_e32 v143, v186, v217
	v_sub_f32_e32 v142, v177, v217
	v_pk_mul_f32 v[138:139], v[216:217], v[138:139] op_sel_hi:[0,1]
	v_pk_mul_f32 v[136:137], v[216:217], v[136:137] op_sel_hi:[0,1]
	v_pk_mul_f32 v[142:143], v[216:217], v[142:143] op_sel_hi:[0,1]
	v_pk_mul_f32 v[140:141], v[216:217], v[140:141] op_sel_hi:[0,1]
	v_pk_fma_f32 v[136:137], v[72:73], v[136:137], v[68:69]
	v_pk_fma_f32 v[138:139], v[74:75], v[138:139], v[70:71]
	v_pk_fma_f32 v[140:141], v[64:65], v[140:141], v[76:77]
	v_pk_fma_f32 v[142:143], v[66:67], v[142:143], v[78:79]
	v_pk_fma_f32 v[22:23], v[138:139], s[36:37], v[22:23] op_sel_hi:[1,0,1]
	v_pk_fma_f32 v[20:21], v[136:137], s[36:37], v[20:21] op_sel_hi:[1,0,1]
	v_pk_fma_f32 v[18:19], v[142:143], s[36:37], v[18:19] op_sel_hi:[1,0,1]
	v_pk_fma_f32 v[16:17], v[140:141], s[36:37], v[16:17] op_sel_hi:[1,0,1]
	v_cvt_pk_bf16_f32 v136, v20, v21
	v_cvt_pk_bf16_f32 v137, v22, v23
	v_cvt_pk_bf16_f32 v138, v16, v17
	v_cvt_pk_bf16_f32 v139, v18, v19
	global_store_dwordx4 v[208:209], v[136:139], off offset:256
	s_nop 0
	global_load_dwordx4 v[240:243], v[212:213], off offset:256
	s_waitcnt vmcnt(2)
	v_lshlrev_b32_e32 v140, 16, v244
	v_and_b32_e32 v136, 0xffff0000, v244
	v_lshlrev_b32_e32 v141, 16, v245
	v_and_b32_e32 v142, 0xffff0000, v245
	v_lshlrev_b32_e32 v143, 16, v246
	v_and_b32_e32 v176, 0xffff0000, v246
	v_lshlrev_b32_e32 v177, 16, v247
	v_and_b32_e32 v186, 0xffff0000, v247
	v_sub_f32_e32 v137, v136, v219
	v_sub_f32_e32 v136, v140, v219
	v_sub_f32_e32 v139, v142, v219
	v_sub_f32_e32 v138, v141, v219
	v_sub_f32_e32 v141, v176, v219
	v_sub_f32_e32 v140, v143, v219
	v_sub_f32_e32 v143, v186, v219
	v_sub_f32_e32 v142, v177, v219
	v_pk_mul_f32 v[138:139], v[218:219], v[138:139] op_sel_hi:[0,1]
	v_pk_mul_f32 v[136:137], v[218:219], v[136:137] op_sel_hi:[0,1]
	v_pk_mul_f32 v[142:143], v[218:219], v[142:143] op_sel_hi:[0,1]
	v_pk_mul_f32 v[140:141], v[218:219], v[140:141] op_sel_hi:[0,1]
	v_pk_fma_f32 v[136:137], v[72:73], v[136:137], v[68:69]
	v_pk_fma_f32 v[138:139], v[74:75], v[138:139], v[70:71]
	v_pk_fma_f32 v[140:141], v[64:65], v[140:141], v[76:77]
	v_pk_fma_f32 v[142:143], v[66:67], v[142:143], v[78:79]
	v_pk_fma_f32 v[14:15], v[138:139], s[36:37], v[14:15] op_sel_hi:[1,0,1]
	v_pk_fma_f32 v[12:13], v[136:137], s[36:37], v[12:13] op_sel_hi:[1,0,1]
	v_pk_fma_f32 v[10:11], v[142:143], s[36:37], v[10:11] op_sel_hi:[1,0,1]
	v_pk_fma_f32 v[8:9], v[140:141], s[36:37], v[8:9] op_sel_hi:[1,0,1]
	v_cvt_pk_bf16_f32 v136, v12, v13
	v_cvt_pk_bf16_f32 v137, v14, v15
	v_cvt_pk_bf16_f32 v138, v8, v9
	v_cvt_pk_bf16_f32 v139, v10, v11
	global_store_dwordx4 v[214:215], v[136:139], off offset:256
	s_nop 0
	v_add_f32_e32 v140, v124, v125
	v_add_f32_e32 v141, v126, v127
	v_add_f32_e32 v142, v120, v121
	v_add_f32_e32 v143, v122, v123
	v_mul_f32_e32 v125, v125, v125
	v_mul_f32_e32 v127, v127, v127
	v_mul_f32_e32 v121, v121, v121
	v_mul_f32_e32 v123, v123, v123
	v_fmac_f32_e32 v125, v124, v124
	v_fmac_f32_e32 v127, v126, v126
	v_fmac_f32_e32 v121, v120, v120
	v_fmac_f32_e32 v123, v122, v122
	v_add_f32_e32 v122, v125, v127
	v_add_f32_e32 v121, v121, v123
	v_add_f32_e32 v121, v122, v121
	v_add_f32_e32 v122, v60, v61
	v_add_f32_e32 v123, v62, v63
	v_add_f32_e32 v124, v56, v57
	v_add_f32_e32 v125, v58, v59
	v_mul_f32_e32 v61, v61, v61
	v_mul_f32_e32 v63, v63, v63
	v_mul_f32_e32 v57, v57, v57
	v_mul_f32_e32 v59, v59, v59
	v_add_f32_e32 v140, v140, v141
	v_add_f32_e32 v141, v142, v143
	v_fmac_f32_e32 v61, v60, v60
	v_fmac_f32_e32 v63, v62, v62
	v_fmac_f32_e32 v57, v56, v56
	v_fmac_f32_e32 v59, v58, v58
	v_add_f32_e32 v120, v140, v141
	v_add_f32_e32 v122, v122, v123
	v_add_f32_e32 v123, v124, v125
	v_add_f32_e32 v58, v61, v63
	v_add_f32_e32 v57, v57, v59
	v_add_f32_e32 v120, 0, v120
	v_add_f32_e32 v56, v122, v123
	v_add_f32_e32 v57, v58, v57
	v_add_f32_e32 v56, v120, v56
	v_add_f32_e32 v59, v121, v57
	ds_bpermute_b32 v58, v226, v56
	ds_bpermute_b32 v60, v226, v59
	s_waitcnt lgkmcnt(0)
	v_add_f32_e32 v56, v56, v58
	v_add_f32_e32 v58, v59, v60
	ds_bpermute_b32 v57, v227, v56
	s_waitcnt vmcnt(1)
	v_lshlrev_b32_e32 v59, 16, v240
	v_and_b32_e32 v60, 0xffff0000, v240
	v_lshlrev_b32_e32 v62, 16, v241
	v_and_b32_e32 v63, 0xffff0000, v241
	v_lshlrev_b32_e32 v120, 16, v242
	v_and_b32_e32 v121, 0xffff0000, v242
	v_lshlrev_b32_e32 v122, 16, v243
	v_and_b32_e32 v123, 0xffff0000, v243
	v_sub_f32_e32 v61, v60, v203
	v_sub_f32_e32 v60, v59, v203
	v_sub_f32_e32 v63, v63, v203
	v_sub_f32_e32 v62, v62, v203
	v_sub_f32_e32 v121, v121, v203
	v_sub_f32_e32 v120, v120, v203
	v_sub_f32_e32 v123, v123, v203
	v_sub_f32_e32 v122, v122, v203
	v_pk_mul_f32 v[62:63], v[202:203], v[62:63] op_sel_hi:[0,1]
	v_pk_mul_f32 v[60:61], v[202:203], v[60:61] op_sel_hi:[0,1]
	v_pk_mul_f32 v[122:123], v[202:203], v[122:123] op_sel_hi:[0,1]
	v_pk_mul_f32 v[120:121], v[202:203], v[120:121] op_sel_hi:[0,1]
	v_pk_fma_f32 v[60:61], v[72:73], v[60:61], v[68:69]
	v_pk_fma_f32 v[62:63], v[74:75], v[62:63], v[70:71]
	v_pk_fma_f32 v[64:65], v[64:65], v[120:121], v[76:77]
	v_pk_fma_f32 v[66:67], v[66:67], v[122:123], v[78:79]
	v_pk_fma_f32 v[6:7], v[62:63], s[36:37], v[6:7] op_sel_hi:[1,0,1]
	v_pk_fma_f32 v[4:5], v[60:61], s[36:37], v[4:5] op_sel_hi:[1,0,1]
	v_pk_fma_f32 v[2:3], v[66:67], s[36:37], v[2:3] op_sel_hi:[1,0,1]
	v_pk_fma_f32 v[0:1], v[64:65], s[36:37], v[0:1] op_sel_hi:[1,0,1]
	v_cvt_pk_bf16_f32 v60, v4, v5
	v_cvt_pk_bf16_f32 v61, v6, v7
	v_cvt_pk_bf16_f32 v62, v0, v1
	v_cvt_pk_bf16_f32 v63, v2, v3
	ds_bpermute_b32 v59, v227, v58
	global_store_dwordx4 v[212:213], v[60:63], off offset:256
	s_and_saveexec_b64 s[0:1], s[6:7]
	s_cbranch_execz .LBB0_860
	s_waitcnt lgkmcnt(0)
	v_add_f32_e32 v58, v58, v59
	v_add_f32_e32 v59, v56, v57
	v_lshl_add_u64 v[56:57], s[14:15], 0, v[164:165]
	global_atomic_add_f32 v[56:57], v59, off
	global_atomic_add_f32 v[56:57], v58, off offset:4

.LBB0_1099:
	v_lshl_add_u32 v148, s91, 8, v154
	v_ashrrev_i32_e32 v149, 31, v148
	v_lshl_add_u64 v[146:147], v[148:149], 3, s[20:21]
	global_load_dword v136, v[146:147], off offset:4
	global_load_dword v238, v[146:147], off offset:132
	global_load_dword v239, v[146:147], off offset:260
	global_load_dword v240, v[146:147], off offset:388
	global_load_dword v241, v[146:147], off offset:1028
	global_load_dword v242, v[146:147], off offset:1156
	global_load_dword v243, v[146:147], off offset:1284
	global_load_dword v244, v[146:147], off offset:1412
	v_lshl_or_b32 v146, s90, 8, v156
	v_lshlrev_b32_e32 v147, 5, v148
	v_mul_hi_i32 v150, v146, s81
	v_and_b32_e32 v149, 0xf9e0, v147
	v_lshrrev_b32_e32 v147, 31, v150
	v_lshrrev_b32_e32 v150, 5, v150
	v_add_u32_e32 v147, v150, v147
	v_mul_lo_u32 v147, v147, s59
	v_sub_u32_e32 v147, v146, v147
	v_cmp_lt_i32_e64 s[8:9], s86, v147
	v_add_u32_e32 v147, 0xffffff80, v147
	s_waitcnt vmcnt(0)
	v_fmamk_f32 v136, v136, 0x3b000000, v160
	v_mul_f32_e32 v150, 0x4f800000, v136
	v_cmp_gt_f32_e32 vcc, s84, v136
	s_nop 1
	v_cndmask_b32_e32 v136, v136, v150, vcc
	v_sqrt_f32_e32 v150, v136
	s_nop 0
	v_add_u32_e32 v151, -1, v150
	v_add_u32_e32 v152, 1, v150
	v_fma_f32 v153, -v151, v150, v136
	v_fma_f32 v163, -v152, v150, v136
	v_cmp_ge_f32_e64 s[0:1], 0, v153
	s_nop 1
	v_cndmask_b32_e64 v150, v150, v151, s[0:1]
	v_cmp_lt_f32_e64 s[0:1], 0, v163
	s_nop 1
	v_cndmask_b32_e64 v150, v150, v152, s[0:1]
	v_mul_f32_e32 v151, 0x37800000, v150
	v_cndmask_b32_e32 v150, v150, v151, vcc
	v_cmp_class_f32_e32 vcc, v136, v161
	s_nop 1
	v_cndmask_b32_e32 v136, v150, v136, vcc
	v_div_scale_f32 v150, s[0:1], v136, v136, s85
	v_rcp_f32_e32 v151, v150
	v_div_scale_f32 v152, vcc, s85, v136, s85
	v_fma_f32 v153, -v150, v151, 1.0
	v_fmac_f32_e32 v151, v153, v151
	v_mul_f32_e32 v153, v152, v151
	v_fma_f32 v163, -v150, v153, v152
	v_fmac_f32_e32 v153, v163, v151
	v_fma_f32 v150, -v150, v153, v152
	v_div_fmas_f32 v150, v150, v151, v153
	v_div_fixup_f32 v150, v150, v136, s85
	v_pk_mul_f32 v[152:153], v[122:123], v[150:151] op_sel_hi:[1,0]
	v_pk_mul_f32 v[122:123], v[120:121], v[150:151] op_sel_hi:[1,0]
	v_pk_mul_f32 v[126:127], v[126:127], v[150:151] op_sel_hi:[1,0]
	v_pk_mul_f32 v[120:121], v[124:125], v[150:151] op_sel_hi:[1,0]
	v_lshrrev_b32_e32 v124, 1, v147
	s_and_saveexec_b64 s[0:1], s[8:9]
	s_cbranch_execz .LBB0_1101
	v_add_u32_e32 v136, v124, v149
	v_lshl_add_u64 v[168:169], v[136:137], 3, s[74:75]
	global_load_dwordx4 v[164:167], v[168:169], off
	s_nop 0
	global_load_dwordx4 v[168:171], v[168:169], off offset:16
	s_waitcnt vmcnt(0)
	v_pk_mul_f32 v[174:175], v[122:123], v[164:165] op_sel:[1,1] op_sel_hi:[0,1]
	v_mul_f32_e32 v136, v153, v167
	v_mul_f32_e32 v176, v152, v167
	v_pk_mul_f32 v[180:181], v[120:121], v[168:169] op_sel:[1,1] op_sel_hi:[0,1]
	v_mul_f32_e32 v182, v127, v171
	v_mul_f32_e32 v184, v126, v171
	v_pk_mul_f32 v[172:173], v[122:123], v[164:165]
	v_pk_mul_f32 v[178:179], v[120:121], v[168:169]
	v_pk_fma_f32 v[122:123], v[122:123], v[164:165], v[174:175] op_sel_hi:[1,0,1]
	v_pk_fma_f32 v[164:165], v[152:153], v[166:167], v[136:137] op_sel_hi:[1,1,0] neg_lo:[0,0,1] neg_hi:[0,0,1]
	v_pk_fma_f32 v[166:167], v[152:153], v[166:167], v[176:177] op_sel:[1,0,0] op_sel_hi:[0,1,0]
	v_pk_fma_f32 v[120:121], v[120:121], v[168:169], v[180:181] op_sel_hi:[1,0,1]
	v_pk_fma_f32 v[168:169], v[126:127], v[170:171], v[182:183] op_sel_hi:[1,1,0] neg_lo:[0,0,1] neg_hi:[0,0,1]
	v_pk_fma_f32 v[170:171], v[126:127], v[170:171], v[184:185] op_sel:[1,0,0] op_sel_hi:[0,1,0]
	v_sub_f32_e32 v122, v172, v174
	v_sub_f32_e32 v120, v178, v180
	v_mov_b32_e32 v152, v164
	v_mov_b32_e32 v153, v166
	v_mov_b32_e32 v126, v168
	v_mov_b32_e32 v127, v170

.LBB0_1103:
	s_or_b64 exec, exec, s[0:1]
	v_cvt_pk_bf16_f32 v116, v116, v117
	v_cvt_pk_bf16_f32 v117, v118, v119
	v_cvt_pk_bf16_f32 v118, v112, v113
	v_cvt_pk_bf16_f32 v119, v114, v115
	v_or_b32_e32 v112, 16, v148
	global_store_dwordx4 v[120:121], v[116:119], off offset:256
	v_ashrrev_i32_e32 v113, 31, v112
	v_lshl_add_u64 v[114:115], v[112:113], 3, s[20:21]
	s_nop 0
	v_lshlrev_b32_e32 v115, 5, v112
	s_nop 0
	v_fmamk_f32 v113, v238, 0x3b000000, v160
	v_mul_f32_e32 v114, 0x4f800000, v113
	v_cmp_gt_f32_e32 vcc, s84, v113
	s_nop 1
	v_cndmask_b32_e32 v113, v113, v114, vcc
	v_sqrt_f32_e32 v114, v113
	s_nop 0
	v_add_u32_e32 v116, -1, v114
	v_add_u32_e32 v117, 1, v114
	v_fma_f32 v118, -v116, v114, v113
	v_fma_f32 v119, -v117, v114, v113
	v_cmp_ge_f32_e64 s[0:1], 0, v118
	s_nop 1
	v_cndmask_b32_e64 v114, v114, v116, s[0:1]
	v_cmp_lt_f32_e64 s[0:1], 0, v119
	s_nop 1
	v_cndmask_b32_e64 v114, v114, v117, s[0:1]
	v_mul_f32_e32 v116, 0x37800000, v114
	v_cndmask_b32_e32 v114, v114, v116, vcc
	v_cmp_class_f32_e32 vcc, v113, v161
	s_nop 1
	v_cndmask_b32_e32 v114, v114, v113, vcc
	v_div_scale_f32 v116, s[0:1], v114, v114, s85
	v_rcp_f32_e32 v117, v116
	v_and_b32_e32 v113, 0xfbe0, v115
	v_div_scale_f32 v115, vcc, s85, v114, s85
	v_fma_f32 v118, -v116, v117, 1.0
	v_fmac_f32_e32 v117, v118, v117
	v_mul_f32_e32 v118, v115, v117
	v_fma_f32 v119, -v116, v118, v115
	v_fmac_f32_e32 v118, v119, v117
	v_fma_f32 v115, -v116, v118, v115
	v_div_fmas_f32 v115, v115, v117, v118
	v_div_fixup_f32 v114, v115, v114, s85
	v_pk_mul_f32 v[110:111], v[110:111], v[114:115] op_sel_hi:[1,0]
	v_pk_mul_f32 v[108:109], v[108:109], v[114:115] op_sel_hi:[1,0]
	v_pk_mul_f32 v[106:107], v[106:107], v[114:115] op_sel_hi:[1,0]
	v_pk_mul_f32 v[104:105], v[104:105], v[114:115] op_sel_hi:[1,0]
	s_and_saveexec_b64 s[0:1], s[8:9]
	s_cbranch_execz .LBB0_1105
	v_add_u32_e32 v136, v113, v124
	v_lshl_add_u64 v[120:121], v[136:137], 3, s[74:75]
	global_load_dwordx4 v[116:119], v[120:121], off
	global_load_dwordx4 v[150:153], v[120:121], off offset:16
	s_waitcnt vmcnt(0)
	v_pk_mul_f32 v[126:127], v[108:109], v[116:117] op_sel:[1,1] op_sel_hi:[0,1]
	v_mul_f32_e32 v136, v111, v119
	v_mul_f32_e32 v164, v110, v119
	v_pk_mul_f32 v[168:169], v[104:105], v[150:151] op_sel:[1,1] op_sel_hi:[0,1]
	v_mul_f32_e32 v170, v107, v153
	v_mul_f32_e32 v172, v106, v153
	v_pk_mul_f32 v[120:121], v[108:109], v[116:117]
	v_pk_mul_f32 v[166:167], v[104:105], v[150:151]
	v_pk_fma_f32 v[108:109], v[108:109], v[116:117], v[126:127] op_sel_hi:[1,0,1]
	v_pk_fma_f32 v[116:117], v[110:111], v[118:119], v[136:137] op_sel_hi:[1,1,0] neg_lo:[0,0,1] neg_hi:[0,0,1]
	v_pk_fma_f32 v[118:119], v[110:111], v[118:119], v[164:165] op_sel:[1,0,0] op_sel_hi:[0,1,0]
	v_pk_fma_f32 v[104:105], v[104:105], v[150:151], v[168:169] op_sel_hi:[1,0,1]
	v_pk_fma_f32 v[150:151], v[106:107], v[152:153], v[170:171] op_sel_hi:[1,1,0] neg_lo:[0,0,1] neg_hi:[0,0,1]
	v_pk_fma_f32 v[152:153], v[106:107], v[152:153], v[172:173] op_sel:[1,0,0] op_sel_hi:[0,1,0]
	v_sub_f32_e32 v108, v120, v126
	v_sub_f32_e32 v104, v166, v168
	v_mov_b32_e32 v110, v116
	v_mov_b32_e32 v111, v118
	v_mov_b32_e32 v106, v150
	v_mov_b32_e32 v107, v152

.LBB0_1107:
	s_or_b64 exec, exec, s[0:1]
	v_cvt_pk_bf16_f32 v100, v100, v101
	v_cvt_pk_bf16_f32 v101, v102, v103
	v_cvt_pk_bf16_f32 v102, v96, v97
	v_cvt_pk_bf16_f32 v103, v98, v99
	v_or_b32_e32 v96, 32, v148
	global_store_dwordx4 v[104:105], v[100:103], off offset:256
	v_ashrrev_i32_e32 v97, 31, v96
	v_lshl_add_u64 v[98:99], v[96:97], 3, s[20:21]
	s_nop 0
	v_lshlrev_b32_e32 v99, 5, v96
	s_nop 0
	v_fmamk_f32 v97, v239, 0x3b000000, v160
	v_mul_f32_e32 v98, 0x4f800000, v97
	v_cmp_gt_f32_e32 vcc, s84, v97
	s_nop 1
	v_cndmask_b32_e32 v97, v97, v98, vcc
	v_sqrt_f32_e32 v98, v97
	s_nop 0
	v_add_u32_e32 v100, -1, v98
	v_add_u32_e32 v101, 1, v98
	v_fma_f32 v102, -v100, v98, v97
	v_fma_f32 v103, -v101, v98, v97
	v_cmp_ge_f32_e64 s[0:1], 0, v102
	s_nop 1
	v_cndmask_b32_e64 v98, v98, v100, s[0:1]
	v_cmp_lt_f32_e64 s[0:1], 0, v103
	s_nop 1
	v_cndmask_b32_e64 v98, v98, v101, s[0:1]
	v_mul_f32_e32 v100, 0x37800000, v98
	v_cndmask_b32_e32 v98, v98, v100, vcc
	v_cmp_class_f32_e32 vcc, v97, v161
	s_nop 1
	v_cndmask_b32_e32 v98, v98, v97, vcc
	v_div_scale_f32 v100, s[0:1], v98, v98, s85
	v_rcp_f32_e32 v101, v100
	v_and_b32_e32 v97, 0xfde0, v99
	v_div_scale_f32 v99, vcc, s85, v98, s85
	v_fma_f32 v102, -v100, v101, 1.0
	v_fmac_f32_e32 v101, v102, v101
	v_mul_f32_e32 v102, v99, v101
	v_fma_f32 v103, -v100, v102, v99
	v_fmac_f32_e32 v102, v103, v101
	v_fma_f32 v99, -v100, v102, v99
	v_div_fmas_f32 v99, v99, v101, v102
	v_div_fixup_f32 v98, v99, v98, s85
	v_pk_mul_f32 v[94:95], v[94:95], v[98:99] op_sel_hi:[1,0]
	v_pk_mul_f32 v[92:93], v[92:93], v[98:99] op_sel_hi:[1,0]
	v_pk_mul_f32 v[90:91], v[90:91], v[98:99] op_sel_hi:[1,0]
	v_pk_mul_f32 v[88:89], v[88:89], v[98:99] op_sel_hi:[1,0]
	s_and_saveexec_b64 s[0:1], s[8:9]
	s_cbranch_execz .LBB0_1109
	v_add_u32_e32 v136, v97, v124
	v_lshl_add_u64 v[104:105], v[136:137], 3, s[74:75]
	global_load_dwordx4 v[100:103], v[104:105], off
	s_nop 0
	global_load_dwordx4 v[104:107], v[104:105], off offset:16
	s_waitcnt vmcnt(0)
	v_pk_mul_f32 v[110:111], v[92:93], v[100:101] op_sel:[1,1] op_sel_hi:[0,1]
	v_mul_f32_e32 v112, v95, v103
	v_mul_f32_e32 v114, v94, v103
	v_pk_mul_f32 v[118:119], v[88:89], v[104:105] op_sel:[1,1] op_sel_hi:[0,1]
	v_mul_f32_e32 v120, v91, v107
	v_mul_f32_e32 v126, v90, v107
	v_pk_mul_f32 v[108:109], v[92:93], v[100:101]
	v_pk_mul_f32 v[116:117], v[88:89], v[104:105]
	v_pk_fma_f32 v[92:93], v[92:93], v[100:101], v[110:111] op_sel_hi:[1,0,1]
	v_pk_fma_f32 v[100:101], v[94:95], v[102:103], v[112:113] op_sel_hi:[1,1,0] neg_lo:[0,0,1] neg_hi:[0,0,1]
	v_pk_fma_f32 v[102:103], v[94:95], v[102:103], v[114:115] op_sel:[1,0,0] op_sel_hi:[0,1,0]
	v_pk_fma_f32 v[88:89], v[88:89], v[104:105], v[118:119] op_sel_hi:[1,0,1]
	v_pk_fma_f32 v[104:105], v[90:91], v[106:107], v[120:121] op_sel_hi:[1,1,0] neg_lo:[0,0,1] neg_hi:[0,0,1]
	v_pk_fma_f32 v[106:107], v[90:91], v[106:107], v[126:127] op_sel:[1,0,0] op_sel_hi:[0,1,0]
	v_sub_f32_e32 v92, v108, v110
	v_sub_f32_e32 v88, v116, v118
	v_mov_b32_e32 v94, v100
	v_mov_b32_e32 v95, v102
	v_mov_b32_e32 v90, v104
	v_mov_b32_e32 v91, v106

.LBB0_1111:
	s_or_b64 exec, exec, s[0:1]
	v_cvt_pk_bf16_f32 v84, v84, v85
	v_cvt_pk_bf16_f32 v85, v86, v87
	v_cvt_pk_bf16_f32 v86, v80, v81
	v_cvt_pk_bf16_f32 v87, v82, v83
	v_or_b32_e32 v80, 48, v148
	global_store_dwordx4 v[88:89], v[84:87], off offset:256
	v_ashrrev_i32_e32 v81, 31, v80
	v_lshl_add_u64 v[82:83], v[80:81], 3, s[20:21]
	s_nop 0
	v_lshlrev_b32_e32 v83, 5, v80
	s_nop 0
	v_fmamk_f32 v81, v240, 0x3b000000, v160
	v_mul_f32_e32 v82, 0x4f800000, v81
	v_cmp_gt_f32_e32 vcc, s84, v81
	s_nop 1
	v_cndmask_b32_e32 v81, v81, v82, vcc
	v_sqrt_f32_e32 v82, v81
	s_nop 0
	v_add_u32_e32 v84, -1, v82
	v_add_u32_e32 v85, 1, v82
	v_fma_f32 v86, -v84, v82, v81
	v_fma_f32 v87, -v85, v82, v81
	v_cmp_ge_f32_e64 s[0:1], 0, v86
	s_nop 1
	v_cndmask_b32_e64 v82, v82, v84, s[0:1]
	v_cmp_lt_f32_e64 s[0:1], 0, v87
	s_nop 1
	v_cndmask_b32_e64 v82, v82, v85, s[0:1]
	v_mul_f32_e32 v84, 0x37800000, v82
	v_cndmask_b32_e32 v82, v82, v84, vcc
	v_cmp_class_f32_e32 vcc, v81, v161
	s_nop 1
	v_cndmask_b32_e32 v82, v82, v81, vcc
	v_div_scale_f32 v84, s[0:1], v82, v82, s85
	v_rcp_f32_e32 v85, v84
	v_and_b32_e32 v81, 0xffe0, v83
	v_div_scale_f32 v83, vcc, s85, v82, s85
	v_fma_f32 v86, -v84, v85, 1.0
	v_fmac_f32_e32 v85, v86, v85
	v_mul_f32_e32 v86, v83, v85
	v_fma_f32 v87, -v84, v86, v83
	v_fmac_f32_e32 v86, v87, v85
	v_fma_f32 v83, -v84, v86, v83
	v_div_fmas_f32 v83, v83, v85, v86
	v_div_fixup_f32 v82, v83, v82, s85
	v_pk_mul_f32 v[78:79], v[78:79], v[82:83] op_sel_hi:[1,0]
	v_pk_mul_f32 v[76:77], v[76:77], v[82:83] op_sel_hi:[1,0]
	v_pk_mul_f32 v[74:75], v[74:75], v[82:83] op_sel_hi:[1,0]
	v_pk_mul_f32 v[72:73], v[72:73], v[82:83] op_sel_hi:[1,0]
	s_and_saveexec_b64 s[0:1], s[8:9]
	s_cbranch_execz .LBB0_1113
	v_add_u32_e32 v136, v81, v124
	v_lshl_add_u64 v[88:89], v[136:137], 3, s[74:75]
	global_load_dwordx4 v[84:87], v[88:89], off
	s_nop 0
	global_load_dwordx4 v[88:91], v[88:89], off offset:16
	s_waitcnt vmcnt(0)
	v_pk_mul_f32 v[94:95], v[76:77], v[84:85] op_sel:[1,1] op_sel_hi:[0,1]
	v_mul_f32_e32 v96, v79, v87
	v_mul_f32_e32 v98, v78, v87
	v_pk_mul_f32 v[102:103], v[72:73], v[88:89] op_sel:[1,1] op_sel_hi:[0,1]
	v_mul_f32_e32 v104, v75, v91
	v_mul_f32_e32 v106, v74, v91
	v_pk_mul_f32 v[92:93], v[76:77], v[84:85]
	v_pk_mul_f32 v[100:101], v[72:73], v[88:89]
	v_pk_fma_f32 v[76:77], v[76:77], v[84:85], v[94:95] op_sel_hi:[1,0,1]
	v_pk_fma_f32 v[84:85], v[78:79], v[86:87], v[96:97] op_sel_hi:[1,1,0] neg_lo:[0,0,1] neg_hi:[0,0,1]
	v_pk_fma_f32 v[86:87], v[78:79], v[86:87], v[98:99] op_sel:[1,0,0] op_sel_hi:[0,1,0]
	v_pk_fma_f32 v[72:73], v[72:73], v[88:89], v[102:103] op_sel_hi:[1,0,1]
	v_pk_fma_f32 v[88:89], v[74:75], v[90:91], v[104:105] op_sel_hi:[1,1,0] neg_lo:[0,0,1] neg_hi:[0,0,1]
	v_pk_fma_f32 v[90:91], v[74:75], v[90:91], v[106:107] op_sel:[1,0,0] op_sel_hi:[0,1,0]
	v_sub_f32_e32 v76, v92, v94
	v_sub_f32_e32 v72, v100, v102
	v_mov_b32_e32 v78, v84
	v_mov_b32_e32 v79, v86
	v_mov_b32_e32 v74, v88
	v_mov_b32_e32 v75, v90

.LBB0_1115:
	s_or_b64 exec, exec, s[0:1]
	v_cvt_pk_bf16_f32 v68, v68, v69
	v_cvt_pk_bf16_f32 v69, v70, v71
	v_cvt_pk_bf16_f32 v70, v64, v65
	v_cvt_pk_bf16_f32 v71, v66, v67
	v_add_u32_e32 v64, 0x80, v148
	global_store_dwordx4 v[72:73], v[68:71], off offset:256
	v_ashrrev_i32_e32 v65, 31, v64
	v_lshl_add_u64 v[66:67], v[64:65], 3, s[20:21]
	s_nop 0
	v_lshlrev_b32_e32 v67, 5, v64
	s_nop 0
	v_fmamk_f32 v65, v241, 0x3b000000, v160
	v_mul_f32_e32 v66, 0x4f800000, v65
	v_cmp_gt_f32_e32 vcc, s84, v65
	s_nop 1
	v_cndmask_b32_e32 v65, v65, v66, vcc
	v_sqrt_f32_e32 v66, v65
	s_nop 0
	v_add_u32_e32 v68, -1, v66
	v_add_u32_e32 v69, 1, v66
	v_fma_f32 v70, -v68, v66, v65
	v_fma_f32 v71, -v69, v66, v65
	v_cmp_ge_f32_e64 s[0:1], 0, v70
	s_nop 1
	v_cndmask_b32_e64 v66, v66, v68, s[0:1]
	v_cmp_lt_f32_e64 s[0:1], 0, v71
	s_nop 1
	v_cndmask_b32_e64 v66, v66, v69, s[0:1]
	v_mul_f32_e32 v68, 0x37800000, v66
	v_cndmask_b32_e32 v66, v66, v68, vcc
	v_cmp_class_f32_e32 vcc, v65, v161
	s_nop 1
	v_cndmask_b32_e32 v66, v66, v65, vcc
	v_div_scale_f32 v68, s[0:1], v66, v66, s85
	v_rcp_f32_e32 v69, v68
	v_and_b32_e32 v65, 0xf9e0, v67
	v_div_scale_f32 v67, vcc, s85, v66, s85
	v_fma_f32 v70, -v68, v69, 1.0
	v_fmac_f32_e32 v69, v70, v69
	v_mul_f32_e32 v70, v67, v69
	v_fma_f32 v71, -v68, v70, v67
	v_fmac_f32_e32 v70, v71, v69
	v_fma_f32 v67, -v68, v70, v67
	v_div_fmas_f32 v67, v67, v69, v70
	v_div_fixup_f32 v66, v67, v66, s85
	v_pk_mul_f32 v[62:63], v[62:63], v[66:67] op_sel_hi:[1,0]
	v_pk_mul_f32 v[60:61], v[60:61], v[66:67] op_sel_hi:[1,0]
	v_pk_mul_f32 v[58:59], v[58:59], v[66:67] op_sel_hi:[1,0]
	v_pk_mul_f32 v[56:57], v[56:57], v[66:67] op_sel_hi:[1,0]
	s_and_saveexec_b64 s[0:1], s[8:9]
	s_cbranch_execz .LBB0_1117
	v_add_u32_e32 v136, v65, v124
	v_lshl_add_u64 v[72:73], v[136:137], 3, s[74:75]
	global_load_dwordx4 v[68:71], v[72:73], off
	s_nop 0
	global_load_dwordx4 v[72:75], v[72:73], off offset:16
	s_waitcnt vmcnt(0)
	v_pk_mul_f32 v[78:79], v[60:61], v[68:69] op_sel:[1,1] op_sel_hi:[0,1]
	v_mul_f32_e32 v80, v63, v71
	v_mul_f32_e32 v82, v62, v71
	v_pk_mul_f32 v[86:87], v[56:57], v[72:73] op_sel:[1,1] op_sel_hi:[0,1]
	v_mul_f32_e32 v88, v59, v75
	v_mul_f32_e32 v90, v58, v75
	v_pk_mul_f32 v[76:77], v[60:61], v[68:69]
	v_pk_mul_f32 v[84:85], v[56:57], v[72:73]
	v_pk_fma_f32 v[60:61], v[60:61], v[68:69], v[78:79] op_sel_hi:[1,0,1]
	v_pk_fma_f32 v[68:69], v[62:63], v[70:71], v[80:81] op_sel_hi:[1,1,0] neg_lo:[0,0,1] neg_hi:[0,0,1]
	v_pk_fma_f32 v[70:71], v[62:63], v[70:71], v[82:83] op_sel:[1,0,0] op_sel_hi:[0,1,0]
	v_pk_fma_f32 v[56:57], v[56:57], v[72:73], v[86:87] op_sel_hi:[1,0,1]
	v_pk_fma_f32 v[72:73], v[58:59], v[74:75], v[88:89] op_sel_hi:[1,1,0] neg_lo:[0,0,1] neg_hi:[0,0,1]
	v_pk_fma_f32 v[74:75], v[58:59], v[74:75], v[90:91] op_sel:[1,0,0] op_sel_hi:[0,1,0]
	v_sub_f32_e32 v60, v76, v78
	v_sub_f32_e32 v56, v84, v86
	v_mov_b32_e32 v62, v68
	v_mov_b32_e32 v63, v70
	v_mov_b32_e32 v58, v72
	v_mov_b32_e32 v59, v74

.LBB0_1119:
	s_or_b64 exec, exec, s[0:1]
	v_cvt_pk_bf16_f32 v52, v52, v53
	v_cvt_pk_bf16_f32 v53, v54, v55
	v_cvt_pk_bf16_f32 v54, v48, v49
	v_cvt_pk_bf16_f32 v55, v50, v51
	v_add_u32_e32 v48, 0x90, v148
	global_store_dwordx4 v[56:57], v[52:55], off offset:256
	v_ashrrev_i32_e32 v49, 31, v48
	v_lshl_add_u64 v[50:51], v[48:49], 3, s[20:21]
	s_nop 0
	v_lshlrev_b32_e32 v51, 5, v48
	s_nop 0
	v_fmamk_f32 v49, v242, 0x3b000000, v160
	v_mul_f32_e32 v50, 0x4f800000, v49
	v_cmp_gt_f32_e32 vcc, s84, v49
	s_nop 1
	v_cndmask_b32_e32 v49, v49, v50, vcc
	v_sqrt_f32_e32 v50, v49
	s_nop 0
	v_add_u32_e32 v52, -1, v50
	v_add_u32_e32 v53, 1, v50
	v_fma_f32 v54, -v52, v50, v49
	v_fma_f32 v55, -v53, v50, v49
	v_cmp_ge_f32_e64 s[0:1], 0, v54
	s_nop 1
	v_cndmask_b32_e64 v50, v50, v52, s[0:1]
	v_cmp_lt_f32_e64 s[0:1], 0, v55
	s_nop 1
	v_cndmask_b32_e64 v50, v50, v53, s[0:1]
	v_mul_f32_e32 v52, 0x37800000, v50
	v_cndmask_b32_e32 v50, v50, v52, vcc
	v_cmp_class_f32_e32 vcc, v49, v161
	s_nop 1
	v_cndmask_b32_e32 v50, v50, v49, vcc
	v_div_scale_f32 v52, s[0:1], v50, v50, s85
	v_rcp_f32_e32 v53, v52
	v_and_b32_e32 v49, 0xfbe0, v51
	v_div_scale_f32 v51, vcc, s85, v50, s85
	v_fma_f32 v54, -v52, v53, 1.0
	v_fmac_f32_e32 v53, v54, v53
	v_mul_f32_e32 v54, v51, v53
	v_fma_f32 v55, -v52, v54, v51
	v_fmac_f32_e32 v54, v55, v53
	v_fma_f32 v51, -v52, v54, v51
	v_div_fmas_f32 v51, v51, v53, v54
	v_div_fixup_f32 v50, v51, v50, s85
	v_pk_mul_f32 v[46:47], v[46:47], v[50:51] op_sel_hi:[1,0]
	v_pk_mul_f32 v[44:45], v[44:45], v[50:51] op_sel_hi:[1,0]
	v_pk_mul_f32 v[42:43], v[42:43], v[50:51] op_sel_hi:[1,0]
	v_pk_mul_f32 v[40:41], v[40:41], v[50:51] op_sel_hi:[1,0]
	s_and_saveexec_b64 s[0:1], s[8:9]
	s_cbranch_execz .LBB0_1121
	v_add_u32_e32 v136, v49, v124
	v_lshl_add_u64 v[56:57], v[136:137], 3, s[74:75]
	global_load_dwordx4 v[52:55], v[56:57], off
	s_nop 0
	global_load_dwordx4 v[56:59], v[56:57], off offset:16
	s_waitcnt vmcnt(0)
	v_pk_mul_f32 v[62:63], v[44:45], v[52:53] op_sel:[1,1] op_sel_hi:[0,1]
	v_mul_f32_e32 v64, v47, v55
	v_mul_f32_e32 v66, v46, v55
	v_pk_mul_f32 v[70:71], v[40:41], v[56:57] op_sel:[1,1] op_sel_hi:[0,1]
	v_mul_f32_e32 v72, v43, v59
	v_mul_f32_e32 v74, v42, v59
	v_pk_mul_f32 v[60:61], v[44:45], v[52:53]
	v_pk_mul_f32 v[68:69], v[40:41], v[56:57]
	v_pk_fma_f32 v[44:45], v[44:45], v[52:53], v[62:63] op_sel_hi:[1,0,1]
	v_pk_fma_f32 v[52:53], v[46:47], v[54:55], v[64:65] op_sel_hi:[1,1,0] neg_lo:[0,0,1] neg_hi:[0,0,1]
	v_pk_fma_f32 v[54:55], v[46:47], v[54:55], v[66:67] op_sel:[1,0,0] op_sel_hi:[0,1,0]
	v_pk_fma_f32 v[40:41], v[40:41], v[56:57], v[70:71] op_sel_hi:[1,0,1]
	v_pk_fma_f32 v[56:57], v[42:43], v[58:59], v[72:73] op_sel_hi:[1,1,0] neg_lo:[0,0,1] neg_hi:[0,0,1]
	v_pk_fma_f32 v[58:59], v[42:43], v[58:59], v[74:75] op_sel:[1,0,0] op_sel_hi:[0,1,0]
	v_sub_f32_e32 v44, v60, v62
	v_sub_f32_e32 v40, v68, v70
	v_mov_b32_e32 v46, v52
	v_mov_b32_e32 v47, v54
	v_mov_b32_e32 v42, v56
	v_mov_b32_e32 v43, v58

.LBB0_1123:
	s_or_b64 exec, exec, s[0:1]
	v_cvt_pk_bf16_f32 v36, v36, v37
	v_cvt_pk_bf16_f32 v37, v38, v39
	v_cvt_pk_bf16_f32 v38, v32, v33
	v_cvt_pk_bf16_f32 v39, v34, v35
	v_add_u32_e32 v32, 0xa0, v148
	global_store_dwordx4 v[40:41], v[36:39], off offset:256
	v_ashrrev_i32_e32 v33, 31, v32
	v_lshl_add_u64 v[34:35], v[32:33], 3, s[20:21]
	s_nop 0
	v_lshlrev_b32_e32 v35, 5, v32
	s_nop 0
	v_fmamk_f32 v33, v243, 0x3b000000, v160
	v_mul_f32_e32 v34, 0x4f800000, v33
	v_cmp_gt_f32_e32 vcc, s84, v33
	s_nop 1
	v_cndmask_b32_e32 v33, v33, v34, vcc
	v_sqrt_f32_e32 v34, v33
	s_nop 0
	v_add_u32_e32 v36, -1, v34
	v_add_u32_e32 v37, 1, v34
	v_fma_f32 v38, -v36, v34, v33
	v_fma_f32 v39, -v37, v34, v33
	v_cmp_ge_f32_e64 s[0:1], 0, v38
	s_nop 1
	v_cndmask_b32_e64 v34, v34, v36, s[0:1]
	v_cmp_lt_f32_e64 s[0:1], 0, v39
	s_nop 1
	v_cndmask_b32_e64 v34, v34, v37, s[0:1]
	v_mul_f32_e32 v36, 0x37800000, v34
	v_cndmask_b32_e32 v34, v34, v36, vcc
	v_cmp_class_f32_e32 vcc, v33, v161
	s_nop 1
	v_cndmask_b32_e32 v34, v34, v33, vcc
	v_div_scale_f32 v36, s[0:1], v34, v34, s85
	v_rcp_f32_e32 v37, v36
	v_and_b32_e32 v33, 0xfde0, v35
	v_div_scale_f32 v35, vcc, s85, v34, s85
	v_fma_f32 v38, -v36, v37, 1.0
	v_fmac_f32_e32 v37, v38, v37
	v_mul_f32_e32 v38, v35, v37
	v_fma_f32 v39, -v36, v38, v35
	v_fmac_f32_e32 v38, v39, v37
	v_fma_f32 v35, -v36, v38, v35
	v_div_fmas_f32 v35, v35, v37, v38
	v_div_fixup_f32 v34, v35, v34, s85
	v_pk_mul_f32 v[30:31], v[30:31], v[34:35] op_sel_hi:[1,0]
	v_pk_mul_f32 v[28:29], v[28:29], v[34:35] op_sel_hi:[1,0]
	v_pk_mul_f32 v[26:27], v[26:27], v[34:35] op_sel_hi:[1,0]
	v_pk_mul_f32 v[24:25], v[24:25], v[34:35] op_sel_hi:[1,0]
	s_and_saveexec_b64 s[0:1], s[8:9]
	s_cbranch_execz .LBB0_1125
	v_add_u32_e32 v136, v33, v124
	v_lshl_add_u64 v[40:41], v[136:137], 3, s[74:75]
	global_load_dwordx4 v[36:39], v[40:41], off
	s_nop 0
	global_load_dwordx4 v[40:43], v[40:41], off offset:16
	s_waitcnt vmcnt(0)
	v_pk_mul_f32 v[46:47], v[28:29], v[36:37] op_sel:[1,1] op_sel_hi:[0,1]
	v_mul_f32_e32 v48, v31, v39
	v_mul_f32_e32 v50, v30, v39
	v_pk_mul_f32 v[54:55], v[24:25], v[40:41] op_sel:[1,1] op_sel_hi:[0,1]
	v_mul_f32_e32 v56, v27, v43
	v_mul_f32_e32 v58, v26, v43
	v_pk_mul_f32 v[44:45], v[28:29], v[36:37]
	v_pk_mul_f32 v[52:53], v[24:25], v[40:41]
	v_pk_fma_f32 v[28:29], v[28:29], v[36:37], v[46:47] op_sel_hi:[1,0,1]
	v_pk_fma_f32 v[36:37], v[30:31], v[38:39], v[48:49] op_sel_hi:[1,1,0] neg_lo:[0,0,1] neg_hi:[0,0,1]
	v_pk_fma_f32 v[38:39], v[30:31], v[38:39], v[50:51] op_sel:[1,0,0] op_sel_hi:[0,1,0]
	v_pk_fma_f32 v[24:25], v[24:25], v[40:41], v[54:55] op_sel_hi:[1,0,1]
	v_pk_fma_f32 v[40:41], v[26:27], v[42:43], v[56:57] op_sel_hi:[1,1,0] neg_lo:[0,0,1] neg_hi:[0,0,1]
	v_pk_fma_f32 v[42:43], v[26:27], v[42:43], v[58:59] op_sel:[1,0,0] op_sel_hi:[0,1,0]
	v_sub_f32_e32 v28, v44, v46
	v_sub_f32_e32 v24, v52, v54
	v_mov_b32_e32 v30, v36
	v_mov_b32_e32 v31, v38
	v_mov_b32_e32 v26, v40
	v_mov_b32_e32 v27, v42

.LBB0_1127:
	s_or_b64 exec, exec, s[0:1]
	v_cvt_pk_bf16_f32 v20, v20, v21
	v_cvt_pk_bf16_f32 v21, v22, v23
	v_cvt_pk_bf16_f32 v22, v16, v17
	v_cvt_pk_bf16_f32 v23, v18, v19
	v_add_u32_e32 v16, 0xb0, v148
	global_store_dwordx4 v[24:25], v[20:23], off offset:256
	v_ashrrev_i32_e32 v17, 31, v16
	v_lshl_add_u64 v[18:19], v[16:17], 3, s[20:21]
	s_nop 0
	v_lshlrev_b32_e32 v19, 5, v16
	s_nop 0
	v_fmamk_f32 v17, v244, 0x3b000000, v160
	v_mul_f32_e32 v18, 0x4f800000, v17
	v_cmp_gt_f32_e32 vcc, s84, v17
	s_nop 1
	v_cndmask_b32_e32 v17, v17, v18, vcc
	v_sqrt_f32_e32 v18, v17
	s_nop 0
	v_add_u32_e32 v20, -1, v18
	v_add_u32_e32 v21, 1, v18
	v_fma_f32 v22, -v20, v18, v17
	v_fma_f32 v23, -v21, v18, v17
	v_cmp_ge_f32_e64 s[0:1], 0, v22
	s_nop 1
	v_cndmask_b32_e64 v18, v18, v20, s[0:1]
	v_cmp_lt_f32_e64 s[0:1], 0, v23
	s_nop 1
	v_cndmask_b32_e64 v18, v18, v21, s[0:1]
	v_mul_f32_e32 v20, 0x37800000, v18
	v_cndmask_b32_e32 v18, v18, v20, vcc
	v_cmp_class_f32_e32 vcc, v17, v161
	s_nop 1
	v_cndmask_b32_e32 v18, v18, v17, vcc
	v_div_scale_f32 v20, s[0:1], v18, v18, s85
	v_rcp_f32_e32 v21, v20
	v_and_b32_e32 v17, 0xffe0, v19
	v_div_scale_f32 v19, vcc, s85, v18, s85
	v_fma_f32 v22, -v20, v21, 1.0
	v_fmac_f32_e32 v21, v22, v21
	v_mul_f32_e32 v22, v19, v21
	v_fma_f32 v23, -v20, v22, v19
	v_fmac_f32_e32 v22, v23, v21
	v_fma_f32 v19, -v20, v22, v19
	v_div_fmas_f32 v19, v19, v21, v22
	v_div_fixup_f32 v18, v19, v18, s85
	v_pk_mul_f32 v[14:15], v[14:15], v[18:19] op_sel_hi:[1,0]
	v_pk_mul_f32 v[12:13], v[12:13], v[18:19] op_sel_hi:[1,0]
	v_pk_mul_f32 v[10:11], v[10:11], v[18:19] op_sel_hi:[1,0]
	v_pk_mul_f32 v[8:9], v[8:9], v[18:19] op_sel_hi:[1,0]
	s_and_saveexec_b64 s[0:1], s[8:9]
	s_cbranch_execz .LBB0_1129
	v_add_u32_e32 v136, v17, v124
	v_lshl_add_u64 v[24:25], v[136:137], 3, s[74:75]
	global_load_dwordx4 v[20:23], v[24:25], off
	s_nop 0
	global_load_dwordx4 v[24:27], v[24:25], off offset:16
	s_waitcnt vmcnt(0)
	v_pk_mul_f32 v[30:31], v[12:13], v[20:21] op_sel:[1,1] op_sel_hi:[0,1]
	v_mul_f32_e32 v32, v15, v23
	v_mul_f32_e32 v34, v14, v23
	v_pk_mul_f32 v[38:39], v[8:9], v[24:25] op_sel:[1,1] op_sel_hi:[0,1]
	v_mul_f32_e32 v40, v11, v27
	v_mul_f32_e32 v42, v10, v27
	v_pk_mul_f32 v[28:29], v[12:13], v[20:21]
	v_pk_mul_f32 v[36:37], v[8:9], v[24:25]
	v_pk_fma_f32 v[12:13], v[12:13], v[20:21], v[30:31] op_sel_hi:[1,0,1]
	v_pk_fma_f32 v[20:21], v[14:15], v[22:23], v[32:33] op_sel_hi:[1,1,0] neg_lo:[0,0,1] neg_hi:[0,0,1]
	v_pk_fma_f32 v[22:23], v[14:15], v[22:23], v[34:35] op_sel:[1,0,0] op_sel_hi:[0,1,0]
	v_pk_fma_f32 v[8:9], v[8:9], v[24:25], v[38:39] op_sel_hi:[1,0,1]
	v_pk_fma_f32 v[24:25], v[10:11], v[26:27], v[40:41] op_sel_hi:[1,1,0] neg_lo:[0,0,1] neg_hi:[0,0,1]
	v_pk_fma_f32 v[26:27], v[10:11], v[26:27], v[42:43] op_sel:[1,0,0] op_sel_hi:[0,1,0]
	v_sub_f32_e32 v12, v28, v30
	v_sub_f32_e32 v8, v36, v38
	v_mov_b32_e32 v14, v20
	v_mov_b32_e32 v15, v22
	v_mov_b32_e32 v10, v24
	v_mov_b32_e32 v11, v26

.LBB0_1295:
	v_lshl_add_u32 v128, s79, 8, v223
	v_ashrrev_i32_e32 v129, 31, v128
	v_lshlrev_b64 v[164:165], 3, v[128:129]
	v_lshl_add_u64 v[130:131], s[14:15], 0, v[164:165]
	global_load_dwordx2 v[186:187], v[130:131], off
	v_lshl_or_b32 v130, s78, 8, v225
	v_ashrrev_i32_e32 v131, 31, v130
	v_lshlrev_b64 v[132:133], 12, v[128:129]
	v_lshl_add_u64 v[132:133], s[16:17], 0, v[132:133]
	v_lshlrev_b64 v[178:179], 1, v[130:131]
	v_lshl_add_u64 v[176:177], v[132:133], 0, v[178:179]
	global_load_dwordx4 v[192:195], v[176:177], off
	v_or_b32_e32 v196, 16, v128
	v_or_b32_e32 v218, 32, v128
	v_or_b32_e32 v198, 48, v128
	v_add_u32_e32 v204, 0x80, v128
	v_add_u32_e32 v208, 0x90, v128
	v_add_u32_e32 v184, 0xa0, v128
	v_add_u32_e32 v180, 0xb0, v128
	v_lshlrev_b64 v[128:129], 2, v[130:131]
	v_lshl_add_u64 v[188:189], s[68:69], 0, v[128:129]
	v_lshl_add_u64 v[190:191], s[70:71], 0, v[128:129]
	global_load_dwordx4 v[128:131], v[188:189], off offset:16
	global_load_dwordx4 v[136:139], v[188:189], off
	global_load_dwordx4 v[132:135], v[190:191], off offset:16
	global_load_dwordx4 v[140:143], v[190:191], off
	v_ashrrev_i32_e32 v197, 31, v196
	v_ashrrev_i32_e32 v219, 31, v218
	v_ashrrev_i32_e32 v199, 31, v198
	v_ashrrev_i32_e32 v205, 31, v204
	v_ashrrev_i32_e32 v209, 31, v208
	v_ashrrev_i32_e32 v185, 31, v184
	v_ashrrev_i32_e32 v181, 31, v180
	v_lshlrev_b64 v[174:175], 3, v[196:197]
	v_lshlrev_b64 v[172:173], 3, v[218:219]
	v_lshlrev_b64 v[170:171], 3, v[198:199]
	v_lshlrev_b64 v[168:169], 3, v[204:205]
	v_lshlrev_b64 v[166:167], 3, v[208:209]
	v_lshlrev_b64 v[162:163], 3, v[184:185]
	v_lshlrev_b64 v[160:161], 3, v[180:181]
	v_lshl_add_u64 v[182:183], s[14:15], 0, v[174:175]
	v_lshl_add_u64 v[200:201], s[14:15], 0, v[172:173]
	v_lshl_add_u64 v[202:203], s[14:15], 0, v[170:171]
	v_lshl_add_u64 v[210:211], s[14:15], 0, v[168:169]
	v_lshl_add_u64 v[212:213], s[14:15], 0, v[166:167]
	v_lshl_add_u64 v[214:215], s[14:15], 0, v[162:163]
	v_lshl_add_u64 v[216:217], s[14:15], 0, v[160:161]
	global_load_dwordx2 v[230:231], v[182:183], off
	s_nop 0
	global_load_dwordx2 v[200:201], v[200:201], off
	s_nop 0
	global_load_dwordx2 v[206:207], v[202:203], off
	s_nop 0
	global_load_dwordx2 v[210:211], v[210:211], off
	s_nop 0
	global_load_dwordx2 v[212:213], v[212:213], off
	s_nop 0
	global_load_dwordx2 v[182:183], v[214:215], off
	global_load_dwordx2 v[202:203], v[216:217], off
	v_lshlrev_b64 v[198:199], 12, v[198:199]
	v_lshl_add_u64 v[198:199], s[16:17], 0, v[198:199]
	v_lshl_add_u64 v[198:199], v[198:199], 0, v[178:179]
	v_lshlrev_b64 v[204:205], 12, v[204:205]
	v_lshl_add_u64 v[204:205], s[16:17], 0, v[204:205]
	v_lshl_add_u64 v[204:205], v[204:205], 0, v[178:179]
	v_lshlrev_b64 v[208:209], 12, v[208:209]
	v_lshl_add_u64 v[208:209], s[16:17], 0, v[208:209]
	v_lshl_add_u64 v[208:209], v[208:209], 0, v[178:179]
	v_lshlrev_b64 v[184:185], 12, v[184:185]
	v_lshl_add_u64 v[184:185], s[16:17], 0, v[184:185]
	v_lshlrev_b64 v[180:181], 12, v[180:181]
	v_lshl_add_u64 v[180:181], s[16:17], 0, v[180:181]
	s_waitcnt vmcnt(0)
	v_pk_mul_f32 v[186:187], v[186:187], s[30:31] op_sel:[1,0] op_sel_hi:[0,0]
	v_fma_f32 v186, -v187, v187, v186
	v_max_f32_e32 v186, 0, v186
	v_add_f32_e32 v186, 0x3727c5ac, v186
	v_cmp_gt_f32_e32 vcc, s63, v186
	v_lshlrev_b32_e32 v214, 16, v192
	v_and_b32_e32 v192, 0xffff0000, v192
	v_lshlrev_b32_e32 v215, 16, v193
	v_and_b32_e32 v216, 0xffff0000, v193
	v_sub_f32_e32 v193, v192, v187
	v_sub_f32_e32 v192, v214, v187
	v_mul_f32_e32 v214, 0x4f800000, v186
	v_cndmask_b32_e32 v186, v186, v214, vcc
	v_lshlrev_b32_e32 v233, 16, v195
	v_and_b32_e32 v234, 0xffff0000, v195
	v_sub_f32_e32 v195, v216, v187
	v_sqrt_f32_e32 v216, v186
	v_and_b32_e32 v232, 0xffff0000, v194
	v_lshlrev_b32_e32 v217, 16, v194
	v_sub_f32_e32 v194, v215, v187
	v_sub_f32_e32 v215, v232, v187
	v_add_u32_e32 v232, -1, v216
	v_sub_f32_e32 v214, v217, v187
	v_sub_f32_e32 v217, v234, v187
	v_add_u32_e32 v234, 1, v216
	v_fma_f32 v235, -v232, v216, v186
	v_fma_f32 v236, -v234, v216, v186
	v_cmp_ge_f32_e64 s[0:1], 0, v235
	v_pk_mul_f32 v[200:201], v[200:201], s[30:31] op_sel:[1,0] op_sel_hi:[0,0]
	s_nop 0
	v_cndmask_b32_e64 v216, v216, v232, s[0:1]
	v_cmp_lt_f32_e64 s[0:1], 0, v236
	v_fma_f32 v200, -v201, v201, v200
	v_max_f32_e32 v200, 0, v200
	v_cndmask_b32_e64 v216, v216, v234, s[0:1]
	v_mul_f32_e32 v232, 0x37800000, v216
	v_cndmask_b32_e32 v216, v216, v232, vcc
	v_cmp_class_f32_e32 vcc, v186, v229
	v_add_f32_e32 v200, 0x3727c5ac, v200
	v_pk_mul_f32 v[206:207], v[206:207], s[30:31] op_sel:[1,0] op_sel_hi:[0,0]
	v_cndmask_b32_e32 v186, v216, v186, vcc
	v_div_scale_f32 v232, s[0:1], v186, v186, 1.0
	v_rcp_f32_e32 v234, v232
	v_sub_f32_e32 v216, v233, v187
	v_div_scale_f32 v233, vcc, 1.0, v186, 1.0
	v_fma_f32 v235, -v232, v234, 1.0
	v_fmac_f32_e32 v234, v235, v234
	v_mul_f32_e32 v235, v233, v234
	v_fma_f32 v236, -v232, v235, v233
	v_fmac_f32_e32 v235, v236, v234
	v_fma_f32 v232, -v232, v235, v233
	v_div_fmas_f32 v232, v232, v234, v235
	v_div_fixup_f32 v186, v232, v186, 1.0
	v_pk_mul_f32 v[194:195], v[186:187], v[194:195] op_sel_hi:[0,1]
	v_pk_mul_f32 v[192:193], v[186:187], v[192:193] op_sel_hi:[0,1]
	v_pk_mul_f32 v[216:217], v[186:187], v[216:217] op_sel_hi:[0,1]
	v_pk_mul_f32 v[214:215], v[186:187], v[214:215] op_sel_hi:[0,1]
	v_pk_fma_f32 v[192:193], v[136:137], v[192:193], v[140:141]
	v_pk_fma_f32 v[194:195], v[138:139], v[194:195], v[142:143]
	v_pk_fma_f32 v[214:215], v[128:129], v[214:215], v[132:133]
	v_pk_fma_f32 v[216:217], v[130:131], v[216:217], v[134:135]
	v_pk_fma_f32 v[126:127], v[194:195], s[34:35], v[126:127] op_sel_hi:[1,0,1]
	v_pk_fma_f32 v[124:125], v[192:193], s[34:35], v[124:125] op_sel_hi:[1,0,1]
	v_pk_fma_f32 v[122:123], v[216:217], s[34:35], v[122:123] op_sel_hi:[1,0,1]
	v_pk_fma_f32 v[120:121], v[214:215], s[34:35], v[120:121] op_sel_hi:[1,0,1]
	v_cvt_pk_bf16_f32 v192, v124, v125
	v_cvt_pk_bf16_f32 v193, v126, v127
	v_cvt_pk_bf16_f32 v194, v120, v121
	v_cvt_pk_bf16_f32 v195, v122, v123
	global_store_dwordx4 v[176:177], v[192:195], off
	v_fma_f32 v206, -v207, v207, v206
	v_max_f32_e32 v206, 0, v206
	v_lshlrev_b64 v[192:193], 12, v[196:197]
	v_lshl_add_u64 v[192:193], s[16:17], 0, v[192:193]
	v_lshl_add_u64 v[192:193], v[192:193], 0, v[178:179]
	global_load_dwordx4 v[240:243], v[192:193], off
	v_pk_mul_f32 v[196:197], v[230:231], s[30:31] op_sel:[1,0] op_sel_hi:[0,0]
	v_fma_f32 v194, -v197, v197, v196
	v_max_f32_e32 v194, 0, v194
	v_add_f32_e32 v194, 0x3727c5ac, v194
	v_mul_f32_e32 v195, 0x4f800000, v194
	v_cmp_gt_f32_e32 vcc, s63, v194
	v_add_f32_e32 v206, 0x3727c5ac, v206
	v_pk_mul_f32 v[210:211], v[210:211], s[30:31] op_sel:[1,0] op_sel_hi:[0,0]
	v_cndmask_b32_e32 v196, v194, v195, vcc
	v_sqrt_f32_e32 v230, v196
	v_lshlrev_b64 v[194:195], 12, v[218:219]
	v_lshl_add_u64 v[194:195], s[16:17], 0, v[194:195]
	v_lshl_add_u64 v[194:195], v[194:195], 0, v[178:179]
	v_add_u32_e32 v218, -1, v230
	v_add_u32_e32 v219, 1, v230
	v_fma_f32 v231, -v218, v230, v196
	v_fma_f32 v232, -v219, v230, v196
	v_cmp_ge_f32_e64 s[0:1], 0, v231
	v_fma_f32 v210, -v211, v211, v210
	v_max_f32_e32 v210, 0, v210
	v_cndmask_b32_e64 v218, v230, v218, s[0:1]
	v_cmp_lt_f32_e64 s[0:1], 0, v232
	v_add_f32_e32 v210, 0x3727c5ac, v210
	v_pk_mul_f32 v[202:203], v[202:203], s[30:31] op_sel:[1,0] op_sel_hi:[0,0]
	v_cndmask_b32_e64 v218, v218, v219, s[0:1]
	v_mul_f32_e32 v219, 0x37800000, v218
	v_cndmask_b32_e32 v218, v218, v219, vcc
	v_cmp_class_f32_e32 vcc, v196, v229
	global_load_dwordx4 v[244:247], v[194:195], off
	s_waitcnt vmcnt(1)
	v_lshlrev_b32_e32 v233, 16, v243
	v_cndmask_b32_e32 v196, v218, v196, vcc
	v_div_scale_f32 v218, s[0:1], v196, v196, 1.0
	v_rcp_f32_e32 v219, v218
	v_div_scale_f32 v230, vcc, 1.0, v196, 1.0
	v_and_b32_e32 v234, 0xffff0000, v243
	v_fma_f32 v231, -v218, v219, 1.0
	v_fmac_f32_e32 v219, v231, v219
	v_mul_f32_e32 v231, v230, v219
	v_fma_f32 v232, -v218, v231, v230
	v_fmac_f32_e32 v231, v232, v219
	v_fma_f32 v218, -v218, v231, v230
	v_div_fmas_f32 v218, v218, v219, v231
	v_div_fixup_f32 v196, v218, v196, 1.0
	v_lshlrev_b32_e32 v218, 16, v240
	v_and_b32_e32 v214, 0xffff0000, v240
	v_lshlrev_b32_e32 v219, 16, v241
	v_and_b32_e32 v230, 0xffff0000, v241
	v_lshlrev_b32_e32 v231, 16, v242
	v_and_b32_e32 v232, 0xffff0000, v242
	v_sub_f32_e32 v215, v214, v197
	v_sub_f32_e32 v214, v218, v197
	v_sub_f32_e32 v217, v230, v197
	v_sub_f32_e32 v216, v219, v197
	v_sub_f32_e32 v219, v232, v197
	v_sub_f32_e32 v218, v231, v197
	v_sub_f32_e32 v231, v234, v197
	v_sub_f32_e32 v230, v233, v197
	v_pk_mul_f32 v[216:217], v[196:197], v[216:217] op_sel_hi:[0,1]
	v_pk_mul_f32 v[214:215], v[196:197], v[214:215] op_sel_hi:[0,1]
	v_pk_mul_f32 v[230:231], v[196:197], v[230:231] op_sel_hi:[0,1]
	v_pk_mul_f32 v[218:219], v[196:197], v[218:219] op_sel_hi:[0,1]
	v_pk_fma_f32 v[214:215], v[136:137], v[214:215], v[140:141]
	v_pk_fma_f32 v[216:217], v[138:139], v[216:217], v[142:143]
	v_pk_fma_f32 v[218:219], v[128:129], v[218:219], v[132:133]
	v_pk_fma_f32 v[230:231], v[130:131], v[230:231], v[134:135]
	v_pk_fma_f32 v[118:119], v[216:217], s[34:35], v[118:119] op_sel_hi:[1,0,1]
	v_pk_fma_f32 v[116:117], v[214:215], s[34:35], v[116:117] op_sel_hi:[1,0,1]
	v_pk_fma_f32 v[114:115], v[230:231], s[34:35], v[114:115] op_sel_hi:[1,0,1]
	v_pk_fma_f32 v[112:113], v[218:219], s[34:35], v[112:113] op_sel_hi:[1,0,1]
	v_cvt_pk_bf16_f32 v214, v116, v117
	v_cvt_pk_bf16_f32 v215, v118, v119
	v_cvt_pk_bf16_f32 v216, v112, v113
	v_cvt_pk_bf16_f32 v217, v114, v115
	global_store_dwordx4 v[192:193], v[214:217], off
	s_nop 0
	v_mul_f32_e32 v218, 0x4f800000, v200
	v_cmp_gt_f32_e32 vcc, s63, v200
	global_load_dwordx4 v[240:243], v[198:199], off
	s_waitcnt vmcnt(2)
	v_lshlrev_b32_e32 v233, 16, v247
	v_cndmask_b32_e32 v200, v200, v218, vcc
	v_sqrt_f32_e32 v218, v200
	v_and_b32_e32 v234, 0xffff0000, v247
	v_add_u32_e32 v219, -1, v218
	v_add_u32_e32 v230, 1, v218
	v_fma_f32 v231, -v219, v218, v200
	v_fma_f32 v232, -v230, v218, v200
	v_cmp_ge_f32_e64 s[0:1], 0, v231
	s_nop 1
	v_cndmask_b32_e64 v218, v218, v219, s[0:1]
	v_cmp_lt_f32_e64 s[0:1], 0, v232
	s_nop 1
	v_cndmask_b32_e64 v218, v218, v230, s[0:1]
	v_mul_f32_e32 v219, 0x37800000, v218
	v_cndmask_b32_e32 v218, v218, v219, vcc
	v_cmp_class_f32_e32 vcc, v200, v229
	s_nop 1
	v_cndmask_b32_e32 v200, v218, v200, vcc
	v_div_scale_f32 v218, s[0:1], v200, v200, 1.0
	v_rcp_f32_e32 v219, v218
	v_div_scale_f32 v230, vcc, 1.0, v200, 1.0
	v_fma_f32 v231, -v218, v219, 1.0
	v_fmac_f32_e32 v219, v231, v219
	v_mul_f32_e32 v231, v230, v219
	v_fma_f32 v232, -v218, v231, v230
	v_fmac_f32_e32 v231, v232, v219
	v_fma_f32 v218, -v218, v231, v230
	v_div_fmas_f32 v218, v218, v219, v231
	v_div_fixup_f32 v200, v218, v200, 1.0
	v_lshlrev_b32_e32 v218, 16, v244
	v_and_b32_e32 v214, 0xffff0000, v244
	v_lshlrev_b32_e32 v219, 16, v245
	v_and_b32_e32 v230, 0xffff0000, v245
	v_lshlrev_b32_e32 v231, 16, v246
	v_and_b32_e32 v232, 0xffff0000, v246
	v_sub_f32_e32 v215, v214, v201
	v_sub_f32_e32 v214, v218, v201
	v_sub_f32_e32 v217, v230, v201
	v_sub_f32_e32 v216, v219, v201
	v_sub_f32_e32 v219, v232, v201
	v_sub_f32_e32 v218, v231, v201
	v_sub_f32_e32 v231, v234, v201
	v_sub_f32_e32 v230, v233, v201
	v_pk_mul_f32 v[216:217], v[200:201], v[216:217] op_sel_hi:[0,1]
	v_pk_mul_f32 v[214:215], v[200:201], v[214:215] op_sel_hi:[0,1]
	v_pk_mul_f32 v[230:231], v[200:201], v[230:231] op_sel_hi:[0,1]
	v_pk_mul_f32 v[218:219], v[200:201], v[218:219] op_sel_hi:[0,1]
	v_pk_fma_f32 v[214:215], v[136:137], v[214:215], v[140:141]
	v_pk_fma_f32 v[216:217], v[138:139], v[216:217], v[142:143]
	v_pk_fma_f32 v[218:219], v[128:129], v[218:219], v[132:133]
	v_pk_fma_f32 v[230:231], v[130:131], v[230:231], v[134:135]
	v_pk_fma_f32 v[110:111], v[216:217], s[34:35], v[110:111] op_sel_hi:[1,0,1]
	v_pk_fma_f32 v[108:109], v[214:215], s[34:35], v[108:109] op_sel_hi:[1,0,1]
	v_pk_fma_f32 v[106:107], v[230:231], s[34:35], v[106:107] op_sel_hi:[1,0,1]
	v_pk_fma_f32 v[104:105], v[218:219], s[34:35], v[104:105] op_sel_hi:[1,0,1]
	v_cvt_pk_bf16_f32 v214, v108, v109
	v_cvt_pk_bf16_f32 v215, v110, v111
	v_cvt_pk_bf16_f32 v216, v104, v105
	v_cvt_pk_bf16_f32 v217, v106, v107
	global_store_dwordx4 v[194:195], v[214:217], off
	s_nop 0
	v_mul_f32_e32 v218, 0x4f800000, v206
	v_cmp_gt_f32_e32 vcc, s63, v206
	global_load_dwordx4 v[244:247], v[204:205], off
	s_waitcnt vmcnt(2)
	v_lshlrev_b32_e32 v233, 16, v243
	v_cndmask_b32_e32 v206, v206, v218, vcc
	v_sqrt_f32_e32 v218, v206
	v_and_b32_e32 v234, 0xffff0000, v243
	v_add_u32_e32 v219, -1, v218
	v_add_u32_e32 v230, 1, v218
	v_fma_f32 v231, -v219, v218, v206
	v_fma_f32 v232, -v230, v218, v206
	v_cmp_ge_f32_e64 s[0:1], 0, v231
	s_nop 1
	v_cndmask_b32_e64 v218, v218, v219, s[0:1]
	v_cmp_lt_f32_e64 s[0:1], 0, v232
	s_nop 1
	v_cndmask_b32_e64 v218, v218, v230, s[0:1]
	v_mul_f32_e32 v219, 0x37800000, v218
	v_cndmask_b32_e32 v218, v218, v219, vcc
	v_cmp_class_f32_e32 vcc, v206, v229
	s_nop 1
	v_cndmask_b32_e32 v206, v218, v206, vcc
	v_div_scale_f32 v218, s[0:1], v206, v206, 1.0
	v_rcp_f32_e32 v219, v218
	v_div_scale_f32 v230, vcc, 1.0, v206, 1.0
	v_fma_f32 v231, -v218, v219, 1.0
	v_fmac_f32_e32 v219, v231, v219
	v_mul_f32_e32 v231, v230, v219
	v_fma_f32 v232, -v218, v231, v230
	v_fmac_f32_e32 v231, v232, v219
	v_fma_f32 v218, -v218, v231, v230
	v_div_fmas_f32 v218, v218, v219, v231
	v_div_fixup_f32 v206, v218, v206, 1.0
	v_lshlrev_b32_e32 v218, 16, v240
	v_and_b32_e32 v214, 0xffff0000, v240
	v_lshlrev_b32_e32 v219, 16, v241
	v_and_b32_e32 v230, 0xffff0000, v241
	v_lshlrev_b32_e32 v231, 16, v242
	v_and_b32_e32 v232, 0xffff0000, v242
	v_sub_f32_e32 v215, v214, v207
	v_sub_f32_e32 v214, v218, v207
	v_sub_f32_e32 v217, v230, v207
	v_sub_f32_e32 v216, v219, v207
	v_sub_f32_e32 v219, v232, v207
	v_sub_f32_e32 v218, v231, v207
	v_sub_f32_e32 v231, v234, v207
	v_sub_f32_e32 v230, v233, v207
	v_pk_mul_f32 v[216:217], v[206:207], v[216:217] op_sel_hi:[0,1]
	v_pk_mul_f32 v[214:215], v[206:207], v[214:215] op_sel_hi:[0,1]
	v_pk_mul_f32 v[230:231], v[206:207], v[230:231] op_sel_hi:[0,1]
	v_pk_mul_f32 v[218:219], v[206:207], v[218:219] op_sel_hi:[0,1]
	v_pk_fma_f32 v[214:215], v[136:137], v[214:215], v[140:141]
	v_pk_fma_f32 v[216:217], v[138:139], v[216:217], v[142:143]
	v_pk_fma_f32 v[218:219], v[128:129], v[218:219], v[132:133]
	v_pk_fma_f32 v[230:231], v[130:131], v[230:231], v[134:135]
	v_pk_fma_f32 v[102:103], v[216:217], s[34:35], v[102:103] op_sel_hi:[1,0,1]
	v_pk_fma_f32 v[100:101], v[214:215], s[34:35], v[100:101] op_sel_hi:[1,0,1]
	v_pk_fma_f32 v[98:99], v[230:231], s[34:35], v[98:99] op_sel_hi:[1,0,1]
	v_pk_fma_f32 v[96:97], v[218:219], s[34:35], v[96:97] op_sel_hi:[1,0,1]
	v_cvt_pk_bf16_f32 v214, v100, v101
	v_cvt_pk_bf16_f32 v215, v102, v103
	v_cvt_pk_bf16_f32 v216, v96, v97
	v_cvt_pk_bf16_f32 v217, v98, v99
	global_store_dwordx4 v[198:199], v[214:217], off
	s_nop 0
	v_mul_f32_e32 v218, 0x4f800000, v210
	v_cmp_gt_f32_e32 vcc, s63, v210
	global_load_dwordx4 v[240:243], v[208:209], off
	s_waitcnt vmcnt(2)
	v_lshlrev_b32_e32 v233, 16, v247
	v_cndmask_b32_e32 v210, v210, v218, vcc
	v_sqrt_f32_e32 v218, v210
	v_and_b32_e32 v234, 0xffff0000, v247
	v_add_u32_e32 v219, -1, v218
	v_add_u32_e32 v230, 1, v218
	v_fma_f32 v231, -v219, v218, v210
	v_fma_f32 v232, -v230, v218, v210
	v_cmp_ge_f32_e64 s[0:1], 0, v231
	s_nop 1
	v_cndmask_b32_e64 v218, v218, v219, s[0:1]
	v_cmp_lt_f32_e64 s[0:1], 0, v232
	s_nop 1
	v_cndmask_b32_e64 v218, v218, v230, s[0:1]
	v_mul_f32_e32 v219, 0x37800000, v218
	v_cndmask_b32_e32 v218, v218, v219, vcc
	v_cmp_class_f32_e32 vcc, v210, v229
	s_nop 1
	v_cndmask_b32_e32 v210, v218, v210, vcc
	v_div_scale_f32 v218, s[0:1], v210, v210, 1.0
	v_rcp_f32_e32 v219, v218
	v_div_scale_f32 v230, vcc, 1.0, v210, 1.0
	v_fma_f32 v231, -v218, v219, 1.0
	v_fmac_f32_e32 v219, v231, v219
	v_mul_f32_e32 v231, v230, v219
	v_fma_f32 v232, -v218, v231, v230
	v_fmac_f32_e32 v231, v232, v219
	v_fma_f32 v218, -v218, v231, v230
	v_div_fmas_f32 v218, v218, v219, v231
	v_div_fixup_f32 v210, v218, v210, 1.0
	v_lshlrev_b32_e32 v218, 16, v244
	v_and_b32_e32 v214, 0xffff0000, v244
	v_lshlrev_b32_e32 v219, 16, v245
	v_and_b32_e32 v230, 0xffff0000, v245
	v_lshlrev_b32_e32 v231, 16, v246
	v_and_b32_e32 v232, 0xffff0000, v246
	v_sub_f32_e32 v215, v214, v211
	v_sub_f32_e32 v214, v218, v211
	v_sub_f32_e32 v217, v230, v211
	v_sub_f32_e32 v216, v219, v211
	v_sub_f32_e32 v219, v232, v211
	v_sub_f32_e32 v218, v231, v211
	v_sub_f32_e32 v231, v234, v211
	v_sub_f32_e32 v230, v233, v211
	v_pk_mul_f32 v[216:217], v[210:211], v[216:217] op_sel_hi:[0,1]
	v_pk_mul_f32 v[214:215], v[210:211], v[214:215] op_sel_hi:[0,1]
	v_pk_mul_f32 v[230:231], v[210:211], v[230:231] op_sel_hi:[0,1]
	v_pk_mul_f32 v[218:219], v[210:211], v[218:219] op_sel_hi:[0,1]
	v_pk_fma_f32 v[214:215], v[136:137], v[214:215], v[140:141]
	v_pk_fma_f32 v[216:217], v[138:139], v[216:217], v[142:143]
	v_pk_fma_f32 v[218:219], v[128:129], v[218:219], v[132:133]
	v_pk_fma_f32 v[230:231], v[130:131], v[230:231], v[134:135]
	v_pk_fma_f32 v[94:95], v[216:217], s[34:35], v[94:95] op_sel_hi:[1,0,1]
	v_pk_fma_f32 v[92:93], v[214:215], s[34:35], v[92:93] op_sel_hi:[1,0,1]
	v_pk_fma_f32 v[90:91], v[230:231], s[34:35], v[90:91] op_sel_hi:[1,0,1]
	v_pk_fma_f32 v[88:89], v[218:219], s[34:35], v[88:89] op_sel_hi:[1,0,1]
	v_cvt_pk_bf16_f32 v214, v92, v93
	v_cvt_pk_bf16_f32 v215, v94, v95
	v_cvt_pk_bf16_f32 v216, v88, v89
	v_cvt_pk_bf16_f32 v217, v90, v91
	global_store_dwordx4 v[204:205], v[214:217], off
	s_nop 0
	s_waitcnt vmcnt(1)
	v_and_b32_e32 v219, 0xffff0000, v242
	v_pk_mul_f32 v[216:217], v[212:213], s[30:31] op_sel:[1,0] op_sel_hi:[0,0]
	v_fma_f32 v212, -v217, v217, v216
	v_max_f32_e32 v212, 0, v212
	v_add_f32_e32 v212, 0x3727c5ac, v212
	v_mul_f32_e32 v213, 0x4f800000, v212
	v_cmp_gt_f32_e32 vcc, s63, v212
	v_sub_f32_e32 v219, v219, v217
	s_nop 0
	v_cndmask_b32_e32 v212, v212, v213, vcc
	v_sqrt_f32_e32 v213, v212
	s_nop 0
	v_add_u32_e32 v214, -1, v213
	v_add_u32_e32 v215, 1, v213
	v_fma_f32 v216, -v214, v213, v212
	v_fma_f32 v218, -v215, v213, v212
	v_cmp_ge_f32_e64 s[0:1], 0, v216
	s_nop 1
	v_cndmask_b32_e64 v213, v213, v214, s[0:1]
	v_cmp_lt_f32_e64 s[0:1], 0, v218
	s_nop 1
	v_cndmask_b32_e64 v213, v213, v215, s[0:1]
	v_mul_f32_e32 v214, 0x37800000, v213
	v_cndmask_b32_e32 v213, v213, v214, vcc
	v_cmp_class_f32_e32 vcc, v212, v229
	v_lshl_add_u64 v[214:215], v[184:185], 0, v[178:179]
	global_load_dwordx4 v[244:247], v[214:215], off
	s_nop 0
	v_cndmask_b32_e32 v212, v213, v212, vcc
	v_div_scale_f32 v213, s[0:1], v212, v212, 1.0
	v_rcp_f32_e32 v216, v213
	v_div_scale_f32 v184, vcc, 1.0, v212, 1.0
	v_fma_f32 v185, -v213, v216, 1.0
	v_fmac_f32_e32 v216, v185, v216
	v_mul_f32_e32 v185, v184, v216
	v_fma_f32 v218, -v213, v185, v184
	v_fmac_f32_e32 v185, v218, v216
	v_fma_f32 v184, -v213, v185, v184
	v_div_fmas_f32 v184, v184, v216, v185
	v_div_fixup_f32 v216, v184, v212, 1.0
	v_lshlrev_b32_e32 v184, 16, v240
	v_and_b32_e32 v185, 0xffff0000, v240
	v_lshlrev_b32_e32 v212, 16, v241
	v_and_b32_e32 v213, 0xffff0000, v241
	v_lshlrev_b32_e32 v218, 16, v242
	v_lshlrev_b32_e32 v230, 16, v243
	v_and_b32_e32 v231, 0xffff0000, v243
	v_sub_f32_e32 v185, v185, v217
	v_sub_f32_e32 v184, v184, v217
	v_sub_f32_e32 v213, v213, v217
	v_sub_f32_e32 v212, v212, v217
	v_sub_f32_e32 v218, v218, v217
	v_sub_f32_e32 v231, v231, v217
	v_sub_f32_e32 v230, v230, v217
	v_pk_mul_f32 v[212:213], v[216:217], v[212:213] op_sel_hi:[0,1]
	v_pk_mul_f32 v[184:185], v[216:217], v[184:185] op_sel_hi:[0,1]
	v_pk_mul_f32 v[230:231], v[216:217], v[230:231] op_sel_hi:[0,1]
	v_pk_mul_f32 v[218:219], v[216:217], v[218:219] op_sel_hi:[0,1]
	v_pk_fma_f32 v[184:185], v[136:137], v[184:185], v[140:141]
	v_pk_fma_f32 v[212:213], v[138:139], v[212:213], v[142:143]
	v_pk_fma_f32 v[218:219], v[128:129], v[218:219], v[132:133]
	v_pk_fma_f32 v[230:231], v[130:131], v[230:231], v[134:135]
	v_pk_fma_f32 v[86:87], v[212:213], s[34:35], v[86:87] op_sel_hi:[1,0,1]
	v_pk_fma_f32 v[84:85], v[184:185], s[34:35], v[84:85] op_sel_hi:[1,0,1]
	v_pk_fma_f32 v[82:83], v[230:231], s[34:35], v[82:83] op_sel_hi:[1,0,1]
	v_pk_fma_f32 v[80:81], v[218:219], s[34:35], v[80:81] op_sel_hi:[1,0,1]
	v_cvt_pk_bf16_f32 v230, v84, v85
	v_cvt_pk_bf16_f32 v231, v86, v87
	v_cvt_pk_bf16_f32 v232, v80, v81
	v_cvt_pk_bf16_f32 v233, v82, v83
	global_store_dwordx4 v[208:209], v[230:233], off
	s_nop 0
	v_pk_mul_f32 v[218:219], v[182:183], s[30:31] op_sel:[1,0] op_sel_hi:[0,0]
	v_fma_f32 v182, -v219, v219, v218
	v_max_f32_e32 v182, 0, v182
	v_add_f32_e32 v182, 0x3727c5ac, v182
	v_mul_f32_e32 v183, 0x4f800000, v182
	v_cmp_gt_f32_e32 vcc, s63, v182
	s_nop 1
	v_cndmask_b32_e32 v182, v182, v183, vcc
	v_sqrt_f32_e32 v183, v182
	s_nop 0
	v_add_u32_e32 v184, -1, v183
	v_add_u32_e32 v185, 1, v183
	v_fma_f32 v212, -v184, v183, v182
	v_fma_f32 v213, -v185, v183, v182
	v_cmp_ge_f32_e64 s[0:1], 0, v212
	s_nop 1
	v_cndmask_b32_e64 v183, v183, v184, s[0:1]
	v_cmp_lt_f32_e64 s[0:1], 0, v213
	v_lshl_add_u64 v[212:213], v[180:181], 0, v[178:179]
	global_load_dwordx4 v[240:243], v[212:213], off
	s_waitcnt vmcnt(2)
	v_and_b32_e32 v181, 0xffff0000, v245
	v_cndmask_b32_e64 v183, v183, v185, s[0:1]
	v_mul_f32_e32 v184, 0x37800000, v183
	v_cndmask_b32_e32 v183, v183, v184, vcc
	v_cmp_class_f32_e32 vcc, v182, v229
	v_and_b32_e32 v185, 0xffff0000, v247
	v_sub_f32_e32 v181, v181, v219
	v_cndmask_b32_e32 v182, v183, v182, vcc
	v_div_scale_f32 v183, s[0:1], v182, v182, 1.0
	v_rcp_f32_e32 v184, v183
	v_div_scale_f32 v178, vcc, 1.0, v182, 1.0
	v_sub_f32_e32 v185, v185, v219
	v_fma_f32 v179, -v183, v184, 1.0
	v_fmac_f32_e32 v184, v179, v184
	v_mul_f32_e32 v179, v178, v184
	v_fma_f32 v180, -v183, v179, v178
	v_fmac_f32_e32 v179, v180, v184
	v_fma_f32 v178, -v183, v179, v178
	v_div_fmas_f32 v178, v178, v184, v179
	v_div_fixup_f32 v218, v178, v182, 1.0
	v_lshlrev_b32_e32 v178, 16, v244
	v_and_b32_e32 v179, 0xffff0000, v244
	v_lshlrev_b32_e32 v180, 16, v245
	v_lshlrev_b32_e32 v182, 16, v246
	v_and_b32_e32 v183, 0xffff0000, v246
	v_lshlrev_b32_e32 v184, 16, v247
	v_sub_f32_e32 v179, v179, v219
	v_sub_f32_e32 v178, v178, v219
	v_sub_f32_e32 v180, v180, v219
	v_sub_f32_e32 v183, v183, v219
	v_sub_f32_e32 v182, v182, v219
	v_sub_f32_e32 v184, v184, v219
	v_pk_mul_f32 v[180:181], v[218:219], v[180:181] op_sel_hi:[0,1]
	v_pk_mul_f32 v[178:179], v[218:219], v[178:179] op_sel_hi:[0,1]
	v_pk_mul_f32 v[184:185], v[218:219], v[184:185] op_sel_hi:[0,1]
	v_pk_mul_f32 v[182:183], v[218:219], v[182:183] op_sel_hi:[0,1]
	v_pk_fma_f32 v[178:179], v[136:137], v[178:179], v[140:141]
	v_pk_fma_f32 v[180:181], v[138:139], v[180:181], v[142:143]
	v_pk_fma_f32 v[230:231], v[128:129], v[182:183], v[132:133]
	v_pk_fma_f32 v[232:233], v[130:131], v[184:185], v[134:135]
	v_pk_fma_f32 v[182:183], v[180:181], s[34:35], v[78:79] op_sel_hi:[1,0,1]
	v_pk_fma_f32 v[184:185], v[178:179], s[34:35], v[76:77] op_sel_hi:[1,0,1]
	v_pk_fma_f32 v[178:179], v[232:233], s[34:35], v[74:75] op_sel_hi:[1,0,1]
	v_pk_fma_f32 v[180:181], v[230:231], s[34:35], v[72:73] op_sel_hi:[1,0,1]
	v_cvt_pk_bf16_f32 v72, v184, v185
	v_cvt_pk_bf16_f32 v73, v182, v183
	v_cvt_pk_bf16_f32 v74, v180, v181
	v_cvt_pk_bf16_f32 v75, v178, v179
	global_store_dwordx4 v[214:215], v[72:75], off
	s_nop 0
	v_fma_f32 v76, -v203, v203, v202
	v_max_f32_e32 v76, 0, v76
	v_add_f32_e32 v76, 0x3727c5ac, v76
	v_mul_f32_e32 v77, 0x4f800000, v76
	v_cmp_gt_f32_e32 vcc, s63, v76
	s_waitcnt vmcnt(1)
	v_lshlrev_b32_e32 v231, 16, v243
	v_cndmask_b32_e32 v76, v76, v77, vcc
	v_sqrt_f32_e32 v77, v76
	v_and_b32_e32 v232, 0xffff0000, v243
	v_add_u32_e32 v78, -1, v77
	v_add_u32_e32 v79, 1, v77
	v_fma_f32 v202, -v78, v77, v76
	v_fma_f32 v230, -v79, v77, v76
	v_cmp_ge_f32_e64 s[0:1], 0, v202
	s_nop 1
	v_cndmask_b32_e64 v77, v77, v78, s[0:1]
	v_cmp_lt_f32_e64 s[0:1], 0, v230
	s_nop 1
	v_cndmask_b32_e64 v77, v77, v79, s[0:1]
	v_mul_f32_e32 v78, 0x37800000, v77
	v_cndmask_b32_e32 v77, v77, v78, vcc
	v_cmp_class_f32_e32 vcc, v76, v229
	s_nop 1
	v_cndmask_b32_e32 v76, v77, v76, vcc
	v_div_scale_f32 v77, s[0:1], v76, v76, 1.0
	v_rcp_f32_e32 v78, v77
	v_div_scale_f32 v79, vcc, 1.0, v76, 1.0
	v_fma_f32 v202, -v77, v78, 1.0
	v_fmac_f32_e32 v78, v202, v78
	v_mul_f32_e32 v202, v79, v78
	v_fma_f32 v230, -v77, v202, v79
	v_fmac_f32_e32 v202, v230, v78
	v_fma_f32 v77, -v77, v202, v79
	v_div_fmas_f32 v77, v77, v78, v202
	v_div_fixup_f32 v202, v77, v76, 1.0
	v_lshlrev_b32_e32 v76, 16, v240
	v_and_b32_e32 v72, 0xffff0000, v240
	v_lshlrev_b32_e32 v77, 16, v241
	v_and_b32_e32 v78, 0xffff0000, v241
	v_lshlrev_b32_e32 v79, 16, v242
	v_and_b32_e32 v230, 0xffff0000, v242
	v_sub_f32_e32 v73, v72, v203
	v_sub_f32_e32 v72, v76, v203
	v_sub_f32_e32 v75, v78, v203
	v_sub_f32_e32 v74, v77, v203
	v_sub_f32_e32 v77, v230, v203
	v_sub_f32_e32 v76, v79, v203
	v_sub_f32_e32 v79, v232, v203
	v_sub_f32_e32 v78, v231, v203
	v_pk_mul_f32 v[74:75], v[202:203], v[74:75] op_sel_hi:[0,1]
	v_pk_mul_f32 v[72:73], v[202:203], v[72:73] op_sel_hi:[0,1]
	v_pk_mul_f32 v[78:79], v[202:203], v[78:79] op_sel_hi:[0,1]
	v_pk_mul_f32 v[76:77], v[202:203], v[76:77] op_sel_hi:[0,1]
	v_pk_fma_f32 v[72:73], v[136:137], v[72:73], v[140:141]
	v_pk_fma_f32 v[74:75], v[138:139], v[74:75], v[142:143]
	v_pk_fma_f32 v[76:77], v[128:129], v[76:77], v[132:133]
	v_pk_fma_f32 v[78:79], v[130:131], v[78:79], v[134:135]
	v_pk_fma_f32 v[130:131], v[74:75], s[34:35], v[70:71] op_sel_hi:[1,0,1]
	v_pk_fma_f32 v[134:135], v[72:73], s[34:35], v[68:69] op_sel_hi:[1,0,1]
	v_pk_fma_f32 v[128:129], v[78:79], s[34:35], v[66:67] op_sel_hi:[1,0,1]
	v_pk_fma_f32 v[132:133], v[76:77], s[34:35], v[64:65] op_sel_hi:[1,0,1]
	v_cvt_pk_bf16_f32 v64, v134, v135
	v_cvt_pk_bf16_f32 v65, v130, v131
	v_cvt_pk_bf16_f32 v66, v132, v133
	v_cvt_pk_bf16_f32 v67, v128, v129
	global_store_dwordx4 v[212:213], v[64:67], off
	global_load_dwordx4 v[136:139], v[176:177], off offset:256
	global_load_dwordx4 v[68:71], v[190:191], off offset:512
	global_load_dwordx4 v[72:75], v[188:189], off offset:512
	global_load_dwordx4 v[64:67], v[188:189], off offset:528
	global_load_dwordx4 v[76:79], v[190:191], off offset:528
	s_waitcnt vmcnt(0)
	v_lshlrev_b32_e32 v140, 16, v136
	v_and_b32_e32 v136, 0xffff0000, v136
	v_lshlrev_b32_e32 v141, 16, v137
	v_and_b32_e32 v142, 0xffff0000, v137
	v_lshlrev_b32_e32 v143, 16, v138
	v_and_b32_e32 v188, 0xffff0000, v138
	v_lshlrev_b32_e32 v189, 16, v139
	v_and_b32_e32 v190, 0xffff0000, v139
	v_sub_f32_e32 v137, v136, v187
	v_sub_f32_e32 v136, v140, v187
	v_sub_f32_e32 v139, v142, v187
	v_sub_f32_e32 v138, v141, v187
	v_sub_f32_e32 v141, v188, v187
	v_sub_f32_e32 v140, v143, v187
	v_sub_f32_e32 v143, v190, v187
	v_sub_f32_e32 v142, v189, v187
	v_pk_mul_f32 v[138:139], v[186:187], v[138:139] op_sel_hi:[0,1]
	v_pk_mul_f32 v[136:137], v[186:187], v[136:137] op_sel_hi:[0,1]
	v_pk_mul_f32 v[142:143], v[186:187], v[142:143] op_sel_hi:[0,1]
	v_pk_mul_f32 v[140:141], v[186:187], v[140:141] op_sel_hi:[0,1]
	v_pk_fma_f32 v[136:137], v[72:73], v[136:137], v[68:69]
	v_pk_fma_f32 v[138:139], v[74:75], v[138:139], v[70:71]
	v_pk_fma_f32 v[140:141], v[64:65], v[140:141], v[76:77]
	v_pk_fma_f32 v[142:143], v[66:67], v[142:143], v[78:79]
	v_pk_fma_f32 v[62:63], v[138:139], s[34:35], v[62:63] op_sel_hi:[1,0,1]
	v_pk_fma_f32 v[60:61], v[136:137], s[34:35], v[60:61] op_sel_hi:[1,0,1]
	v_pk_fma_f32 v[58:59], v[142:143], s[34:35], v[58:59] op_sel_hi:[1,0,1]
	v_pk_fma_f32 v[56:57], v[140:141], s[34:35], v[56:57] op_sel_hi:[1,0,1]
	v_cvt_pk_bf16_f32 v136, v60, v61
	v_cvt_pk_bf16_f32 v137, v62, v63
	v_cvt_pk_bf16_f32 v138, v56, v57
	v_cvt_pk_bf16_f32 v139, v58, v59
	global_store_dwordx4 v[176:177], v[136:139], off offset:256
	global_load_dwordx4 v[240:243], v[192:193], off offset:256
	global_load_dwordx4 v[244:247], v[194:195], off offset:256
	s_waitcnt vmcnt(1)
	v_lshlrev_b32_e32 v140, 16, v240
	v_and_b32_e32 v136, 0xffff0000, v240
	v_lshlrev_b32_e32 v141, 16, v241
	v_and_b32_e32 v142, 0xffff0000, v241
	v_lshlrev_b32_e32 v143, 16, v242
	v_and_b32_e32 v176, 0xffff0000, v242
	v_lshlrev_b32_e32 v177, 16, v243
	v_and_b32_e32 v186, 0xffff0000, v243
	v_sub_f32_e32 v137, v136, v197
	v_sub_f32_e32 v136, v140, v197
	v_sub_f32_e32 v139, v142, v197
	v_sub_f32_e32 v138, v141, v197
	v_sub_f32_e32 v141, v176, v197
	v_sub_f32_e32 v140, v143, v197
	v_sub_f32_e32 v143, v186, v197
	v_sub_f32_e32 v142, v177, v197
	v_pk_mul_f32 v[138:139], v[196:197], v[138:139] op_sel_hi:[0,1]
	v_pk_mul_f32 v[136:137], v[196:197], v[136:137] op_sel_hi:[0,1]
	v_pk_mul_f32 v[142:143], v[196:197], v[142:143] op_sel_hi:[0,1]
	v_pk_mul_f32 v[140:141], v[196:197], v[140:141] op_sel_hi:[0,1]
	v_pk_fma_f32 v[136:137], v[72:73], v[136:137], v[68:69]
	v_pk_fma_f32 v[138:139], v[74:75], v[138:139], v[70:71]
	v_pk_fma_f32 v[140:141], v[64:65], v[140:141], v[76:77]
	v_pk_fma_f32 v[142:143], v[66:67], v[142:143], v[78:79]
	v_pk_fma_f32 v[54:55], v[138:139], s[34:35], v[54:55] op_sel_hi:[1,0,1]
	v_pk_fma_f32 v[52:53], v[136:137], s[34:35], v[52:53] op_sel_hi:[1,0,1]
	v_pk_fma_f32 v[50:51], v[142:143], s[34:35], v[50:51] op_sel_hi:[1,0,1]
	v_pk_fma_f32 v[48:49], v[140:141], s[34:35], v[48:49] op_sel_hi:[1,0,1]
	v_cvt_pk_bf16_f32 v136, v52, v53
	v_cvt_pk_bf16_f32 v137, v54, v55
	v_cvt_pk_bf16_f32 v138, v48, v49
	v_cvt_pk_bf16_f32 v139, v50, v51
	global_store_dwordx4 v[192:193], v[136:139], off offset:256
	s_nop 0
	global_load_dwordx4 v[240:243], v[198:199], off offset:256
	s_waitcnt vmcnt(2)
	v_lshlrev_b32_e32 v140, 16, v244
	v_and_b32_e32 v136, 0xffff0000, v244
	v_lshlrev_b32_e32 v141, 16, v245
	v_and_b32_e32 v142, 0xffff0000, v245
	v_lshlrev_b32_e32 v143, 16, v246
	v_and_b32_e32 v176, 0xffff0000, v246
	v_lshlrev_b32_e32 v177, 16, v247
	v_and_b32_e32 v186, 0xffff0000, v247
	v_sub_f32_e32 v137, v136, v201
	v_sub_f32_e32 v136, v140, v201
	v_sub_f32_e32 v139, v142, v201
	v_sub_f32_e32 v138, v141, v201
	v_sub_f32_e32 v141, v176, v201
	v_sub_f32_e32 v140, v143, v201
	v_sub_f32_e32 v143, v186, v201
	v_sub_f32_e32 v142, v177, v201
	v_pk_mul_f32 v[138:139], v[200:201], v[138:139] op_sel_hi:[0,1]
	v_pk_mul_f32 v[136:137], v[200:201], v[136:137] op_sel_hi:[0,1]
	v_pk_mul_f32 v[142:143], v[200:201], v[142:143] op_sel_hi:[0,1]
	v_pk_mul_f32 v[140:141], v[200:201], v[140:141] op_sel_hi:[0,1]
	v_pk_fma_f32 v[136:137], v[72:73], v[136:137], v[68:69]
	v_pk_fma_f32 v[138:139], v[74:75], v[138:139], v[70:71]
	v_pk_fma_f32 v[140:141], v[64:65], v[140:141], v[76:77]
	v_pk_fma_f32 v[142:143], v[66:67], v[142:143], v[78:79]
	v_pk_fma_f32 v[46:47], v[138:139], s[34:35], v[46:47] op_sel_hi:[1,0,1]
	v_pk_fma_f32 v[44:45], v[136:137], s[34:35], v[44:45] op_sel_hi:[1,0,1]
	v_pk_fma_f32 v[42:43], v[142:143], s[34:35], v[42:43] op_sel_hi:[1,0,1]
	v_pk_fma_f32 v[40:41], v[140:141], s[34:35], v[40:41] op_sel_hi:[1,0,1]
	v_cvt_pk_bf16_f32 v136, v44, v45
	v_cvt_pk_bf16_f32 v137, v46, v47
	v_cvt_pk_bf16_f32 v138, v40, v41
	v_cvt_pk_bf16_f32 v139, v42, v43
	global_store_dwordx4 v[194:195], v[136:139], off offset:256
	s_nop 0
	global_load_dwordx4 v[244:247], v[204:205], off offset:256
	s_waitcnt vmcnt(2)
	v_lshlrev_b32_e32 v140, 16, v240
	v_and_b32_e32 v136, 0xffff0000, v240
	v_lshlrev_b32_e32 v141, 16, v241
	v_and_b32_e32 v142, 0xffff0000, v241
	v_lshlrev_b32_e32 v143, 16, v242
	v_and_b32_e32 v176, 0xffff0000, v242
	v_lshlrev_b32_e32 v177, 16, v243
	v_and_b32_e32 v186, 0xffff0000, v243
	v_sub_f32_e32 v137, v136, v207
	v_sub_f32_e32 v136, v140, v207
	v_sub_f32_e32 v139, v142, v207
	v_sub_f32_e32 v138, v141, v207
	v_sub_f32_e32 v141, v176, v207
	v_sub_f32_e32 v140, v143, v207
	v_sub_f32_e32 v143, v186, v207
	v_sub_f32_e32 v142, v177, v207
	v_pk_mul_f32 v[138:139], v[206:207], v[138:139] op_sel_hi:[0,1]
	v_pk_mul_f32 v[136:137], v[206:207], v[136:137] op_sel_hi:[0,1]
	v_pk_mul_f32 v[142:143], v[206:207], v[142:143] op_sel_hi:[0,1]
	v_pk_mul_f32 v[140:141], v[206:207], v[140:141] op_sel_hi:[0,1]
	v_pk_fma_f32 v[136:137], v[72:73], v[136:137], v[68:69]
	v_pk_fma_f32 v[138:139], v[74:75], v[138:139], v[70:71]
	v_pk_fma_f32 v[140:141], v[64:65], v[140:141], v[76:77]
	v_pk_fma_f32 v[142:143], v[66:67], v[142:143], v[78:79]
	v_pk_fma_f32 v[38:39], v[138:139], s[34:35], v[38:39] op_sel_hi:[1,0,1]
	v_pk_fma_f32 v[36:37], v[136:137], s[34:35], v[36:37] op_sel_hi:[1,0,1]
	v_pk_fma_f32 v[34:35], v[142:143], s[34:35], v[34:35] op_sel_hi:[1,0,1]
	v_pk_fma_f32 v[32:33], v[140:141], s[34:35], v[32:33] op_sel_hi:[1,0,1]
	v_cvt_pk_bf16_f32 v136, v36, v37
	v_cvt_pk_bf16_f32 v137, v38, v39
	v_cvt_pk_bf16_f32 v138, v32, v33
	v_cvt_pk_bf16_f32 v139, v34, v35
	global_store_dwordx4 v[198:199], v[136:139], off offset:256
	s_nop 0
	global_load_dwordx4 v[240:243], v[208:209], off offset:256
	s_waitcnt vmcnt(2)
	v_lshlrev_b32_e32 v140, 16, v244
	v_and_b32_e32 v136, 0xffff0000, v244
	v_lshlrev_b32_e32 v141, 16, v245
	v_and_b32_e32 v142, 0xffff0000, v245
	v_lshlrev_b32_e32 v143, 16, v246
	v_and_b32_e32 v176, 0xffff0000, v246
	v_lshlrev_b32_e32 v177, 16, v247
	v_and_b32_e32 v186, 0xffff0000, v247
	v_sub_f32_e32 v137, v136, v211
	v_sub_f32_e32 v136, v140, v211
	v_sub_f32_e32 v139, v142, v211
	v_sub_f32_e32 v138, v141, v211
	v_sub_f32_e32 v141, v176, v211
	v_sub_f32_e32 v140, v143, v211
	v_sub_f32_e32 v143, v186, v211
	v_sub_f32_e32 v142, v177, v211
	v_pk_mul_f32 v[138:139], v[210:211], v[138:139] op_sel_hi:[0,1]
	v_pk_mul_f32 v[136:137], v[210:211], v[136:137] op_sel_hi:[0,1]
	v_pk_mul_f32 v[142:143], v[210:211], v[142:143] op_sel_hi:[0,1]
	v_pk_mul_f32 v[140:141], v[210:211], v[140:141] op_sel_hi:[0,1]
	v_pk_fma_f32 v[136:137], v[72:73], v[136:137], v[68:69]
	v_pk_fma_f32 v[138:139], v[74:75], v[138:139], v[70:71]
	v_pk_fma_f32 v[140:141], v[64:65], v[140:141], v[76:77]
	v_pk_fma_f32 v[142:143], v[66:67], v[142:143], v[78:79]
	v_pk_fma_f32 v[30:31], v[138:139], s[34:35], v[30:31] op_sel_hi:[1,0,1]
	v_pk_fma_f32 v[28:29], v[136:137], s[34:35], v[28:29] op_sel_hi:[1,0,1]
	v_pk_fma_f32 v[26:27], v[142:143], s[34:35], v[26:27] op_sel_hi:[1,0,1]
	v_pk_fma_f32 v[24:25], v[140:141], s[34:35], v[24:25] op_sel_hi:[1,0,1]
	v_cvt_pk_bf16_f32 v136, v28, v29
	v_cvt_pk_bf16_f32 v137, v30, v31
	v_cvt_pk_bf16_f32 v138, v24, v25
	v_cvt_pk_bf16_f32 v139, v26, v27
	global_store_dwordx4 v[204:205], v[136:139], off offset:256
	s_nop 0
	global_load_dwordx4 v[244:247], v[214:215], off offset:256
	s_waitcnt vmcnt(2)
	v_lshlrev_b32_e32 v140, 16, v240
	v_and_b32_e32 v136, 0xffff0000, v240
	v_lshlrev_b32_e32 v141, 16, v241
	v_and_b32_e32 v142, 0xffff0000, v241
	v_lshlrev_b32_e32 v143, 16, v242
	v_and_b32_e32 v176, 0xffff0000, v242
	v_lshlrev_b32_e32 v177, 16, v243
	v_and_b32_e32 v186, 0xffff0000, v243
	v_sub_f32_e32 v137, v136, v217
	v_sub_f32_e32 v136, v140, v217
	v_sub_f32_e32 v139, v142, v217
	v_sub_f32_e32 v138, v141, v217
	v_sub_f32_e32 v141, v176, v217
	v_sub_f32_e32 v140, v143, v217
	v_sub_f32_e32 v143, v186, v217
	v_sub_f32_e32 v142, v177, v217
	v_pk_mul_f32 v[138:139], v[216:217], v[138:139] op_sel_hi:[0,1]
	v_pk_mul_f32 v[136:137], v[216:217], v[136:137] op_sel_hi:[0,1]
	v_pk_mul_f32 v[142:143], v[216:217], v[142:143] op_sel_hi:[0,1]
	v_pk_mul_f32 v[140:141], v[216:217], v[140:141] op_sel_hi:[0,1]
	v_pk_fma_f32 v[136:137], v[72:73], v[136:137], v[68:69]
	v_pk_fma_f32 v[138:139], v[74:75], v[138:139], v[70:71]
	v_pk_fma_f32 v[140:141], v[64:65], v[140:141], v[76:77]
	v_pk_fma_f32 v[142:143], v[66:67], v[142:143], v[78:79]
	v_pk_fma_f32 v[22:23], v[138:139], s[34:35], v[22:23] op_sel_hi:[1,0,1]
	v_pk_fma_f32 v[20:21], v[136:137], s[34:35], v[20:21] op_sel_hi:[1,0,1]
	v_pk_fma_f32 v[18:19], v[142:143], s[34:35], v[18:19] op_sel_hi:[1,0,1]
	v_pk_fma_f32 v[16:17], v[140:141], s[34:35], v[16:17] op_sel_hi:[1,0,1]
	v_cvt_pk_bf16_f32 v136, v20, v21
	v_cvt_pk_bf16_f32 v137, v22, v23
	v_cvt_pk_bf16_f32 v138, v16, v17
	v_cvt_pk_bf16_f32 v139, v18, v19
	global_store_dwordx4 v[208:209], v[136:139], off offset:256
	s_nop 0
	global_load_dwordx4 v[240:243], v[212:213], off offset:256
	s_waitcnt vmcnt(2)
	v_lshlrev_b32_e32 v140, 16, v244
	v_and_b32_e32 v136, 0xffff0000, v244
	v_lshlrev_b32_e32 v141, 16, v245
	v_and_b32_e32 v142, 0xffff0000, v245
	v_lshlrev_b32_e32 v143, 16, v246
	v_and_b32_e32 v176, 0xffff0000, v246
	v_lshlrev_b32_e32 v177, 16, v247
	v_and_b32_e32 v186, 0xffff0000, v247
	v_sub_f32_e32 v137, v136, v219
	v_sub_f32_e32 v136, v140, v219
	v_sub_f32_e32 v139, v142, v219
	v_sub_f32_e32 v138, v141, v219
	v_sub_f32_e32 v141, v176, v219
	v_sub_f32_e32 v140, v143, v219
	v_sub_f32_e32 v143, v186, v219
	v_sub_f32_e32 v142, v177, v219
	v_pk_mul_f32 v[138:139], v[218:219], v[138:139] op_sel_hi:[0,1]
	v_pk_mul_f32 v[136:137], v[218:219], v[136:137] op_sel_hi:[0,1]
	v_pk_mul_f32 v[142:143], v[218:219], v[142:143] op_sel_hi:[0,1]
	v_pk_mul_f32 v[140:141], v[218:219], v[140:141] op_sel_hi:[0,1]
	v_pk_fma_f32 v[136:137], v[72:73], v[136:137], v[68:69]
	v_pk_fma_f32 v[138:139], v[74:75], v[138:139], v[70:71]
	v_pk_fma_f32 v[140:141], v[64:65], v[140:141], v[76:77]
	v_pk_fma_f32 v[142:143], v[66:67], v[142:143], v[78:79]
	v_pk_fma_f32 v[14:15], v[138:139], s[34:35], v[14:15] op_sel_hi:[1,0,1]
	v_pk_fma_f32 v[12:13], v[136:137], s[34:35], v[12:13] op_sel_hi:[1,0,1]
	v_pk_fma_f32 v[10:11], v[142:143], s[34:35], v[10:11] op_sel_hi:[1,0,1]
	v_pk_fma_f32 v[8:9], v[140:141], s[34:35], v[8:9] op_sel_hi:[1,0,1]
	v_cvt_pk_bf16_f32 v136, v12, v13
	v_cvt_pk_bf16_f32 v137, v14, v15
	v_cvt_pk_bf16_f32 v138, v8, v9
	v_cvt_pk_bf16_f32 v139, v10, v11
	global_store_dwordx4 v[214:215], v[136:139], off offset:256
	s_nop 0
	v_add_f32_e32 v140, v124, v125
	v_add_f32_e32 v141, v126, v127
	v_add_f32_e32 v142, v120, v121
	v_add_f32_e32 v143, v122, v123
	v_mul_f32_e32 v125, v125, v125
	v_mul_f32_e32 v127, v127, v127
	v_mul_f32_e32 v121, v121, v121
	v_mul_f32_e32 v123, v123, v123
	v_fmac_f32_e32 v125, v124, v124
	v_fmac_f32_e32 v127, v126, v126
	v_fmac_f32_e32 v121, v120, v120
	v_fmac_f32_e32 v123, v122, v122
	v_add_f32_e32 v122, v125, v127
	v_add_f32_e32 v121, v121, v123
	v_add_f32_e32 v121, v122, v121
	v_add_f32_e32 v122, v60, v61
	v_add_f32_e32 v123, v62, v63
	v_add_f32_e32 v124, v56, v57
	v_add_f32_e32 v125, v58, v59
	v_mul_f32_e32 v61, v61, v61
	v_mul_f32_e32 v63, v63, v63
	v_mul_f32_e32 v57, v57, v57
	v_mul_f32_e32 v59, v59, v59
	v_add_f32_e32 v140, v140, v141
	v_add_f32_e32 v141, v142, v143
	v_fmac_f32_e32 v61, v60, v60
	v_fmac_f32_e32 v63, v62, v62
	v_fmac_f32_e32 v57, v56, v56
	v_fmac_f32_e32 v59, v58, v58
	v_add_f32_e32 v120, v140, v141
	v_add_f32_e32 v122, v122, v123
	v_add_f32_e32 v123, v124, v125
	v_add_f32_e32 v58, v61, v63
	v_add_f32_e32 v57, v57, v59
	v_add_f32_e32 v120, 0, v120
	v_add_f32_e32 v56, v122, v123
	v_add_f32_e32 v57, v58, v57
	v_add_f32_e32 v56, v120, v56
	v_add_f32_e32 v59, v121, v57
	ds_bpermute_b32 v58, v222, v56
	ds_bpermute_b32 v60, v222, v59
	s_waitcnt lgkmcnt(0)
	v_add_f32_e32 v56, v56, v58
	v_add_f32_e32 v58, v59, v60
	ds_bpermute_b32 v57, v221, v56
	s_waitcnt vmcnt(1)
	v_lshlrev_b32_e32 v59, 16, v240
	v_and_b32_e32 v60, 0xffff0000, v240
	v_lshlrev_b32_e32 v62, 16, v241
	v_and_b32_e32 v63, 0xffff0000, v241
	v_lshlrev_b32_e32 v120, 16, v242
	v_and_b32_e32 v121, 0xffff0000, v242
	v_lshlrev_b32_e32 v122, 16, v243
	v_and_b32_e32 v123, 0xffff0000, v243
	v_sub_f32_e32 v61, v60, v203
	v_sub_f32_e32 v60, v59, v203
	v_sub_f32_e32 v63, v63, v203
	v_sub_f32_e32 v62, v62, v203
	v_sub_f32_e32 v121, v121, v203
	v_sub_f32_e32 v120, v120, v203
	v_sub_f32_e32 v123, v123, v203
	v_sub_f32_e32 v122, v122, v203
	v_pk_mul_f32 v[62:63], v[202:203], v[62:63] op_sel_hi:[0,1]
	v_pk_mul_f32 v[60:61], v[202:203], v[60:61] op_sel_hi:[0,1]
	v_pk_mul_f32 v[122:123], v[202:203], v[122:123] op_sel_hi:[0,1]
	v_pk_mul_f32 v[120:121], v[202:203], v[120:121] op_sel_hi:[0,1]
	v_pk_fma_f32 v[60:61], v[72:73], v[60:61], v[68:69]
	v_pk_fma_f32 v[62:63], v[74:75], v[62:63], v[70:71]
	v_pk_fma_f32 v[64:65], v[64:65], v[120:121], v[76:77]
	v_pk_fma_f32 v[66:67], v[66:67], v[122:123], v[78:79]
	v_pk_fma_f32 v[6:7], v[62:63], s[34:35], v[6:7] op_sel_hi:[1,0,1]
	v_pk_fma_f32 v[4:5], v[60:61], s[34:35], v[4:5] op_sel_hi:[1,0,1]
	v_pk_fma_f32 v[2:3], v[66:67], s[34:35], v[2:3] op_sel_hi:[1,0,1]
	v_pk_fma_f32 v[0:1], v[64:65], s[34:35], v[0:1] op_sel_hi:[1,0,1]
	v_cvt_pk_bf16_f32 v60, v4, v5
	v_cvt_pk_bf16_f32 v61, v6, v7
	v_cvt_pk_bf16_f32 v62, v0, v1
	v_cvt_pk_bf16_f32 v63, v2, v3
	ds_bpermute_b32 v59, v221, v58
	global_store_dwordx4 v[212:213], v[60:63], off offset:256
	s_and_saveexec_b64 s[0:1], s[6:7]
	s_cbranch_execz .LBB0_1297
	s_waitcnt lgkmcnt(0)
	v_add_f32_e32 v58, v58, v59
	v_add_f32_e32 v59, v56, v57
	v_lshl_add_u64 v[56:57], s[18:19], 0, v[164:165]
	global_atomic_add_f32 v[56:57], v59, off
	global_atomic_add_f32 v[56:57], v58, off offset:4

.LBB0_1475:
	v_lshl_add_u32 v128, s77, 8, v218
	v_ashrrev_i32_e32 v129, 31, v128
	v_lshlrev_b64 v[164:165], 3, v[128:129]
	v_lshl_add_u64 v[130:131], s[18:19], 0, v[164:165]
	v_lshl_or_b32 v186, s76, 8, v223
	global_load_dwordx2 v[188:189], v[130:131], off
	v_ashrrev_i32_e32 v187, 31, v186
	v_lshlrev_b64 v[130:131], 12, v[128:129]
	v_lshl_add_u64 v[130:131], s[16:17], 0, v[130:131]
	v_lshlrev_b64 v[178:179], 1, v[186:187]
	v_lshl_add_u64 v[176:177], v[130:131], 0, v[178:179]
	global_load_dwordx4 v[190:193], v[176:177], off
	v_or_b32_e32 v194, 16, v128
	v_or_b32_e32 v216, 32, v128
	v_or_b32_e32 v196, 48, v128
	v_add_u32_e32 v202, 0x80, v128
	v_add_u32_e32 v206, 0x90, v128
	v_add_u32_e32 v184, 0xa0, v128
	v_add_u32_e32 v180, 0xb0, v128
	v_lshlrev_b64 v[128:129], 2, v[186:187]
	v_lshl_add_u64 v[132:133], s[14:15], 0, v[128:129]
	v_lshl_add_u64 v[140:141], s[20:21], 0, v[128:129]
	global_load_dwordx4 v[128:131], v[132:133], off offset:16
	global_load_dwordx4 v[136:139], v[132:133], off
	s_nop 0
	global_load_dwordx4 v[132:135], v[140:141], off offset:16
	s_nop 0
	global_load_dwordx4 v[140:143], v[140:141], off
	v_ashrrev_i32_e32 v195, 31, v194
	v_ashrrev_i32_e32 v217, 31, v216
	v_ashrrev_i32_e32 v197, 31, v196
	v_ashrrev_i32_e32 v203, 31, v202
	v_ashrrev_i32_e32 v207, 31, v206
	v_ashrrev_i32_e32 v185, 31, v184
	v_ashrrev_i32_e32 v181, 31, v180
	v_lshlrev_b64 v[174:175], 3, v[194:195]
	v_lshlrev_b64 v[172:173], 3, v[216:217]
	v_lshlrev_b64 v[170:171], 3, v[196:197]
	v_lshlrev_b64 v[168:169], 3, v[202:203]
	v_lshlrev_b64 v[166:167], 3, v[206:207]
	v_lshlrev_b64 v[162:163], 3, v[184:185]
	v_lshlrev_b64 v[160:161], 3, v[180:181]
	v_lshl_add_u64 v[182:183], s[18:19], 0, v[174:175]
	v_lshl_add_u64 v[198:199], s[18:19], 0, v[172:173]
	v_lshl_add_u64 v[200:201], s[18:19], 0, v[170:171]
	v_lshl_add_u64 v[208:209], s[18:19], 0, v[168:169]
	v_lshl_add_u64 v[210:211], s[18:19], 0, v[166:167]
	v_lshl_add_u64 v[212:213], s[18:19], 0, v[162:163]
	v_lshl_add_u64 v[214:215], s[18:19], 0, v[160:161]
	global_load_dwordx2 v[228:229], v[182:183], off
	s_nop 0
	global_load_dwordx2 v[198:199], v[198:199], off
	s_nop 0
	global_load_dwordx2 v[204:205], v[200:201], off
	s_nop 0
	global_load_dwordx2 v[208:209], v[208:209], off
	s_nop 0
	global_load_dwordx2 v[210:211], v[210:211], off
	s_nop 0
	global_load_dwordx2 v[182:183], v[212:213], off
	global_load_dwordx2 v[200:201], v[214:215], off
	v_lshlrev_b64 v[196:197], 12, v[196:197]
	v_lshl_add_u64 v[196:197], s[16:17], 0, v[196:197]
	v_lshl_add_u64 v[196:197], v[196:197], 0, v[178:179]
	v_lshlrev_b64 v[202:203], 12, v[202:203]
	v_lshl_add_u64 v[202:203], s[16:17], 0, v[202:203]
	v_lshl_add_u64 v[202:203], v[202:203], 0, v[178:179]
	v_lshlrev_b64 v[206:207], 12, v[206:207]
	v_lshl_add_u64 v[206:207], s[16:17], 0, v[206:207]
	v_lshl_add_u64 v[206:207], v[206:207], 0, v[178:179]
	v_lshlrev_b64 v[184:185], 12, v[184:185]
	v_lshl_add_u64 v[184:185], s[16:17], 0, v[184:185]
	v_lshlrev_b64 v[180:181], 12, v[180:181]
	v_lshl_add_u64 v[180:181], s[16:17], 0, v[180:181]
	s_waitcnt vmcnt(0)
	v_pk_mul_f32 v[188:189], v[188:189], s[30:31] op_sel:[1,0] op_sel_hi:[0,0]
	v_fma_f32 v187, -v189, v189, v188
	v_max_f32_e32 v187, 0, v187
	v_add_f32_e32 v187, 0x3727c5ac, v187
	v_cmp_gt_f32_e32 vcc, s61, v187
	v_lshlrev_b32_e32 v188, 16, v190
	v_and_b32_e32 v190, 0xffff0000, v190
	v_lshlrev_b32_e32 v212, 16, v191
	v_and_b32_e32 v213, 0xffff0000, v191
	v_sub_f32_e32 v191, v190, v189
	v_sub_f32_e32 v190, v188, v189
	v_mul_f32_e32 v188, 0x4f800000, v187
	v_cndmask_b32_e32 v187, v187, v188, vcc
	v_sqrt_f32_e32 v188, v187
	v_lshlrev_b32_e32 v214, 16, v192
	v_and_b32_e32 v215, 0xffff0000, v192
	v_and_b32_e32 v231, 0xffff0000, v193
	v_sub_f32_e32 v192, v212, v189
	v_sub_f32_e32 v212, v214, v189
	v_add_u32_e32 v214, -1, v188
	v_lshlrev_b32_e32 v230, 16, v193
	v_sub_f32_e32 v193, v213, v189
	v_sub_f32_e32 v213, v215, v189
	v_sub_f32_e32 v215, v231, v189
	v_add_u32_e32 v231, 1, v188
	v_fma_f32 v232, -v214, v188, v187
	v_fma_f32 v233, -v231, v188, v187
	v_cmp_ge_f32_e64 s[0:1], 0, v232
	v_pk_mul_f32 v[198:199], v[198:199], s[30:31] op_sel:[1,0] op_sel_hi:[0,0]
	s_nop 0
	v_cndmask_b32_e64 v188, v188, v214, s[0:1]
	v_cmp_lt_f32_e64 s[0:1], 0, v233
	v_pk_mul_f32 v[204:205], v[204:205], s[30:31] op_sel:[1,0] op_sel_hi:[0,0]
	v_pk_mul_f32 v[208:209], v[208:209], s[30:31] op_sel:[1,0] op_sel_hi:[0,0]
	v_cndmask_b32_e64 v188, v188, v231, s[0:1]
	v_mul_f32_e32 v214, 0x37800000, v188
	v_cndmask_b32_e32 v188, v188, v214, vcc
	v_cmp_class_f32_e32 vcc, v187, v227
	v_sub_f32_e32 v214, v230, v189
	v_pk_mul_f32 v[200:201], v[200:201], s[30:31] op_sel:[1,0] op_sel_hi:[0,0]
	v_cndmask_b32_e32 v187, v188, v187, vcc
	v_div_scale_f32 v188, s[0:1], v187, v187, 1.0
	v_rcp_f32_e32 v231, v188
	v_div_scale_f32 v230, vcc, 1.0, v187, 1.0
	v_fma_f32 v232, -v188, v231, 1.0
	v_fmac_f32_e32 v231, v232, v231
	v_mul_f32_e32 v232, v230, v231
	v_fma_f32 v233, -v188, v232, v230
	v_fmac_f32_e32 v232, v233, v231
	v_fma_f32 v188, -v188, v232, v230
	v_div_fmas_f32 v188, v188, v231, v232
	v_div_fixup_f32 v188, v188, v187, 1.0
	v_pk_mul_f32 v[192:193], v[188:189], v[192:193] op_sel_hi:[0,1]
	v_pk_mul_f32 v[190:191], v[188:189], v[190:191] op_sel_hi:[0,1]
	v_pk_mul_f32 v[214:215], v[188:189], v[214:215] op_sel_hi:[0,1]
	v_pk_mul_f32 v[212:213], v[188:189], v[212:213] op_sel_hi:[0,1]
	v_pk_fma_f32 v[190:191], v[136:137], v[190:191], v[140:141]
	v_pk_fma_f32 v[192:193], v[138:139], v[192:193], v[142:143]
	v_pk_fma_f32 v[212:213], v[128:129], v[212:213], v[132:133]
	v_pk_fma_f32 v[214:215], v[130:131], v[214:215], v[134:135]
	v_pk_fma_f32 v[126:127], v[192:193], s[34:35], v[126:127] op_sel_hi:[1,0,1]
	v_pk_fma_f32 v[124:125], v[190:191], s[34:35], v[124:125] op_sel_hi:[1,0,1]
	v_pk_fma_f32 v[122:123], v[214:215], s[34:35], v[122:123] op_sel_hi:[1,0,1]
	v_pk_fma_f32 v[120:121], v[212:213], s[34:35], v[120:121] op_sel_hi:[1,0,1]
	v_cvt_pk_bf16_f32 v190, v124, v125
	v_cvt_pk_bf16_f32 v191, v126, v127
	v_cvt_pk_bf16_f32 v192, v120, v121
	v_cvt_pk_bf16_f32 v193, v122, v123
	global_store_dwordx4 v[176:177], v[190:193], off
	s_nop 1
	v_lshlrev_b64 v[190:191], 12, v[194:195]
	v_lshl_add_u64 v[190:191], s[16:17], 0, v[190:191]
	v_lshl_add_u64 v[190:191], v[190:191], 0, v[178:179]
	global_load_dwordx4 v[240:243], v[190:191], off
	v_pk_mul_f32 v[194:195], v[228:229], s[30:31] op_sel:[1,0] op_sel_hi:[0,0]
	v_fma_f32 v187, -v195, v195, v194
	v_max_f32_e32 v187, 0, v187
	v_add_f32_e32 v187, 0x3727c5ac, v187
	v_mul_f32_e32 v192, 0x4f800000, v187
	v_cmp_gt_f32_e32 vcc, s61, v187
	s_waitcnt vmcnt(0)
	v_lshlrev_b32_e32 v230, 16, v243
	v_cndmask_b32_e32 v187, v187, v192, vcc
	v_sqrt_f32_e32 v194, v187
	v_lshlrev_b64 v[192:193], 12, v[216:217]
	v_and_b32_e32 v231, 0xffff0000, v243
	v_lshl_add_u64 v[192:193], s[16:17], 0, v[192:193]
	v_add_u32_e32 v216, -1, v194
	v_add_u32_e32 v217, 1, v194
	v_fma_f32 v228, -v216, v194, v187
	v_fma_f32 v229, -v217, v194, v187
	v_cmp_ge_f32_e64 s[0:1], 0, v228
	v_lshl_add_u64 v[192:193], v[192:193], 0, v[178:179]
	global_load_dwordx4 v[244:247], v[192:193], off
	s_nop 0
	v_cndmask_b32_e64 v194, v194, v216, s[0:1]
	v_cmp_lt_f32_e64 s[0:1], 0, v229
	s_nop 1
	v_cndmask_b32_e64 v194, v194, v217, s[0:1]
	v_mul_f32_e32 v216, 0x37800000, v194
	v_cndmask_b32_e32 v194, v194, v216, vcc
	v_cmp_class_f32_e32 vcc, v187, v227
	s_nop 1
	v_cndmask_b32_e32 v187, v194, v187, vcc
	v_div_scale_f32 v194, s[0:1], v187, v187, 1.0
	v_rcp_f32_e32 v216, v194
	v_div_scale_f32 v217, vcc, 1.0, v187, 1.0
	v_fma_f32 v228, -v194, v216, 1.0
	v_fmac_f32_e32 v216, v228, v216
	v_mul_f32_e32 v228, v217, v216
	v_fma_f32 v229, -v194, v228, v217
	v_fmac_f32_e32 v228, v229, v216
	v_fma_f32 v194, -v194, v228, v217
	v_div_fmas_f32 v194, v194, v216, v228
	v_div_fixup_f32 v194, v194, v187, 1.0
	v_lshlrev_b32_e32 v187, 16, v240
	v_and_b32_e32 v212, 0xffff0000, v240
	v_lshlrev_b32_e32 v216, 16, v241
	v_and_b32_e32 v217, 0xffff0000, v241
	v_lshlrev_b32_e32 v228, 16, v242
	v_and_b32_e32 v229, 0xffff0000, v242
	v_sub_f32_e32 v213, v212, v195
	v_sub_f32_e32 v212, v187, v195
	v_sub_f32_e32 v215, v217, v195
	v_sub_f32_e32 v214, v216, v195
	v_sub_f32_e32 v217, v229, v195
	v_sub_f32_e32 v216, v228, v195
	v_sub_f32_e32 v229, v231, v195
	v_sub_f32_e32 v228, v230, v195
	v_pk_mul_f32 v[214:215], v[194:195], v[214:215] op_sel_hi:[0,1]
	v_pk_mul_f32 v[212:213], v[194:195], v[212:213] op_sel_hi:[0,1]
	v_pk_mul_f32 v[228:229], v[194:195], v[228:229] op_sel_hi:[0,1]
	v_pk_mul_f32 v[216:217], v[194:195], v[216:217] op_sel_hi:[0,1]
	v_pk_fma_f32 v[212:213], v[136:137], v[212:213], v[140:141]
	v_pk_fma_f32 v[214:215], v[138:139], v[214:215], v[142:143]
	v_pk_fma_f32 v[216:217], v[128:129], v[216:217], v[132:133]
	v_pk_fma_f32 v[228:229], v[130:131], v[228:229], v[134:135]
	v_pk_fma_f32 v[118:119], v[214:215], s[34:35], v[118:119] op_sel_hi:[1,0,1]
	v_pk_fma_f32 v[116:117], v[212:213], s[34:35], v[116:117] op_sel_hi:[1,0,1]
	v_pk_fma_f32 v[114:115], v[228:229], s[34:35], v[114:115] op_sel_hi:[1,0,1]
	v_pk_fma_f32 v[112:113], v[216:217], s[34:35], v[112:113] op_sel_hi:[1,0,1]
	v_cvt_pk_bf16_f32 v212, v116, v117
	v_cvt_pk_bf16_f32 v213, v118, v119
	v_cvt_pk_bf16_f32 v214, v112, v113
	v_cvt_pk_bf16_f32 v215, v114, v115
	global_store_dwordx4 v[190:191], v[212:215], off
	s_nop 0
	v_fma_f32 v187, -v199, v199, v198
	v_max_f32_e32 v187, 0, v187
	v_add_f32_e32 v187, 0x3727c5ac, v187
	v_mul_f32_e32 v198, 0x4f800000, v187
	v_cmp_gt_f32_e32 vcc, s61, v187
	global_load_dwordx4 v[240:243], v[196:197], off
	s_waitcnt vmcnt(2)
	v_lshlrev_b32_e32 v230, 16, v247
	v_cndmask_b32_e32 v187, v187, v198, vcc
	v_sqrt_f32_e32 v198, v187
	v_and_b32_e32 v231, 0xffff0000, v247
	v_add_u32_e32 v216, -1, v198
	v_add_u32_e32 v217, 1, v198
	v_fma_f32 v228, -v216, v198, v187
	v_fma_f32 v229, -v217, v198, v187
	v_cmp_ge_f32_e64 s[0:1], 0, v228
	s_nop 1
	v_cndmask_b32_e64 v198, v198, v216, s[0:1]
	v_cmp_lt_f32_e64 s[0:1], 0, v229
	s_nop 1
	v_cndmask_b32_e64 v198, v198, v217, s[0:1]
	v_mul_f32_e32 v216, 0x37800000, v198
	v_cndmask_b32_e32 v198, v198, v216, vcc
	v_cmp_class_f32_e32 vcc, v187, v227
	s_nop 1
	v_cndmask_b32_e32 v187, v198, v187, vcc
	v_div_scale_f32 v198, s[0:1], v187, v187, 1.0
	v_rcp_f32_e32 v216, v198
	v_div_scale_f32 v217, vcc, 1.0, v187, 1.0
	v_fma_f32 v228, -v198, v216, 1.0
	v_fmac_f32_e32 v216, v228, v216
	v_mul_f32_e32 v228, v217, v216
	v_fma_f32 v229, -v198, v228, v217
	v_fmac_f32_e32 v228, v229, v216
	v_fma_f32 v198, -v198, v228, v217
	v_div_fmas_f32 v198, v198, v216, v228
	v_div_fixup_f32 v198, v198, v187, 1.0
	v_lshlrev_b32_e32 v187, 16, v244
	v_and_b32_e32 v212, 0xffff0000, v244
	v_lshlrev_b32_e32 v216, 16, v245
	v_and_b32_e32 v217, 0xffff0000, v245
	v_lshlrev_b32_e32 v228, 16, v246
	v_and_b32_e32 v229, 0xffff0000, v246
	v_sub_f32_e32 v213, v212, v199
	v_sub_f32_e32 v212, v187, v199
	v_sub_f32_e32 v215, v217, v199
	v_sub_f32_e32 v214, v216, v199
	v_sub_f32_e32 v217, v229, v199
	v_sub_f32_e32 v216, v228, v199
	v_sub_f32_e32 v229, v231, v199
	v_sub_f32_e32 v228, v230, v199
	v_pk_mul_f32 v[214:215], v[198:199], v[214:215] op_sel_hi:[0,1]
	v_pk_mul_f32 v[212:213], v[198:199], v[212:213] op_sel_hi:[0,1]
	v_pk_mul_f32 v[228:229], v[198:199], v[228:229] op_sel_hi:[0,1]
	v_pk_mul_f32 v[216:217], v[198:199], v[216:217] op_sel_hi:[0,1]
	v_pk_fma_f32 v[212:213], v[136:137], v[212:213], v[140:141]
	v_pk_fma_f32 v[214:215], v[138:139], v[214:215], v[142:143]
	v_pk_fma_f32 v[216:217], v[128:129], v[216:217], v[132:133]
	v_pk_fma_f32 v[228:229], v[130:131], v[228:229], v[134:135]
	v_pk_fma_f32 v[110:111], v[214:215], s[34:35], v[110:111] op_sel_hi:[1,0,1]
	v_pk_fma_f32 v[108:109], v[212:213], s[34:35], v[108:109] op_sel_hi:[1,0,1]
	v_pk_fma_f32 v[106:107], v[228:229], s[34:35], v[106:107] op_sel_hi:[1,0,1]
	v_pk_fma_f32 v[104:105], v[216:217], s[34:35], v[104:105] op_sel_hi:[1,0,1]
	v_cvt_pk_bf16_f32 v212, v108, v109
	v_cvt_pk_bf16_f32 v213, v110, v111
	v_cvt_pk_bf16_f32 v214, v104, v105
	v_cvt_pk_bf16_f32 v215, v106, v107
	global_store_dwordx4 v[192:193], v[212:215], off
	s_nop 0
	v_fma_f32 v187, -v205, v205, v204
	v_max_f32_e32 v187, 0, v187
	v_add_f32_e32 v187, 0x3727c5ac, v187
	v_mul_f32_e32 v204, 0x4f800000, v187
	v_cmp_gt_f32_e32 vcc, s61, v187
	global_load_dwordx4 v[244:247], v[202:203], off
	s_waitcnt vmcnt(2)
	v_lshlrev_b32_e32 v230, 16, v243
	v_cndmask_b32_e32 v187, v187, v204, vcc
	v_sqrt_f32_e32 v204, v187
	v_and_b32_e32 v231, 0xffff0000, v243
	v_add_u32_e32 v216, -1, v204
	v_add_u32_e32 v217, 1, v204
	v_fma_f32 v228, -v216, v204, v187
	v_fma_f32 v229, -v217, v204, v187
	v_cmp_ge_f32_e64 s[0:1], 0, v228
	s_nop 1
	v_cndmask_b32_e64 v204, v204, v216, s[0:1]
	v_cmp_lt_f32_e64 s[0:1], 0, v229
	s_nop 1
	v_cndmask_b32_e64 v204, v204, v217, s[0:1]
	v_mul_f32_e32 v216, 0x37800000, v204
	v_cndmask_b32_e32 v204, v204, v216, vcc
	v_cmp_class_f32_e32 vcc, v187, v227
	s_nop 1
	v_cndmask_b32_e32 v187, v204, v187, vcc
	v_div_scale_f32 v204, s[0:1], v187, v187, 1.0
	v_rcp_f32_e32 v216, v204
	v_div_scale_f32 v217, vcc, 1.0, v187, 1.0
	v_fma_f32 v228, -v204, v216, 1.0
	v_fmac_f32_e32 v216, v228, v216
	v_mul_f32_e32 v228, v217, v216
	v_fma_f32 v229, -v204, v228, v217
	v_fmac_f32_e32 v228, v229, v216
	v_fma_f32 v204, -v204, v228, v217
	v_div_fmas_f32 v204, v204, v216, v228
	v_div_fixup_f32 v204, v204, v187, 1.0
	v_lshlrev_b32_e32 v187, 16, v240
	v_and_b32_e32 v212, 0xffff0000, v240
	v_lshlrev_b32_e32 v216, 16, v241
	v_and_b32_e32 v217, 0xffff0000, v241
	v_lshlrev_b32_e32 v228, 16, v242
	v_and_b32_e32 v229, 0xffff0000, v242
	v_sub_f32_e32 v213, v212, v205
	v_sub_f32_e32 v212, v187, v205
	v_sub_f32_e32 v215, v217, v205
	v_sub_f32_e32 v214, v216, v205
	v_sub_f32_e32 v217, v229, v205
	v_sub_f32_e32 v216, v228, v205
	v_sub_f32_e32 v229, v231, v205
	v_sub_f32_e32 v228, v230, v205
	v_pk_mul_f32 v[214:215], v[204:205], v[214:215] op_sel_hi:[0,1]
	v_pk_mul_f32 v[212:213], v[204:205], v[212:213] op_sel_hi:[0,1]
	v_pk_mul_f32 v[228:229], v[204:205], v[228:229] op_sel_hi:[0,1]
	v_pk_mul_f32 v[216:217], v[204:205], v[216:217] op_sel_hi:[0,1]
	v_pk_fma_f32 v[212:213], v[136:137], v[212:213], v[140:141]
	v_pk_fma_f32 v[214:215], v[138:139], v[214:215], v[142:143]
	v_pk_fma_f32 v[216:217], v[128:129], v[216:217], v[132:133]
	v_pk_fma_f32 v[228:229], v[130:131], v[228:229], v[134:135]
	v_pk_fma_f32 v[102:103], v[214:215], s[34:35], v[102:103] op_sel_hi:[1,0,1]
	v_pk_fma_f32 v[100:101], v[212:213], s[34:35], v[100:101] op_sel_hi:[1,0,1]
	v_pk_fma_f32 v[98:99], v[228:229], s[34:35], v[98:99] op_sel_hi:[1,0,1]
	v_pk_fma_f32 v[96:97], v[216:217], s[34:35], v[96:97] op_sel_hi:[1,0,1]
	v_cvt_pk_bf16_f32 v212, v100, v101
	v_cvt_pk_bf16_f32 v213, v102, v103
	v_cvt_pk_bf16_f32 v214, v96, v97
	v_cvt_pk_bf16_f32 v215, v98, v99
	global_store_dwordx4 v[196:197], v[212:215], off
	s_nop 0
	v_fma_f32 v187, -v209, v209, v208
	v_max_f32_e32 v187, 0, v187
	v_add_f32_e32 v187, 0x3727c5ac, v187
	v_mul_f32_e32 v208, 0x4f800000, v187
	v_cmp_gt_f32_e32 vcc, s61, v187
	global_load_dwordx4 v[240:243], v[206:207], off
	s_waitcnt vmcnt(2)
	v_lshlrev_b32_e32 v230, 16, v247
	v_cndmask_b32_e32 v187, v187, v208, vcc
	v_sqrt_f32_e32 v208, v187
	v_and_b32_e32 v231, 0xffff0000, v247
	v_add_u32_e32 v216, -1, v208
	v_add_u32_e32 v217, 1, v208
	v_fma_f32 v228, -v216, v208, v187
	v_fma_f32 v229, -v217, v208, v187
	v_cmp_ge_f32_e64 s[0:1], 0, v228
	s_nop 1
	v_cndmask_b32_e64 v208, v208, v216, s[0:1]
	v_cmp_lt_f32_e64 s[0:1], 0, v229
	s_nop 1
	v_cndmask_b32_e64 v208, v208, v217, s[0:1]
	v_mul_f32_e32 v216, 0x37800000, v208
	v_cndmask_b32_e32 v208, v208, v216, vcc
	v_cmp_class_f32_e32 vcc, v187, v227
	s_nop 1
	v_cndmask_b32_e32 v187, v208, v187, vcc
	v_div_scale_f32 v208, s[0:1], v187, v187, 1.0
	v_rcp_f32_e32 v216, v208
	v_div_scale_f32 v217, vcc, 1.0, v187, 1.0
	v_fma_f32 v228, -v208, v216, 1.0
	v_fmac_f32_e32 v216, v228, v216
	v_mul_f32_e32 v228, v217, v216
	v_fma_f32 v229, -v208, v228, v217
	v_fmac_f32_e32 v228, v229, v216
	v_fma_f32 v208, -v208, v228, v217
	v_div_fmas_f32 v208, v208, v216, v228
	v_div_fixup_f32 v208, v208, v187, 1.0
	v_lshlrev_b32_e32 v187, 16, v244
	v_and_b32_e32 v212, 0xffff0000, v244
	v_lshlrev_b32_e32 v216, 16, v245
	v_and_b32_e32 v217, 0xffff0000, v245
	v_lshlrev_b32_e32 v228, 16, v246
	v_and_b32_e32 v229, 0xffff0000, v246
	v_sub_f32_e32 v213, v212, v209
	v_sub_f32_e32 v212, v187, v209
	v_sub_f32_e32 v215, v217, v209
	v_sub_f32_e32 v214, v216, v209
	v_sub_f32_e32 v217, v229, v209
	v_sub_f32_e32 v216, v228, v209
	v_sub_f32_e32 v229, v231, v209
	v_sub_f32_e32 v228, v230, v209
	v_pk_mul_f32 v[214:215], v[208:209], v[214:215] op_sel_hi:[0,1]
	v_pk_mul_f32 v[212:213], v[208:209], v[212:213] op_sel_hi:[0,1]
	v_pk_mul_f32 v[228:229], v[208:209], v[228:229] op_sel_hi:[0,1]
	v_pk_mul_f32 v[216:217], v[208:209], v[216:217] op_sel_hi:[0,1]
	v_pk_fma_f32 v[212:213], v[136:137], v[212:213], v[140:141]
	v_pk_fma_f32 v[214:215], v[138:139], v[214:215], v[142:143]
	v_pk_fma_f32 v[216:217], v[128:129], v[216:217], v[132:133]
	v_pk_fma_f32 v[228:229], v[130:131], v[228:229], v[134:135]
	v_pk_fma_f32 v[94:95], v[214:215], s[34:35], v[94:95] op_sel_hi:[1,0,1]
	v_pk_fma_f32 v[92:93], v[212:213], s[34:35], v[92:93] op_sel_hi:[1,0,1]
	v_pk_fma_f32 v[90:91], v[228:229], s[34:35], v[90:91] op_sel_hi:[1,0,1]
	v_pk_fma_f32 v[88:89], v[216:217], s[34:35], v[88:89] op_sel_hi:[1,0,1]
	v_cvt_pk_bf16_f32 v212, v92, v93
	v_cvt_pk_bf16_f32 v213, v94, v95
	v_cvt_pk_bf16_f32 v214, v88, v89
	v_cvt_pk_bf16_f32 v215, v90, v91
	global_store_dwordx4 v[202:203], v[212:215], off
	s_nop 0
	s_waitcnt vmcnt(1)
	v_lshlrev_b32_e32 v216, 16, v242
	v_pk_mul_f32 v[214:215], v[210:211], s[30:31] op_sel:[1,0] op_sel_hi:[0,0]
	v_fma_f32 v187, -v215, v215, v214
	v_max_f32_e32 v187, 0, v187
	v_add_f32_e32 v187, 0x3727c5ac, v187
	v_mul_f32_e32 v210, 0x4f800000, v187
	v_cmp_gt_f32_e32 vcc, s61, v187
	v_and_b32_e32 v217, 0xffff0000, v242
	v_sub_f32_e32 v217, v217, v215
	v_cndmask_b32_e32 v187, v187, v210, vcc
	v_sqrt_f32_e32 v210, v187
	v_sub_f32_e32 v216, v216, v215
	v_add_u32_e32 v211, -1, v210
	v_add_u32_e32 v212, 1, v210
	v_fma_f32 v213, -v211, v210, v187
	v_fma_f32 v214, -v212, v210, v187
	v_cmp_ge_f32_e64 s[0:1], 0, v213
	s_nop 1
	v_cndmask_b32_e64 v210, v210, v211, s[0:1]
	v_cmp_lt_f32_e64 s[0:1], 0, v214
	s_nop 1
	v_cndmask_b32_e64 v210, v210, v212, s[0:1]
	v_mul_f32_e32 v211, 0x37800000, v210
	v_cndmask_b32_e32 v210, v210, v211, vcc
	v_cmp_class_f32_e32 vcc, v187, v227
	v_lshl_add_u64 v[212:213], v[184:185], 0, v[178:179]
	global_load_dwordx4 v[244:247], v[212:213], off
	s_nop 0
	v_cndmask_b32_e32 v187, v210, v187, vcc
	v_div_scale_f32 v210, s[0:1], v187, v187, 1.0
	v_rcp_f32_e32 v211, v210
	v_div_scale_f32 v184, vcc, 1.0, v187, 1.0
	v_fma_f32 v185, -v210, v211, 1.0
	v_fmac_f32_e32 v211, v185, v211
	v_mul_f32_e32 v185, v184, v211
	v_fma_f32 v214, -v210, v185, v184
	v_fmac_f32_e32 v185, v214, v211
	v_fma_f32 v184, -v210, v185, v184
	v_div_fmas_f32 v184, v184, v211, v185
	v_div_fixup_f32 v214, v184, v187, 1.0
	v_lshlrev_b32_e32 v184, 16, v240
	v_and_b32_e32 v185, 0xffff0000, v240
	v_lshlrev_b32_e32 v187, 16, v241
	v_and_b32_e32 v210, 0xffff0000, v241
	v_lshlrev_b32_e32 v228, 16, v243
	v_and_b32_e32 v229, 0xffff0000, v243
	v_sub_f32_e32 v185, v185, v215
	v_sub_f32_e32 v184, v184, v215
	v_sub_f32_e32 v211, v210, v215
	v_sub_f32_e32 v210, v187, v215
	v_sub_f32_e32 v229, v229, v215
	v_sub_f32_e32 v228, v228, v215
	v_pk_mul_f32 v[210:211], v[214:215], v[210:211] op_sel_hi:[0,1]
	v_pk_mul_f32 v[184:185], v[214:215], v[184:185] op_sel_hi:[0,1]
	v_pk_mul_f32 v[228:229], v[214:215], v[228:229] op_sel_hi:[0,1]
	v_pk_mul_f32 v[216:217], v[214:215], v[216:217] op_sel_hi:[0,1]
	v_pk_fma_f32 v[184:185], v[136:137], v[184:185], v[140:141]
	v_pk_fma_f32 v[210:211], v[138:139], v[210:211], v[142:143]
	v_pk_fma_f32 v[216:217], v[128:129], v[216:217], v[132:133]
	v_pk_fma_f32 v[228:229], v[130:131], v[228:229], v[134:135]
	v_pk_fma_f32 v[86:87], v[210:211], s[34:35], v[86:87] op_sel_hi:[1,0,1]
	v_pk_fma_f32 v[84:85], v[184:185], s[34:35], v[84:85] op_sel_hi:[1,0,1]
	v_pk_fma_f32 v[82:83], v[228:229], s[34:35], v[82:83] op_sel_hi:[1,0,1]
	v_pk_fma_f32 v[80:81], v[216:217], s[34:35], v[80:81] op_sel_hi:[1,0,1]
	v_cvt_pk_bf16_f32 v228, v84, v85
	v_cvt_pk_bf16_f32 v229, v86, v87
	v_cvt_pk_bf16_f32 v230, v80, v81
	v_cvt_pk_bf16_f32 v231, v82, v83
	global_store_dwordx4 v[206:207], v[228:231], off
	s_nop 0
	v_pk_mul_f32 v[216:217], v[182:183], s[30:31] op_sel:[1,0] op_sel_hi:[0,0]
	v_fma_f32 v182, -v217, v217, v216
	v_max_f32_e32 v182, 0, v182
	v_add_f32_e32 v182, 0x3727c5ac, v182
	v_mul_f32_e32 v183, 0x4f800000, v182
	v_cmp_gt_f32_e32 vcc, s61, v182
	s_nop 1
	v_cndmask_b32_e32 v182, v182, v183, vcc
	v_sqrt_f32_e32 v183, v182
	s_nop 0
	v_add_u32_e32 v184, -1, v183
	v_add_u32_e32 v185, 1, v183
	v_fma_f32 v187, -v184, v183, v182
	v_fma_f32 v210, -v185, v183, v182
	v_cmp_ge_f32_e64 s[0:1], 0, v187
	s_nop 1
	v_cndmask_b32_e64 v183, v183, v184, s[0:1]
	v_cmp_lt_f32_e64 s[0:1], 0, v210
	v_lshl_add_u64 v[210:211], v[180:181], 0, v[178:179]
	global_load_dwordx4 v[240:243], v[210:211], off
	s_waitcnt vmcnt(2)
	v_and_b32_e32 v181, 0xffff0000, v245
	v_cndmask_b32_e64 v183, v183, v185, s[0:1]
	v_mul_f32_e32 v184, 0x37800000, v183
	v_cndmask_b32_e32 v183, v183, v184, vcc
	v_cmp_class_f32_e32 vcc, v182, v227
	v_and_b32_e32 v185, 0xffff0000, v247
	v_sub_f32_e32 v181, v181, v217
	v_cndmask_b32_e32 v182, v183, v182, vcc
	v_div_scale_f32 v183, s[0:1], v182, v182, 1.0
	v_rcp_f32_e32 v184, v183
	v_div_scale_f32 v178, vcc, 1.0, v182, 1.0
	v_sub_f32_e32 v185, v185, v217
	v_fma_f32 v179, -v183, v184, 1.0
	v_fmac_f32_e32 v184, v179, v184
	v_mul_f32_e32 v179, v178, v184
	v_fma_f32 v180, -v183, v179, v178
	v_fmac_f32_e32 v179, v180, v184
	v_fma_f32 v178, -v183, v179, v178
	v_div_fmas_f32 v178, v178, v184, v179
	v_div_fixup_f32 v216, v178, v182, 1.0
	v_lshlrev_b32_e32 v178, 16, v244
	v_and_b32_e32 v179, 0xffff0000, v244
	v_lshlrev_b32_e32 v180, 16, v245
	v_lshlrev_b32_e32 v182, 16, v246
	v_and_b32_e32 v183, 0xffff0000, v246
	v_lshlrev_b32_e32 v184, 16, v247
	v_sub_f32_e32 v179, v179, v217
	v_sub_f32_e32 v178, v178, v217
	v_sub_f32_e32 v180, v180, v217
	v_sub_f32_e32 v183, v183, v217
	v_sub_f32_e32 v182, v182, v217
	v_sub_f32_e32 v184, v184, v217
	v_pk_mul_f32 v[180:181], v[216:217], v[180:181] op_sel_hi:[0,1]
	v_pk_mul_f32 v[178:179], v[216:217], v[178:179] op_sel_hi:[0,1]
	v_pk_mul_f32 v[184:185], v[216:217], v[184:185] op_sel_hi:[0,1]
	v_pk_mul_f32 v[182:183], v[216:217], v[182:183] op_sel_hi:[0,1]
	v_pk_fma_f32 v[178:179], v[136:137], v[178:179], v[140:141]
	v_pk_fma_f32 v[180:181], v[138:139], v[180:181], v[142:143]
	v_pk_fma_f32 v[228:229], v[128:129], v[182:183], v[132:133]
	v_pk_fma_f32 v[230:231], v[130:131], v[184:185], v[134:135]
	v_pk_fma_f32 v[182:183], v[180:181], s[34:35], v[78:79] op_sel_hi:[1,0,1]
	v_pk_fma_f32 v[184:185], v[178:179], s[34:35], v[76:77] op_sel_hi:[1,0,1]
	v_pk_fma_f32 v[178:179], v[230:231], s[34:35], v[74:75] op_sel_hi:[1,0,1]
	v_pk_fma_f32 v[180:181], v[228:229], s[34:35], v[72:73] op_sel_hi:[1,0,1]
	v_cvt_pk_bf16_f32 v72, v184, v185
	v_cvt_pk_bf16_f32 v73, v182, v183
	v_cvt_pk_bf16_f32 v74, v180, v181
	v_cvt_pk_bf16_f32 v75, v178, v179
	global_store_dwordx4 v[212:213], v[72:75], off
	s_nop 0
	v_fma_f32 v76, -v201, v201, v200
	v_max_f32_e32 v76, 0, v76
	v_add_f32_e32 v76, 0x3727c5ac, v76
	v_mul_f32_e32 v77, 0x4f800000, v76
	v_cmp_gt_f32_e32 vcc, s61, v76
	s_waitcnt vmcnt(1)
	v_lshlrev_b32_e32 v228, 16, v243
	v_cndmask_b32_e32 v76, v76, v77, vcc
	v_sqrt_f32_e32 v77, v76
	v_and_b32_e32 v229, 0xffff0000, v243
	v_add_u32_e32 v78, -1, v77
	v_add_u32_e32 v79, 1, v77
	v_fma_f32 v187, -v78, v77, v76
	v_fma_f32 v200, -v79, v77, v76
	v_cmp_ge_f32_e64 s[0:1], 0, v187
	s_nop 1
	v_cndmask_b32_e64 v77, v77, v78, s[0:1]
	v_cmp_lt_f32_e64 s[0:1], 0, v200
	s_nop 1
	v_cndmask_b32_e64 v77, v77, v79, s[0:1]
	v_mul_f32_e32 v78, 0x37800000, v77
	v_cndmask_b32_e32 v77, v77, v78, vcc
	v_cmp_class_f32_e32 vcc, v76, v227
	s_nop 1
	v_cndmask_b32_e32 v76, v77, v76, vcc
	v_div_scale_f32 v77, s[0:1], v76, v76, 1.0
	v_rcp_f32_e32 v78, v77
	v_div_scale_f32 v79, vcc, 1.0, v76, 1.0
	v_fma_f32 v187, -v77, v78, 1.0
	v_fmac_f32_e32 v78, v187, v78
	v_mul_f32_e32 v187, v79, v78
	v_fma_f32 v200, -v77, v187, v79
	v_fmac_f32_e32 v187, v200, v78
	v_fma_f32 v77, -v77, v187, v79
	v_div_fmas_f32 v77, v77, v78, v187
	v_div_fixup_f32 v200, v77, v76, 1.0
	v_lshlrev_b32_e32 v76, 16, v240
	v_and_b32_e32 v72, 0xffff0000, v240
	v_lshlrev_b32_e32 v77, 16, v241
	v_and_b32_e32 v78, 0xffff0000, v241
	v_lshlrev_b32_e32 v79, 16, v242
	v_and_b32_e32 v187, 0xffff0000, v242
	v_sub_f32_e32 v73, v72, v201
	v_sub_f32_e32 v72, v76, v201
	v_sub_f32_e32 v75, v78, v201
	v_sub_f32_e32 v74, v77, v201
	v_sub_f32_e32 v77, v187, v201
	v_sub_f32_e32 v76, v79, v201
	v_sub_f32_e32 v79, v229, v201
	v_sub_f32_e32 v78, v228, v201
	v_pk_mul_f32 v[74:75], v[200:201], v[74:75] op_sel_hi:[0,1]
	v_pk_mul_f32 v[72:73], v[200:201], v[72:73] op_sel_hi:[0,1]
	v_pk_mul_f32 v[78:79], v[200:201], v[78:79] op_sel_hi:[0,1]
	v_pk_mul_f32 v[76:77], v[200:201], v[76:77] op_sel_hi:[0,1]
	v_pk_fma_f32 v[72:73], v[136:137], v[72:73], v[140:141]
	v_pk_fma_f32 v[74:75], v[138:139], v[74:75], v[142:143]
	v_pk_fma_f32 v[76:77], v[128:129], v[76:77], v[132:133]
	v_pk_fma_f32 v[78:79], v[130:131], v[78:79], v[134:135]
	v_pk_fma_f32 v[130:131], v[74:75], s[34:35], v[70:71] op_sel_hi:[1,0,1]
	v_pk_fma_f32 v[134:135], v[72:73], s[34:35], v[68:69] op_sel_hi:[1,0,1]
	v_pk_fma_f32 v[128:129], v[78:79], s[34:35], v[66:67] op_sel_hi:[1,0,1]
	v_pk_fma_f32 v[132:133], v[76:77], s[34:35], v[64:65] op_sel_hi:[1,0,1]
	v_cvt_pk_bf16_f32 v64, v134, v135
	v_cvt_pk_bf16_f32 v65, v130, v131
	v_cvt_pk_bf16_f32 v66, v132, v133
	v_cvt_pk_bf16_f32 v67, v128, v129
	global_store_dwordx4 v[210:211], v[64:67], off
	global_load_dwordx4 v[136:139], v[176:177], off offset:256
	s_waitcnt vmcnt(0)
	v_lshlrev_b32_e32 v140, 16, v136
	v_or_b32_e32 v64, 0x80, v186
	v_ashrrev_i32_e32 v65, 31, v64
	v_lshlrev_b64 v[64:65], 2, v[64:65]
	v_lshl_add_u64 v[66:67], s[14:15], 0, v[64:65]
	v_lshl_add_u64 v[76:77], s[20:21], 0, v[64:65]
	global_load_dwordx4 v[68:71], v[76:77], off
	global_load_dwordx4 v[72:75], v[66:67], off
	s_nop 0
	global_load_dwordx4 v[64:67], v[66:67], off offset:16
	s_nop 0
	global_load_dwordx4 v[76:79], v[76:77], off offset:16
	v_and_b32_e32 v136, 0xffff0000, v136
	v_lshlrev_b32_e32 v141, 16, v137
	v_and_b32_e32 v142, 0xffff0000, v137
	v_lshlrev_b32_e32 v143, 16, v138
	v_and_b32_e32 v186, 0xffff0000, v138
	v_lshlrev_b32_e32 v187, 16, v139
	v_and_b32_e32 v228, 0xffff0000, v139
	v_sub_f32_e32 v137, v136, v189
	v_sub_f32_e32 v136, v140, v189
	v_sub_f32_e32 v139, v142, v189
	v_sub_f32_e32 v138, v141, v189
	v_sub_f32_e32 v141, v186, v189
	v_sub_f32_e32 v140, v143, v189
	v_sub_f32_e32 v143, v228, v189
	v_sub_f32_e32 v142, v187, v189
	v_pk_mul_f32 v[138:139], v[188:189], v[138:139] op_sel_hi:[0,1]
	v_pk_mul_f32 v[136:137], v[188:189], v[136:137] op_sel_hi:[0,1]
	v_pk_mul_f32 v[142:143], v[188:189], v[142:143] op_sel_hi:[0,1]
	v_pk_mul_f32 v[140:141], v[188:189], v[140:141] op_sel_hi:[0,1]
	s_waitcnt vmcnt(0)
	v_pk_fma_f32 v[136:137], v[72:73], v[136:137], v[68:69]
	v_pk_fma_f32 v[138:139], v[74:75], v[138:139], v[70:71]
	v_pk_fma_f32 v[140:141], v[64:65], v[140:141], v[76:77]
	v_pk_fma_f32 v[142:143], v[66:67], v[142:143], v[78:79]
	v_pk_fma_f32 v[62:63], v[138:139], s[34:35], v[62:63] op_sel_hi:[1,0,1]
	v_pk_fma_f32 v[60:61], v[136:137], s[34:35], v[60:61] op_sel_hi:[1,0,1]
	v_pk_fma_f32 v[58:59], v[142:143], s[34:35], v[58:59] op_sel_hi:[1,0,1]
	v_pk_fma_f32 v[56:57], v[140:141], s[34:35], v[56:57] op_sel_hi:[1,0,1]
	v_cvt_pk_bf16_f32 v136, v60, v61
	v_cvt_pk_bf16_f32 v137, v62, v63
	v_cvt_pk_bf16_f32 v138, v56, v57
	v_cvt_pk_bf16_f32 v139, v58, v59
	global_store_dwordx4 v[176:177], v[136:139], off offset:256
	global_load_dwordx4 v[240:243], v[190:191], off offset:256
	global_load_dwordx4 v[244:247], v[192:193], off offset:256
	s_waitcnt vmcnt(1)
	v_lshlrev_b32_e32 v140, 16, v240
	v_and_b32_e32 v136, 0xffff0000, v240
	v_lshlrev_b32_e32 v141, 16, v241
	v_and_b32_e32 v142, 0xffff0000, v241
	v_lshlrev_b32_e32 v143, 16, v242
	v_and_b32_e32 v176, 0xffff0000, v242
	v_lshlrev_b32_e32 v177, 16, v243
	v_and_b32_e32 v186, 0xffff0000, v243
	v_sub_f32_e32 v137, v136, v195
	v_sub_f32_e32 v136, v140, v195
	v_sub_f32_e32 v139, v142, v195
	v_sub_f32_e32 v138, v141, v195
	v_sub_f32_e32 v141, v176, v195
	v_sub_f32_e32 v140, v143, v195
	v_sub_f32_e32 v143, v186, v195
	v_sub_f32_e32 v142, v177, v195
	v_pk_mul_f32 v[138:139], v[194:195], v[138:139] op_sel_hi:[0,1]
	v_pk_mul_f32 v[136:137], v[194:195], v[136:137] op_sel_hi:[0,1]
	v_pk_mul_f32 v[142:143], v[194:195], v[142:143] op_sel_hi:[0,1]
	v_pk_mul_f32 v[140:141], v[194:195], v[140:141] op_sel_hi:[0,1]
	v_pk_fma_f32 v[136:137], v[72:73], v[136:137], v[68:69]
	v_pk_fma_f32 v[138:139], v[74:75], v[138:139], v[70:71]
	v_pk_fma_f32 v[140:141], v[64:65], v[140:141], v[76:77]
	v_pk_fma_f32 v[142:143], v[66:67], v[142:143], v[78:79]
	v_pk_fma_f32 v[54:55], v[138:139], s[34:35], v[54:55] op_sel_hi:[1,0,1]
	v_pk_fma_f32 v[52:53], v[136:137], s[34:35], v[52:53] op_sel_hi:[1,0,1]
	v_pk_fma_f32 v[50:51], v[142:143], s[34:35], v[50:51] op_sel_hi:[1,0,1]
	v_pk_fma_f32 v[48:49], v[140:141], s[34:35], v[48:49] op_sel_hi:[1,0,1]
	v_cvt_pk_bf16_f32 v136, v52, v53
	v_cvt_pk_bf16_f32 v137, v54, v55
	v_cvt_pk_bf16_f32 v138, v48, v49
	v_cvt_pk_bf16_f32 v139, v50, v51
	global_store_dwordx4 v[190:191], v[136:139], off offset:256
	s_nop 0
	global_load_dwordx4 v[240:243], v[196:197], off offset:256
	s_waitcnt vmcnt(2)
	v_lshlrev_b32_e32 v140, 16, v244
	v_and_b32_e32 v136, 0xffff0000, v244
	v_lshlrev_b32_e32 v141, 16, v245
	v_and_b32_e32 v142, 0xffff0000, v245
	v_lshlrev_b32_e32 v143, 16, v246
	v_and_b32_e32 v176, 0xffff0000, v246
	v_lshlrev_b32_e32 v177, 16, v247
	v_and_b32_e32 v186, 0xffff0000, v247
	v_sub_f32_e32 v137, v136, v199
	v_sub_f32_e32 v136, v140, v199
	v_sub_f32_e32 v139, v142, v199
	v_sub_f32_e32 v138, v141, v199
	v_sub_f32_e32 v141, v176, v199
	v_sub_f32_e32 v140, v143, v199
	v_sub_f32_e32 v143, v186, v199
	v_sub_f32_e32 v142, v177, v199
	v_pk_mul_f32 v[138:139], v[198:199], v[138:139] op_sel_hi:[0,1]
	v_pk_mul_f32 v[136:137], v[198:199], v[136:137] op_sel_hi:[0,1]
	v_pk_mul_f32 v[142:143], v[198:199], v[142:143] op_sel_hi:[0,1]
	v_pk_mul_f32 v[140:141], v[198:199], v[140:141] op_sel_hi:[0,1]
	v_pk_fma_f32 v[136:137], v[72:73], v[136:137], v[68:69]
	v_pk_fma_f32 v[138:139], v[74:75], v[138:139], v[70:71]
	v_pk_fma_f32 v[140:141], v[64:65], v[140:141], v[76:77]
	v_pk_fma_f32 v[142:143], v[66:67], v[142:143], v[78:79]
	v_pk_fma_f32 v[46:47], v[138:139], s[34:35], v[46:47] op_sel_hi:[1,0,1]
	v_pk_fma_f32 v[44:45], v[136:137], s[34:35], v[44:45] op_sel_hi:[1,0,1]
	v_pk_fma_f32 v[42:43], v[142:143], s[34:35], v[42:43] op_sel_hi:[1,0,1]
	v_pk_fma_f32 v[40:41], v[140:141], s[34:35], v[40:41] op_sel_hi:[1,0,1]
	v_cvt_pk_bf16_f32 v136, v44, v45
	v_cvt_pk_bf16_f32 v137, v46, v47
	v_cvt_pk_bf16_f32 v138, v40, v41
	v_cvt_pk_bf16_f32 v139, v42, v43
	global_store_dwordx4 v[192:193], v[136:139], off offset:256
	s_nop 0
	global_load_dwordx4 v[244:247], v[202:203], off offset:256
	s_waitcnt vmcnt(2)
	v_lshlrev_b32_e32 v140, 16, v240
	v_and_b32_e32 v136, 0xffff0000, v240
	v_lshlrev_b32_e32 v141, 16, v241
	v_and_b32_e32 v142, 0xffff0000, v241
	v_lshlrev_b32_e32 v143, 16, v242
	v_and_b32_e32 v176, 0xffff0000, v242
	v_lshlrev_b32_e32 v177, 16, v243
	v_and_b32_e32 v186, 0xffff0000, v243
	v_sub_f32_e32 v137, v136, v205
	v_sub_f32_e32 v136, v140, v205
	v_sub_f32_e32 v139, v142, v205
	v_sub_f32_e32 v138, v141, v205
	v_sub_f32_e32 v141, v176, v205
	v_sub_f32_e32 v140, v143, v205
	v_sub_f32_e32 v143, v186, v205
	v_sub_f32_e32 v142, v177, v205
	v_pk_mul_f32 v[138:139], v[204:205], v[138:139] op_sel_hi:[0,1]
	v_pk_mul_f32 v[136:137], v[204:205], v[136:137] op_sel_hi:[0,1]
	v_pk_mul_f32 v[142:143], v[204:205], v[142:143] op_sel_hi:[0,1]
	v_pk_mul_f32 v[140:141], v[204:205], v[140:141] op_sel_hi:[0,1]
	v_pk_fma_f32 v[136:137], v[72:73], v[136:137], v[68:69]
	v_pk_fma_f32 v[138:139], v[74:75], v[138:139], v[70:71]
	v_pk_fma_f32 v[140:141], v[64:65], v[140:141], v[76:77]
	v_pk_fma_f32 v[142:143], v[66:67], v[142:143], v[78:79]
	v_pk_fma_f32 v[38:39], v[138:139], s[34:35], v[38:39] op_sel_hi:[1,0,1]
	v_pk_fma_f32 v[36:37], v[136:137], s[34:35], v[36:37] op_sel_hi:[1,0,1]
	v_pk_fma_f32 v[34:35], v[142:143], s[34:35], v[34:35] op_sel_hi:[1,0,1]
	v_pk_fma_f32 v[32:33], v[140:141], s[34:35], v[32:33] op_sel_hi:[1,0,1]
	v_cvt_pk_bf16_f32 v136, v36, v37
	v_cvt_pk_bf16_f32 v137, v38, v39
	v_cvt_pk_bf16_f32 v138, v32, v33
	v_cvt_pk_bf16_f32 v139, v34, v35
	global_store_dwordx4 v[196:197], v[136:139], off offset:256
	s_nop 0
	global_load_dwordx4 v[240:243], v[206:207], off offset:256
	s_waitcnt vmcnt(2)
	v_lshlrev_b32_e32 v140, 16, v244
	v_and_b32_e32 v136, 0xffff0000, v244
	v_lshlrev_b32_e32 v141, 16, v245
	v_and_b32_e32 v142, 0xffff0000, v245
	v_lshlrev_b32_e32 v143, 16, v246
	v_and_b32_e32 v176, 0xffff0000, v246
	v_lshlrev_b32_e32 v177, 16, v247
	v_and_b32_e32 v186, 0xffff0000, v247
	v_sub_f32_e32 v137, v136, v209
	v_sub_f32_e32 v136, v140, v209
	v_sub_f32_e32 v139, v142, v209
	v_sub_f32_e32 v138, v141, v209
	v_sub_f32_e32 v141, v176, v209
	v_sub_f32_e32 v140, v143, v209
	v_sub_f32_e32 v143, v186, v209
	v_sub_f32_e32 v142, v177, v209
	v_pk_mul_f32 v[138:139], v[208:209], v[138:139] op_sel_hi:[0,1]
	v_pk_mul_f32 v[136:137], v[208:209], v[136:137] op_sel_hi:[0,1]
	v_pk_mul_f32 v[142:143], v[208:209], v[142:143] op_sel_hi:[0,1]
	v_pk_mul_f32 v[140:141], v[208:209], v[140:141] op_sel_hi:[0,1]
	v_pk_fma_f32 v[136:137], v[72:73], v[136:137], v[68:69]
	v_pk_fma_f32 v[138:139], v[74:75], v[138:139], v[70:71]
	v_pk_fma_f32 v[140:141], v[64:65], v[140:141], v[76:77]
	v_pk_fma_f32 v[142:143], v[66:67], v[142:143], v[78:79]
	v_pk_fma_f32 v[30:31], v[138:139], s[34:35], v[30:31] op_sel_hi:[1,0,1]
	v_pk_fma_f32 v[28:29], v[136:137], s[34:35], v[28:29] op_sel_hi:[1,0,1]
	v_pk_fma_f32 v[26:27], v[142:143], s[34:35], v[26:27] op_sel_hi:[1,0,1]
	v_pk_fma_f32 v[24:25], v[140:141], s[34:35], v[24:25] op_sel_hi:[1,0,1]
	v_cvt_pk_bf16_f32 v136, v28, v29
	v_cvt_pk_bf16_f32 v137, v30, v31
	v_cvt_pk_bf16_f32 v138, v24, v25
	v_cvt_pk_bf16_f32 v139, v26, v27
	global_store_dwordx4 v[202:203], v[136:139], off offset:256
	s_nop 0
	global_load_dwordx4 v[244:247], v[212:213], off offset:256
	s_waitcnt vmcnt(2)
	v_lshlrev_b32_e32 v140, 16, v240
	v_and_b32_e32 v136, 0xffff0000, v240
	v_lshlrev_b32_e32 v141, 16, v241
	v_and_b32_e32 v142, 0xffff0000, v241
	v_lshlrev_b32_e32 v143, 16, v242
	v_and_b32_e32 v176, 0xffff0000, v242
	v_lshlrev_b32_e32 v177, 16, v243
	v_and_b32_e32 v186, 0xffff0000, v243
	v_sub_f32_e32 v137, v136, v215
	v_sub_f32_e32 v136, v140, v215
	v_sub_f32_e32 v139, v142, v215
	v_sub_f32_e32 v138, v141, v215
	v_sub_f32_e32 v141, v176, v215
	v_sub_f32_e32 v140, v143, v215
	v_sub_f32_e32 v143, v186, v215
	v_sub_f32_e32 v142, v177, v215
	v_pk_mul_f32 v[138:139], v[214:215], v[138:139] op_sel_hi:[0,1]
	v_pk_mul_f32 v[136:137], v[214:215], v[136:137] op_sel_hi:[0,1]
	v_pk_mul_f32 v[142:143], v[214:215], v[142:143] op_sel_hi:[0,1]
	v_pk_mul_f32 v[140:141], v[214:215], v[140:141] op_sel_hi:[0,1]
	v_pk_fma_f32 v[136:137], v[72:73], v[136:137], v[68:69]
	v_pk_fma_f32 v[138:139], v[74:75], v[138:139], v[70:71]
	v_pk_fma_f32 v[140:141], v[64:65], v[140:141], v[76:77]
	v_pk_fma_f32 v[142:143], v[66:67], v[142:143], v[78:79]
	v_pk_fma_f32 v[22:23], v[138:139], s[34:35], v[22:23] op_sel_hi:[1,0,1]
	v_pk_fma_f32 v[20:21], v[136:137], s[34:35], v[20:21] op_sel_hi:[1,0,1]
	v_pk_fma_f32 v[18:19], v[142:143], s[34:35], v[18:19] op_sel_hi:[1,0,1]
	v_pk_fma_f32 v[16:17], v[140:141], s[34:35], v[16:17] op_sel_hi:[1,0,1]
	v_cvt_pk_bf16_f32 v136, v20, v21
	v_cvt_pk_bf16_f32 v137, v22, v23
	v_cvt_pk_bf16_f32 v138, v16, v17
	v_cvt_pk_bf16_f32 v139, v18, v19
	global_store_dwordx4 v[206:207], v[136:139], off offset:256
	s_nop 0
	global_load_dwordx4 v[240:243], v[210:211], off offset:256
	s_waitcnt vmcnt(2)
	v_lshlrev_b32_e32 v140, 16, v244
	v_and_b32_e32 v136, 0xffff0000, v244
	v_lshlrev_b32_e32 v141, 16, v245
	v_and_b32_e32 v142, 0xffff0000, v245
	v_lshlrev_b32_e32 v143, 16, v246
	v_and_b32_e32 v176, 0xffff0000, v246
	v_lshlrev_b32_e32 v177, 16, v247
	v_and_b32_e32 v186, 0xffff0000, v247
	v_sub_f32_e32 v137, v136, v217
	v_sub_f32_e32 v136, v140, v217
	v_sub_f32_e32 v139, v142, v217
	v_sub_f32_e32 v138, v141, v217
	v_sub_f32_e32 v141, v176, v217
	v_sub_f32_e32 v140, v143, v217
	v_sub_f32_e32 v143, v186, v217
	v_sub_f32_e32 v142, v177, v217
	v_pk_mul_f32 v[138:139], v[216:217], v[138:139] op_sel_hi:[0,1]
	v_pk_mul_f32 v[136:137], v[216:217], v[136:137] op_sel_hi:[0,1]
	v_pk_mul_f32 v[142:143], v[216:217], v[142:143] op_sel_hi:[0,1]
	v_pk_mul_f32 v[140:141], v[216:217], v[140:141] op_sel_hi:[0,1]
	v_pk_fma_f32 v[136:137], v[72:73], v[136:137], v[68:69]
	v_pk_fma_f32 v[138:139], v[74:75], v[138:139], v[70:71]
	v_pk_fma_f32 v[140:141], v[64:65], v[140:141], v[76:77]
	v_pk_fma_f32 v[142:143], v[66:67], v[142:143], v[78:79]
	v_pk_fma_f32 v[14:15], v[138:139], s[34:35], v[14:15] op_sel_hi:[1,0,1]
	v_pk_fma_f32 v[12:13], v[136:137], s[34:35], v[12:13] op_sel_hi:[1,0,1]
	v_pk_fma_f32 v[10:11], v[142:143], s[34:35], v[10:11] op_sel_hi:[1,0,1]
	v_pk_fma_f32 v[8:9], v[140:141], s[34:35], v[8:9] op_sel_hi:[1,0,1]
	v_cvt_pk_bf16_f32 v136, v12, v13
	v_cvt_pk_bf16_f32 v137, v14, v15
	v_cvt_pk_bf16_f32 v138, v8, v9
	v_cvt_pk_bf16_f32 v139, v10, v11
	global_store_dwordx4 v[212:213], v[136:139], off offset:256
	s_nop 0
	v_add_f32_e32 v140, v124, v125
	v_add_f32_e32 v141, v126, v127
	v_add_f32_e32 v142, v120, v121
	v_add_f32_e32 v143, v122, v123
	v_mul_f32_e32 v125, v125, v125
	v_mul_f32_e32 v127, v127, v127
	v_mul_f32_e32 v121, v121, v121
	v_mul_f32_e32 v123, v123, v123
	v_fmac_f32_e32 v125, v124, v124
	v_fmac_f32_e32 v127, v126, v126
	v_fmac_f32_e32 v121, v120, v120
	v_fmac_f32_e32 v123, v122, v122
	v_add_f32_e32 v122, v125, v127
	v_add_f32_e32 v121, v121, v123
	v_add_f32_e32 v121, v122, v121
	v_add_f32_e32 v122, v60, v61
	v_add_f32_e32 v123, v62, v63
	v_add_f32_e32 v124, v56, v57
	v_add_f32_e32 v125, v58, v59
	v_mul_f32_e32 v61, v61, v61
	v_mul_f32_e32 v63, v63, v63
	v_mul_f32_e32 v57, v57, v57
	v_mul_f32_e32 v59, v59, v59
	v_add_f32_e32 v140, v140, v141
	v_add_f32_e32 v141, v142, v143
	v_fmac_f32_e32 v61, v60, v60
	v_fmac_f32_e32 v63, v62, v62
	v_fmac_f32_e32 v57, v56, v56
	v_fmac_f32_e32 v59, v58, v58
	v_add_f32_e32 v120, v140, v141
	v_add_f32_e32 v122, v122, v123
	v_add_f32_e32 v123, v124, v125
	v_add_f32_e32 v58, v61, v63
	v_add_f32_e32 v57, v57, v59
	v_add_f32_e32 v120, 0, v120
	v_add_f32_e32 v56, v122, v123
	v_add_f32_e32 v57, v58, v57
	v_add_f32_e32 v56, v120, v56
	v_add_f32_e32 v59, v121, v57
	ds_bpermute_b32 v58, v222, v56
	ds_bpermute_b32 v60, v222, v59
	s_waitcnt lgkmcnt(0)
	v_add_f32_e32 v56, v56, v58
	v_add_f32_e32 v58, v59, v60
	ds_bpermute_b32 v57, v221, v56
	s_waitcnt vmcnt(1)
	v_lshlrev_b32_e32 v59, 16, v240
	v_and_b32_e32 v60, 0xffff0000, v240
	v_lshlrev_b32_e32 v62, 16, v241
	v_and_b32_e32 v63, 0xffff0000, v241
	v_lshlrev_b32_e32 v120, 16, v242
	v_and_b32_e32 v121, 0xffff0000, v242
	v_lshlrev_b32_e32 v122, 16, v243
	v_and_b32_e32 v123, 0xffff0000, v243
	v_sub_f32_e32 v61, v60, v201
	v_sub_f32_e32 v60, v59, v201
	v_sub_f32_e32 v63, v63, v201
	v_sub_f32_e32 v62, v62, v201
	v_sub_f32_e32 v121, v121, v201
	v_sub_f32_e32 v120, v120, v201
	v_sub_f32_e32 v123, v123, v201
	v_sub_f32_e32 v122, v122, v201
	v_pk_mul_f32 v[62:63], v[200:201], v[62:63] op_sel_hi:[0,1]
	v_pk_mul_f32 v[60:61], v[200:201], v[60:61] op_sel_hi:[0,1]
	v_pk_mul_f32 v[122:123], v[200:201], v[122:123] op_sel_hi:[0,1]
	v_pk_mul_f32 v[120:121], v[200:201], v[120:121] op_sel_hi:[0,1]
	v_pk_fma_f32 v[60:61], v[72:73], v[60:61], v[68:69]
	v_pk_fma_f32 v[62:63], v[74:75], v[62:63], v[70:71]
	v_pk_fma_f32 v[64:65], v[64:65], v[120:121], v[76:77]
	v_pk_fma_f32 v[66:67], v[66:67], v[122:123], v[78:79]
	v_pk_fma_f32 v[6:7], v[62:63], s[34:35], v[6:7] op_sel_hi:[1,0,1]
	v_pk_fma_f32 v[4:5], v[60:61], s[34:35], v[4:5] op_sel_hi:[1,0,1]
	v_pk_fma_f32 v[2:3], v[66:67], s[34:35], v[2:3] op_sel_hi:[1,0,1]
	v_pk_fma_f32 v[0:1], v[64:65], s[34:35], v[0:1] op_sel_hi:[1,0,1]
	v_cvt_pk_bf16_f32 v60, v4, v5
	v_cvt_pk_bf16_f32 v61, v6, v7
	v_cvt_pk_bf16_f32 v62, v0, v1
	v_cvt_pk_bf16_f32 v63, v2, v3
	ds_bpermute_b32 v59, v221, v58
	global_store_dwordx4 v[210:211], v[60:63], off offset:256
	s_and_saveexec_b64 s[0:1], s[4:5]
	s_cbranch_execz .LBB0_1477
	s_waitcnt lgkmcnt(0)
	v_add_f32_e32 v58, v58, v59
	v_add_f32_e32 v59, v56, v57
	v_lshl_add_u64 v[56:57], s[22:23], 0, v[164:165]
	global_atomic_add_f32 v[56:57], v59, off
	global_atomic_add_f32 v[56:57], v58, off offset:4
